# v024
# speedup vs baseline: 1.0124x; 1.0124x over previous
; #define MFMA(a, b, c) __builtin_amdgcn_mfma_f32_16x16x32_bf16((a), (b), (c), 0, 0, 0)
; template <int EPI, int MF>
; __device__ __forceinline__ void gemm_part(const u16* __restrict__ A, int lda, const u16* __restrict__ Bt, int K, int ntn, GemmEpi ep, char* smem,
;                                           int mbase, int mrows) {
;     ...
;     GEMM_ISSUE(0);
;     GEMM_ISSUE(1);
;     for (int kt = 0; kt < nk; ++kt) {
;       if (kt + 1 < nk) {
;         if (MF == 8) asm volatile("s_waitcnt vmcnt(6)" ::: "memory");
;         else asm volatile("s_waitcnt vmcnt(3)" ::: "memory");
;       } else asm volatile("s_waitcnt vmcnt(0)" ::: "memory");
;       asm volatile("s_waitcnt lgkmcnt(0)" ::: "memory");
;       __builtin_amdgcn_s_barrier();
;       const u16* a_ = sbase + (kt % 3) * STG;
;       const u16* b_ = a_ + BM * 32;
;       bf16x8 bfr[4], afc[2], afn[2];
;       const u16* ap_ = a_ + (wr * (16 * MF) + fr) * 32 + fq * 8;
; #pragma unroll
;       for (int n = 0; n < 4; ++n) bfr[n] = rd_std(b_ + (wc * 64 + n * 16 + fr) * 32 + fq * 8);
;       afc[0] = rd_std(ap_); afc[1] = rd_std(ap_ + 16 * 32);
;       __builtin_amdgcn_sched_barrier(0);
;       if (kt + 2 < nk) GEMM_ISSUE(kt + 2);
;       __builtin_amdgcn_sched_barrier(0);
; #pragma unroll
;       for (int mh = 0; mh < MF / 2; ++mh) {
;         if (mh + 1 < MF / 2) {
;           afn[0] = rd_std(ap_ + ((mh + 1) * 2) * 16 * 32);
;           afn[1] = rd_std(ap_ + ((mh + 1) * 2 + 1) * 16 * 32);
;         }
;         __builtin_amdgcn_sched_barrier(0);
; #pragma unroll
;         for (int m = 0; m < 2; ++m)
; #pragma unroll
;           for (int n = 0; n < 4; ++n) acc[mh * 2 + m][n] = MFMA(bfr[n], afc[m], acc[mh * 2 + m][n]);
;         __builtin_amdgcn_sched_barrier(0);
;         afc[0] = afn[0]; afc[1] = afn[1];
;       }
.LBB0_135:
	s_mul_i32 s12, s11, 0xab
	s_add_i32 s13, s12, 0xfeaa
	s_bfe_u32 s13, s13, 0x70009
	s_mul_i32 s13, s13, 3
	s_sub_i32 s13, s11, s13
	s_add_i32 s13, s13, 0xfffe
	s_and_b32 s13, s13, 0xff
	s_mulk_i32 s13, 0x6000
	v_add_u32_e32 v152, s13, v168
	v_add_u32_e32 v150, s13, v156
	s_bfe_u32 s12, s12, 0x70009
	s_mul_i32 s12, s12, 3
	s_sub_i32 s12, s11, s12
	s_and_b32 s12, s12, 0xff
	s_mulk_i32 s12, 0x6000
	v_add_u32_e32 v186, s12, v151
	v_lshl_add_u64 v[170:171], s[4:5], 1, v[148:149]
	v_readfirstlane_b32 s101, v186
	v_lshl_add_u64 v[172:173], v[170:171], 0, s[74:75]
	v_lshl_add_u64 v[174:175], v[170:171], 0, s[92:93]
	v_lshl_add_u64 v[176:177], v[170:171], 0, s[88:89]
	v_lshl_add_u64 v[170:171], v[170:171], 0, s[6:7]
	v_lshl_add_u64 v[178:179], s[4:5], 1, v[146:147]
	v_lshl_add_u64 v[180:181], v[178:179], 0, s[74:75]
	v_lshl_add_u64 v[178:179], v[178:179], 0, s[92:93]
	s_waitcnt vmcnt(6)
	s_waitcnt lgkmcnt(0)
	s_barrier
	s_mov_b32 m0, s101
	s_nop 0
	global_load_lds_dwordx4 v[172:173], off
	s_add_u32 m0, m0, 0x1000
	s_nop 0
	global_load_lds_dwordx4 v[174:175], off
	s_add_u32 m0, m0, 0x1000
	s_nop 0
	global_load_lds_dwordx4 v[176:177], off
	s_add_u32 m0, m0, 0x1000
	s_nop 0
	global_load_lds_dwordx4 v[170:171], off
	s_add_u32 m0, m0, 0x1000
	s_nop 0
	global_load_lds_dwordx4 v[180:181], off
	s_add_u32 m0, m0, 0x1000
	s_nop 0
	global_load_lds_dwordx4 v[178:179], off
	ds_read_b128 v[170:173], v152 offset:16384
	ds_read_b128 v[174:177], v152 offset:17408
	ds_read_b128 v[178:181], v152 offset:18432
	ds_read_b128 v[182:185], v152 offset:19456
	ds_read_b128 v[186:189], v150
	ds_read_b128 v[190:193], v150 offset:1024
	ds_read_b128 v[194:197], v150 offset:2048
	ds_read_b128 v[210:213], v150 offset:3072
	s_waitcnt lgkmcnt(2)
	v_mfma_f32_16x16x32_bf16 v[126:129], v[170:173], v[186:189], v[126:129]
	v_mfma_f32_16x16x32_bf16 v[122:125], v[174:177], v[186:189], v[122:125]
	v_mfma_f32_16x16x32_bf16 v[118:121], v[178:181], v[186:189], v[118:121]
	v_mfma_f32_16x16x32_bf16 v[114:117], v[182:185], v[186:189], v[114:117]
	v_mfma_f32_16x16x32_bf16 v[110:113], v[170:173], v[190:193], v[110:113]
	v_mfma_f32_16x16x32_bf16 v[106:109], v[174:177], v[190:193], v[106:109]
	v_mfma_f32_16x16x32_bf16 v[102:105], v[178:181], v[190:193], v[102:105]
	v_mfma_f32_16x16x32_bf16 v[98:101], v[182:185], v[190:193], v[98:101]
	ds_read_b128 v[186:189], v150 offset:4096
	ds_read_b128 v[190:193], v150 offset:5120
	s_waitcnt lgkmcnt(2)
	v_mfma_f32_16x16x32_bf16 v[94:97], v[170:173], v[194:197], v[94:97]
	v_mfma_f32_16x16x32_bf16 v[90:93], v[174:177], v[194:197], v[90:93]
	v_mfma_f32_16x16x32_bf16 v[86:89], v[178:181], v[194:197], v[86:89]
	v_mfma_f32_16x16x32_bf16 v[82:85], v[182:185], v[194:197], v[82:85]
	v_mfma_f32_16x16x32_bf16 v[78:81], v[170:173], v[210:213], v[78:81]
	v_mfma_f32_16x16x32_bf16 v[74:77], v[174:177], v[210:213], v[74:77]
	v_mfma_f32_16x16x32_bf16 v[70:73], v[178:181], v[210:213], v[70:73]
	v_mfma_f32_16x16x32_bf16 v[66:69], v[182:185], v[210:213], v[66:69]
	ds_read_b128 v[194:197], v150 offset:6144
	ds_read_b128 v[210:213], v150 offset:7168
	s_waitcnt lgkmcnt(2)
	v_mfma_f32_16x16x32_bf16 v[62:65], v[170:173], v[186:189], v[62:65]
	v_mfma_f32_16x16x32_bf16 v[58:61], v[174:177], v[186:189], v[58:61]
	v_mfma_f32_16x16x32_bf16 v[54:57], v[178:181], v[186:189], v[54:57]
	v_mfma_f32_16x16x32_bf16 v[50:53], v[182:185], v[186:189], v[50:53]
	v_mfma_f32_16x16x32_bf16 v[46:49], v[170:173], v[190:193], v[46:49]
	v_mfma_f32_16x16x32_bf16 v[42:45], v[174:177], v[190:193], v[42:45]
	v_mfma_f32_16x16x32_bf16 v[38:41], v[178:181], v[190:193], v[38:41]
	v_mfma_f32_16x16x32_bf16 v[34:37], v[182:185], v[190:193], v[34:37]
	s_waitcnt lgkmcnt(0)
	v_mfma_f32_16x16x32_bf16 v[30:33], v[170:173], v[194:197], v[30:33]
	v_mfma_f32_16x16x32_bf16 v[26:29], v[174:177], v[194:197], v[26:29]
	v_mfma_f32_16x16x32_bf16 v[22:25], v[178:181], v[194:197], v[22:25]
	v_mfma_f32_16x16x32_bf16 v[18:21], v[182:185], v[194:197], v[18:21]
	v_mfma_f32_16x16x32_bf16 v[14:17], v[170:173], v[210:213], v[14:17]
	v_mfma_f32_16x16x32_bf16 v[10:13], v[174:177], v[210:213], v[10:13]
	v_mfma_f32_16x16x32_bf16 v[6:9], v[178:181], v[210:213], v[6:9]
	v_mfma_f32_16x16x32_bf16 v[2:5], v[182:185], v[210:213], v[2:5]
	s_add_u32 s4, s4, 64
	s_addc_u32 s5, s5, 0
	s_add_i32 s11, s11, 1
	s_cmpk_eq_i32 s4, 0x780
	s_cbranch_scc0 .LBB0_135
	s_waitcnt vmcnt(6)
	s_waitcnt lgkmcnt(0)
	s_barrier
; #define MFMA(a, b, c) __builtin_amdgcn_mfma_f32_16x16x32_bf16((a), (b), (c), 0, 0, 0)
; template <int EPI, int MF>
; __device__ __forceinline__ void gemm_part(const u16* __restrict__ A, int lda, const u16* __restrict__ Bt, int K, int ntn, GemmEpi ep, char* smem,
;                                           int mbase, int mrows) {
;     ...
; #pragma unroll
;       for (int n = 0; n < 4; ++n) bfr[n] = rd_std(b_ + (wc * 64 + n * 16 + fr) * 32 + fq * 8);
;       afc[0] = rd_std(ap_); afc[1] = rd_std(ap_ + 16 * 32);
;       __builtin_amdgcn_sched_barrier(0);
;       if (kt + 2 < nk) GEMM_ISSUE(kt + 2);
;       __builtin_amdgcn_sched_barrier(0);
; #pragma unroll
;       for (int mh = 0; mh < MF / 2; ++mh) {
;         if (mh + 1 < MF / 2) {
;           afn[0] = rd_std(ap_ + ((mh + 1) * 2) * 16 * 32);
;           afn[1] = rd_std(ap_ + ((mh + 1) * 2 + 1) * 16 * 32);
;         }
;         __builtin_amdgcn_sched_barrier(0);
; #pragma unroll
;         for (int m = 0; m < 2; ++m)
; #pragma unroll
;           for (int n = 0; n < 4; ++n) acc[mh * 2 + m][n] = MFMA(bfr[n], afc[m], acc[mh * 2 + m][n]);
;         __builtin_amdgcn_sched_barrier(0);
;         afc[0] = afn[0]; afc[1] = afn[1];
;       }
;     }
;     ...
;     __syncthreads();
; #pragma unroll
;     for (int m = 0; m < MF; ++m) {
;       if (EPI == EPI_SWIGLU || (m & 1) == 0) __builtin_amdgcn_sched_barrier(0);
;       const int row = row0 + wr * (16 * MF) + m * 16 + fr;
;       const int cb = col0 + wc * 64 + 4 * fq;
;       float rstd = 1.f;
;       if (EPI != EPI_RESID) { if (ep.rss_in) rstd = rsqrtf(ep.rss_in[row] * (1.f / DM) + 1e-6f); }
	ds_read_b128 v[146:149], v168 offset:16384
	ds_read_b128 v[170:173], v168 offset:17408
	ds_read_b128 v[174:177], v168 offset:18432
	ds_read_b128 v[178:181], v168 offset:19456
	ds_read_b128 v[182:185], v156
	ds_read_b128 v[186:189], v156 offset:1024
	ds_read_b128 v[190:193], v156 offset:2048
	ds_read_b128 v[194:197], v156 offset:3072
	s_waitcnt lgkmcnt(0)
	v_mfma_f32_16x16x32_bf16 v[126:129], v[146:149], v[182:185], v[126:129]
	v_mfma_f32_16x16x32_bf16 v[122:125], v[170:173], v[182:185], v[122:125]
	v_mfma_f32_16x16x32_bf16 v[114:117], v[178:181], v[182:185], v[114:117]
	v_mfma_f32_16x16x32_bf16 v[110:113], v[146:149], v[186:189], v[110:113]
	v_mfma_f32_16x16x32_bf16 v[106:109], v[170:173], v[186:189], v[106:109]
	v_mfma_f32_16x16x32_bf16 v[98:101], v[178:181], v[186:189], v[98:101]
	v_mfma_f32_16x16x32_bf16 v[210:213], v[174:177], v[182:185], v[118:121]
	v_mfma_f32_16x16x32_bf16 v[182:185], v[174:177], v[186:189], v[102:105]
	s_nop 2
	ds_read_b128 v[102:105], v156 offset:4096
	ds_read_b128 v[118:121], v156 offset:5120
	v_mfma_f32_16x16x32_bf16 v[94:97], v[146:149], v[190:193], v[94:97]
	v_mfma_f32_16x16x32_bf16 v[90:93], v[170:173], v[190:193], v[90:93]
	v_mfma_f32_16x16x32_bf16 v[82:85], v[178:181], v[190:193], v[82:85]
	v_mfma_f32_16x16x32_bf16 v[78:81], v[146:149], v[194:197], v[78:81]
	v_mfma_f32_16x16x32_bf16 v[74:77], v[170:173], v[194:197], v[74:77]
	v_mfma_f32_16x16x32_bf16 v[66:69], v[178:181], v[194:197], v[66:69]
	v_mfma_f32_16x16x32_bf16 v[186:189], v[174:177], v[190:193], v[86:89]
	v_mfma_f32_16x16x32_bf16 v[190:193], v[174:177], v[194:197], v[70:73]
	s_nop 2
	ds_read_b128 v[70:73], v156 offset:6144
	ds_read_b128 v[86:89], v156 offset:7168
	s_waitcnt lgkmcnt(0)
	v_mfma_f32_16x16x32_bf16 v[62:65], v[146:149], v[102:105], v[62:65]
	v_mfma_f32_16x16x32_bf16 v[58:61], v[170:173], v[102:105], v[58:61]
	v_mfma_f32_16x16x32_bf16 v[50:53], v[178:181], v[102:105], v[50:53]
	v_mfma_f32_16x16x32_bf16 v[46:49], v[146:149], v[118:121], v[46:49]
	v_mfma_f32_16x16x32_bf16 v[42:45], v[170:173], v[118:121], v[42:45]
	v_mfma_f32_16x16x32_bf16 v[34:37], v[178:181], v[118:121], v[34:37]
	v_mfma_f32_16x16x32_bf16 v[194:197], v[174:177], v[102:105], v[54:57]
	v_mfma_f32_16x16x32_bf16 v[214:217], v[174:177], v[118:121], v[38:41]
	v_mfma_f32_16x16x32_bf16 v[30:33], v[146:149], v[70:73], v[30:33]
	v_mfma_f32_16x16x32_bf16 v[26:29], v[170:173], v[70:73], v[26:29]
	v_mfma_f32_16x16x32_bf16 v[18:21], v[178:181], v[70:73], v[18:21]
	v_mfma_f32_16x16x32_bf16 v[14:17], v[146:149], v[86:89], v[14:17]
	v_mfma_f32_16x16x32_bf16 v[10:13], v[170:173], v[86:89], v[10:13]
	v_mfma_f32_16x16x32_bf16 v[146:149], v[174:177], v[86:89], v[6:9]
	v_mfma_f32_16x16x32_bf16 v[2:5], v[178:181], v[86:89], v[2:5]
	v_mfma_f32_16x16x32_bf16 v[218:221], v[174:177], v[70:73], v[22:25]
	s_waitcnt vmcnt(0)
	s_waitcnt lgkmcnt(0)
	s_barrier
	ds_read_b128 v[6:9], v168 offset:40960
	ds_read_b128 v[170:173], v168 offset:41984
	ds_read_b128 v[174:177], v168 offset:43008
	ds_read_b128 v[178:181], v168 offset:44032
	ds_read_b128 v[22:25], v156 offset:24576
	ds_read_b128 v[38:41], v156 offset:25600
	ds_read_b128 v[54:57], v156 offset:26624
	ds_read_b128 v[222:225], v156 offset:27648
	s_waitcnt lgkmcnt(0)
	v_mfma_f32_16x16x32_bf16 v[126:129], v[6:9], v[22:25], v[126:129]
	v_mfma_f32_16x16x32_bf16 v[118:121], v[170:173], v[22:25], v[122:125]
	v_mfma_f32_16x16x32_bf16 v[122:125], v[174:177], v[22:25], v[210:213]
	v_mfma_f32_16x16x32_bf16 v[114:117], v[178:181], v[22:25], v[114:117]
	v_mfma_f32_16x16x32_bf16 v[110:113], v[6:9], v[38:41], v[110:113]
	v_mfma_f32_16x16x32_bf16 v[102:105], v[170:173], v[38:41], v[106:109]
	v_mfma_f32_16x16x32_bf16 v[106:109], v[174:177], v[38:41], v[182:185]
	v_mfma_f32_16x16x32_bf16 v[98:101], v[178:181], v[38:41], v[98:101]
	ds_read_b128 v[22:25], v156 offset:28672
	s_nop 0
	ds_read_b128 v[182:185], v156 offset:29696
	v_mfma_f32_16x16x32_bf16 v[94:97], v[6:9], v[54:57], v[94:97]
	v_mfma_f32_16x16x32_bf16 v[86:89], v[170:173], v[54:57], v[90:93]
	v_mfma_f32_16x16x32_bf16 v[90:93], v[174:177], v[54:57], v[186:189]
	v_mfma_f32_16x16x32_bf16 v[82:85], v[178:181], v[54:57], v[82:85]
	v_mfma_f32_16x16x32_bf16 v[78:81], v[6:9], v[222:225], v[78:81]
	v_mfma_f32_16x16x32_bf16 v[70:73], v[170:173], v[222:225], v[74:77]
	v_mfma_f32_16x16x32_bf16 v[74:77], v[174:177], v[222:225], v[190:193]
	v_mfma_f32_16x16x32_bf16 v[66:69], v[178:181], v[222:225], v[66:69]
	ds_read_b128 v[186:189], v156 offset:30720
	s_nop 0
	ds_read_b128 v[190:193], v156 offset:31744
	s_waitcnt lgkmcnt(0)
	v_mfma_f32_16x16x32_bf16 v[62:65], v[6:9], v[22:25], v[62:65]
	v_mfma_f32_16x16x32_bf16 v[54:57], v[170:173], v[22:25], v[58:61]
	v_mfma_f32_16x16x32_bf16 v[58:61], v[174:177], v[22:25], v[194:197]
	v_mfma_f32_16x16x32_bf16 v[50:53], v[178:181], v[22:25], v[50:53]
	v_mfma_f32_16x16x32_bf16 v[46:49], v[6:9], v[182:185], v[46:49]
	v_mfma_f32_16x16x32_bf16 v[38:41], v[170:173], v[182:185], v[42:45]
	v_mfma_f32_16x16x32_bf16 v[42:45], v[174:177], v[182:185], v[214:217]
	v_mfma_f32_16x16x32_bf16 v[34:37], v[178:181], v[182:185], v[34:37]
	v_mfma_f32_16x16x32_bf16 v[30:33], v[6:9], v[186:189], v[30:33]
	v_mfma_f32_16x16x32_bf16 v[22:25], v[170:173], v[186:189], v[26:29]
	v_mfma_f32_16x16x32_bf16 v[26:29], v[174:177], v[186:189], v[218:221]
	v_mfma_f32_16x16x32_bf16 v[18:21], v[178:181], v[186:189], v[18:21]
	v_mfma_f32_16x16x32_bf16 v[14:17], v[6:9], v[190:193], v[14:17]
	v_mfma_f32_16x16x32_bf16 v[6:9], v[170:173], v[190:193], v[10:13]
	v_mfma_f32_16x16x32_bf16 v[10:13], v[174:177], v[190:193], v[146:149]
	v_mfma_f32_16x16x32_bf16 v[2:5], v[178:181], v[190:193], v[2:5]
	s_nop 1
	v_add_u32_e32 v146, s9, v154
	s_waitcnt vmcnt(0)
	s_barrier
	v_readlane_b32 s4, v252, 1
	v_readlane_b32 s5, v252, 2
	v_ashrrev_i32_e32 v147, 31, v146
	v_mov_b32_e32 v150, 1.0
	s_and_b64 vcc, exec, s[4:5]
	v_mov_b32_e32 v152, 1.0
	s_cbranch_vccz .LBB0_138
	v_lshl_add_u64 v[148:149], v[146:147], 2, s[14:15]
	global_load_dword v147, v[148:149], off
	s_waitcnt vmcnt(0)
	v_fmamk_f32 v147, v147, 0x3a800000, v142
	v_mul_f32_e32 v148, 0x4b800000, v147
	v_cmp_gt_f32_e32 vcc, s69, v147
	s_nop 1
	v_cndmask_b32_e32 v147, v147, v148, vcc
	v_rsq_f32_e32 v147, v147
	s_nop 0
	v_mul_f32_e32 v148, 0x45800000, v147
	v_cndmask_b32_e32 v152, v147, v148, vcc

; #define MFMA(a, b, c) __builtin_amdgcn_mfma_f32_16x16x32_bf16((a), (b), (c), 0, 0, 0)
; template <int EPI, int MF>
; __device__ __forceinline__ void gemm_part(const u16* __restrict__ A, int lda, const u16* __restrict__ Bt, int K, int ntn, GemmEpi ep, char* smem,
;                                           int mbase, int mrows) {
;     ...
;     GEMM_ISSUE(0);
;     GEMM_ISSUE(1);
;     for (int kt = 0; kt < nk; ++kt) {
;       if (kt + 1 < nk) {
;         if (MF == 8) asm volatile("s_waitcnt vmcnt(6)" ::: "memory");
;         else asm volatile("s_waitcnt vmcnt(3)" ::: "memory");
;       } else asm volatile("s_waitcnt vmcnt(0)" ::: "memory");
;       asm volatile("s_waitcnt lgkmcnt(0)" ::: "memory");
;       __builtin_amdgcn_s_barrier();
;       const u16* a_ = sbase + (kt % 3) * STG;
;       const u16* b_ = a_ + BM * 32;
;       bf16x8 bfr[4], afc[2], afn[2];
;       const u16* ap_ = a_ + (wr * (16 * MF) + fr) * 32 + fq * 8;
; #pragma unroll
;       for (int n = 0; n < 4; ++n) bfr[n] = rd_std(b_ + (wc * 64 + n * 16 + fr) * 32 + fq * 8);
;       afc[0] = rd_std(ap_); afc[1] = rd_std(ap_ + 16 * 32);
;       __builtin_amdgcn_sched_barrier(0);
;       if (kt + 2 < nk) GEMM_ISSUE(kt + 2);
;       __builtin_amdgcn_sched_barrier(0);
; #pragma unroll
;       for (int mh = 0; mh < MF / 2; ++mh) {
;         if (mh + 1 < MF / 2) {
;           afn[0] = rd_std(ap_ + ((mh + 1) * 2) * 16 * 32);
;           afn[1] = rd_std(ap_ + ((mh + 1) * 2 + 1) * 16 * 32);
;         }
;         __builtin_amdgcn_sched_barrier(0);
; #pragma unroll
;         for (int m = 0; m < 2; ++m)
; #pragma unroll
;           for (int n = 0; n < 4; ++n) acc[mh * 2 + m][n] = MFMA(bfr[n], afc[m], acc[mh * 2 + m][n]);
;         __builtin_amdgcn_sched_barrier(0);
;         afc[0] = afn[0]; afc[1] = afn[1];
;       }
.LBB0_205:
	s_mul_hi_u32 s17, s16, 0xaaaaaaab
	s_lshr_b32 s17, s17, 1
	s_mul_i32 s17, s17, 0x12000
	v_add_u32_e32 v146, s3, v161
	v_subrev_u32_e32 v147, s17, v164
	v_subrev_u32_e32 v148, s17, v160
	v_add_u32_e32 v170, v146, v147
	v_add_u32_e32 v190, v146, v148
	s_mul_hi_u32 s17, s15, 0xaaaaaaab
	s_add_i32 s16, s16, 1
	s_lshr_b32 s17, s17, 1
	s_mul_i32 s17, s17, 0x12000
	s_sub_i32 s17, s3, s17
	s_add_i32 s22, s17, 0xc000
	v_add_u32_e32 v178, s22, v154
	v_lshl_add_u64 v[150:151], v[136:137], 0, v[134:135]
	v_readfirstlane_b32 s101, v178
	v_lshl_add_u64 v[152:153], v[150:151], 0, s[74:75]
	v_lshl_add_u64 v[166:167], v[150:151], 0, s[56:57]
	v_lshl_add_u64 v[168:169], v[150:151], 0, s[58:59]
	v_lshl_add_u64 v[150:151], v[150:151], 0, s[86:87]
	v_lshl_add_u64 v[174:175], v[138:139], 0, v[134:135]
	v_lshl_add_u64 v[176:177], v[174:175], 0, s[74:75]
	v_lshl_add_u64 v[174:175], v[174:175], 0, s[56:57]
	s_waitcnt vmcnt(6)
	s_waitcnt lgkmcnt(0)
	s_barrier
	s_mov_b32 m0, s101
	s_nop 0
	global_load_lds_dwordx4 v[152:153], off
	s_add_u32 m0, m0, 0x1000
	s_nop 0
	global_load_lds_dwordx4 v[166:167], off
	s_add_u32 m0, m0, 0x1000
	s_nop 0
	global_load_lds_dwordx4 v[168:169], off
	s_add_u32 m0, m0, 0x1000
	s_nop 0
	global_load_lds_dwordx4 v[150:151], off
	s_add_u32 m0, m0, 0x1000
	s_nop 0
	global_load_lds_dwordx4 v[176:177], off
	s_add_u32 m0, m0, 0x1000
	s_nop 0
	global_load_lds_dwordx4 v[174:175], off
	ds_read_b128 v[146:149], v170 offset:16384
	ds_read_b128 v[150:153], v170 offset:17408
	ds_read_b128 v[166:169], v170 offset:18432
	ds_read_b128 v[170:173], v170 offset:19456
	ds_read_b128 v[174:177], v190
	ds_read_b128 v[178:181], v190 offset:1024
	ds_read_b128 v[182:185], v190 offset:3072
	ds_read_b128 v[186:189], v190 offset:2048
	s_waitcnt lgkmcnt(2)
	v_mfma_f32_16x16x32_bf16 v[126:129], v[146:149], v[174:177], v[126:129]
	v_mfma_f32_16x16x32_bf16 v[122:125], v[150:153], v[174:177], v[122:125]
	v_mfma_f32_16x16x32_bf16 v[118:121], v[166:169], v[174:177], v[118:121]
	v_mfma_f32_16x16x32_bf16 v[114:117], v[170:173], v[174:177], v[114:117]
	v_mfma_f32_16x16x32_bf16 v[110:113], v[146:149], v[178:181], v[110:113]
	v_mfma_f32_16x16x32_bf16 v[106:109], v[150:153], v[178:181], v[106:109]
	v_mfma_f32_16x16x32_bf16 v[102:105], v[166:169], v[178:181], v[102:105]
	v_mfma_f32_16x16x32_bf16 v[98:101], v[170:173], v[178:181], v[98:101]
	ds_read_b128 v[174:177], v190 offset:5120
	ds_read_b128 v[178:181], v190 offset:4096
	s_waitcnt lgkmcnt(2)
	v_mfma_f32_16x16x32_bf16 v[94:97], v[146:149], v[186:189], v[94:97]
	v_mfma_f32_16x16x32_bf16 v[90:93], v[150:153], v[186:189], v[90:93]
	v_mfma_f32_16x16x32_bf16 v[86:89], v[166:169], v[186:189], v[86:89]
	v_mfma_f32_16x16x32_bf16 v[82:85], v[170:173], v[186:189], v[82:85]
	v_mfma_f32_16x16x32_bf16 v[78:81], v[146:149], v[182:185], v[78:81]
	v_mfma_f32_16x16x32_bf16 v[74:77], v[150:153], v[182:185], v[74:77]
	v_mfma_f32_16x16x32_bf16 v[70:73], v[166:169], v[182:185], v[70:73]
	v_mfma_f32_16x16x32_bf16 v[66:69], v[170:173], v[182:185], v[66:69]
	ds_read_b128 v[182:185], v190 offset:7168
	ds_read_b128 v[186:189], v190 offset:6144
	s_waitcnt lgkmcnt(2)
	v_mfma_f32_16x16x32_bf16 v[62:65], v[146:149], v[178:181], v[62:65]
	v_mfma_f32_16x16x32_bf16 v[58:61], v[150:153], v[178:181], v[58:61]
	v_mfma_f32_16x16x32_bf16 v[54:57], v[166:169], v[178:181], v[54:57]
	v_mfma_f32_16x16x32_bf16 v[50:53], v[170:173], v[178:181], v[50:53]
	v_mfma_f32_16x16x32_bf16 v[46:49], v[146:149], v[174:177], v[46:49]
	v_mfma_f32_16x16x32_bf16 v[42:45], v[150:153], v[174:177], v[42:45]
	v_mfma_f32_16x16x32_bf16 v[38:41], v[166:169], v[174:177], v[38:41]
	v_mfma_f32_16x16x32_bf16 v[34:37], v[170:173], v[174:177], v[34:37]
	s_waitcnt lgkmcnt(0)
	v_mfma_f32_16x16x32_bf16 v[30:33], v[146:149], v[186:189], v[30:33]
	v_mfma_f32_16x16x32_bf16 v[26:29], v[150:153], v[186:189], v[26:29]
	v_mfma_f32_16x16x32_bf16 v[22:25], v[166:169], v[186:189], v[22:25]
	v_mfma_f32_16x16x32_bf16 v[18:21], v[170:173], v[186:189], v[18:21]
	v_mfma_f32_16x16x32_bf16 v[14:17], v[146:149], v[182:185], v[14:17]
	v_mfma_f32_16x16x32_bf16 v[10:13], v[150:153], v[182:185], v[10:13]
	v_mfma_f32_16x16x32_bf16 v[6:9], v[166:169], v[182:185], v[6:9]
	v_mfma_f32_16x16x32_bf16 v[2:5], v[170:173], v[182:185], v[2:5]
	s_addk_i32 s3, 0x6000
	s_add_i32 s14, s14, 1
	s_add_i32 s15, s15, 1
	v_lshl_add_u64 v[136:137], v[136:137], 0, 64
	v_lshl_add_u64 v[136:137], v[136:137], 0, 64
	s_cmp_eq_u32 s3, 0x204000
	v_lshl_add_u64 v[138:139], v[138:139], 0, 64
	v_lshl_add_u64 v[138:139], v[138:139], 0, 64
	s_cbranch_scc0 .LBB0_205
	s_waitcnt vmcnt(6)
	s_waitcnt lgkmcnt(0)
	s_barrier
; #define MFMA(a, b, c) __builtin_amdgcn_mfma_f32_16x16x32_bf16((a), (b), (c), 0, 0, 0)
; template <int EPI, int MF>
; __device__ __forceinline__ void gemm_part(const u16* __restrict__ A, int lda, const u16* __restrict__ Bt, int K, int ntn, GemmEpi ep, char* smem,
;                                           int mbase, int mrows) {
;     ...
; #pragma unroll
;       for (int n = 0; n < 4; ++n) bfr[n] = rd_std(b_ + (wc * 64 + n * 16 + fr) * 32 + fq * 8);
;       afc[0] = rd_std(ap_); afc[1] = rd_std(ap_ + 16 * 32);
;       __builtin_amdgcn_sched_barrier(0);
;       if (kt + 2 < nk) GEMM_ISSUE(kt + 2);
;       __builtin_amdgcn_sched_barrier(0);
; #pragma unroll
;       for (int mh = 0; mh < MF / 2; ++mh) {
;         if (mh + 1 < MF / 2) {
;           afn[0] = rd_std(ap_ + ((mh + 1) * 2) * 16 * 32);
;           afn[1] = rd_std(ap_ + ((mh + 1) * 2 + 1) * 16 * 32);
;         }
;         __builtin_amdgcn_sched_barrier(0);
; #pragma unroll
;         for (int m = 0; m < 2; ++m)
; #pragma unroll
;           for (int n = 0; n < 4; ++n) acc[mh * 2 + m][n] = MFMA(bfr[n], afc[m], acc[mh * 2 + m][n]);
;         __builtin_amdgcn_sched_barrier(0);
;         afc[0] = afn[0]; afc[1] = afn[1];
;       }
	ds_read_b128 v[136:139], v165
	ds_read_b128 v[146:149], v165 offset:1024
	ds_read_b128 v[150:153], v165 offset:2048
	ds_read_b128 v[166:169], v165 offset:3072
	ds_read_b128 v[170:173], v162 offset:49152
	ds_read_b128 v[174:177], v162 offset:50176
	s_mul_hi_u32 s14, s14, 0xaaaaaaab
	s_lshr_b32 s14, s14, 1
	s_mul_i32 s14, s14, 0x12000
	s_sub_i32 s3, s3, s14
	s_add_i32 s3, s3, 0
	s_addk_i32 s3, 0x6000
	ds_read_b128 v[178:181], v162 offset:52224
	ds_read_b128 v[182:185], v162 offset:51200
	s_waitcnt lgkmcnt(0)
	v_mfma_f32_16x16x32_bf16 v[126:129], v[136:139], v[170:173], v[126:129]
	v_mfma_f32_16x16x32_bf16 v[122:125], v[146:149], v[170:173], v[122:125]
	v_mfma_f32_16x16x32_bf16 v[118:121], v[150:153], v[170:173], v[118:121]
	v_mfma_f32_16x16x32_bf16 v[114:117], v[166:169], v[170:173], v[114:117]
	v_mfma_f32_16x16x32_bf16 v[110:113], v[136:139], v[174:177], v[110:113]
	v_mfma_f32_16x16x32_bf16 v[106:109], v[146:149], v[174:177], v[106:109]
	v_mfma_f32_16x16x32_bf16 v[102:105], v[150:153], v[174:177], v[102:105]
	v_mfma_f32_16x16x32_bf16 v[98:101], v[166:169], v[174:177], v[98:101]
	ds_read_b128 v[170:173], v162 offset:54272
	ds_read_b128 v[174:177], v162 offset:53248
	v_mfma_f32_16x16x32_bf16 v[94:97], v[136:139], v[182:185], v[94:97]
	v_mfma_f32_16x16x32_bf16 v[90:93], v[146:149], v[182:185], v[90:93]
	v_mfma_f32_16x16x32_bf16 v[86:89], v[150:153], v[182:185], v[86:89]
	v_mfma_f32_16x16x32_bf16 v[82:85], v[166:169], v[182:185], v[82:85]
	v_mfma_f32_16x16x32_bf16 v[78:81], v[136:139], v[178:181], v[78:81]
	v_mfma_f32_16x16x32_bf16 v[74:77], v[146:149], v[178:181], v[74:77]
	v_mfma_f32_16x16x32_bf16 v[70:73], v[150:153], v[178:181], v[70:73]
	v_mfma_f32_16x16x32_bf16 v[66:69], v[166:169], v[178:181], v[66:69]
	ds_read_b128 v[178:181], v162 offset:56320
	ds_read_b128 v[182:185], v162 offset:55296
	s_waitcnt lgkmcnt(0)
	v_mfma_f32_16x16x32_bf16 v[62:65], v[136:139], v[174:177], v[62:65]
	v_mfma_f32_16x16x32_bf16 v[58:61], v[146:149], v[174:177], v[58:61]
	v_mfma_f32_16x16x32_bf16 v[54:57], v[150:153], v[174:177], v[54:57]
	v_mfma_f32_16x16x32_bf16 v[50:53], v[166:169], v[174:177], v[50:53]
	v_mfma_f32_16x16x32_bf16 v[46:49], v[136:139], v[170:173], v[46:49]
	v_mfma_f32_16x16x32_bf16 v[42:45], v[146:149], v[170:173], v[42:45]
	v_mfma_f32_16x16x32_bf16 v[38:41], v[150:153], v[170:173], v[38:41]
	v_mfma_f32_16x16x32_bf16 v[34:37], v[166:169], v[170:173], v[34:37]
	v_mfma_f32_16x16x32_bf16 v[30:33], v[136:139], v[182:185], v[30:33]
	v_mfma_f32_16x16x32_bf16 v[26:29], v[146:149], v[182:185], v[26:29]
	v_mfma_f32_16x16x32_bf16 v[22:25], v[150:153], v[182:185], v[22:25]
	v_mfma_f32_16x16x32_bf16 v[18:21], v[166:169], v[182:185], v[18:21]
	v_mfma_f32_16x16x32_bf16 v[14:17], v[136:139], v[178:181], v[14:17]
	v_mfma_f32_16x16x32_bf16 v[10:13], v[146:149], v[178:181], v[10:13]
	v_mfma_f32_16x16x32_bf16 v[6:9], v[150:153], v[178:181], v[6:9]
	v_mfma_f32_16x16x32_bf16 v[2:5], v[166:169], v[178:181], v[2:5]
	v_add_u32_e32 v136, s3, v161
	s_waitcnt vmcnt(0)
	v_add3_u32 v166, v136, v158, v159
	s_waitcnt lgkmcnt(0)
	s_barrier
; #define MFMA(a, b, c) __builtin_amdgcn_mfma_f32_16x16x32_bf16((a), (b), (c), 0, 0, 0)
; template <int EPI, int MF>
; __device__ __forceinline__ void gemm_part(const u16* __restrict__ A, int lda, const u16* __restrict__ Bt, int K, int ntn, GemmEpi ep, char* smem,
;                                           int mbase, int mrows) {
;     ...
; #pragma unroll
;       for (int n = 0; n < 4; ++n) bfr[n] = rd_std(b_ + (wc * 64 + n * 16 + fr) * 32 + fq * 8);
;       afc[0] = rd_std(ap_); afc[1] = rd_std(ap_ + 16 * 32);
;       __builtin_amdgcn_sched_barrier(0);
;       if (kt + 2 < nk) GEMM_ISSUE(kt + 2);
;       __builtin_amdgcn_sched_barrier(0);
; #pragma unroll
;       for (int mh = 0; mh < MF / 2; ++mh) {
;         if (mh + 1 < MF / 2) {
;           afn[0] = rd_std(ap_ + ((mh + 1) * 2) * 16 * 32);
;           afn[1] = rd_std(ap_ + ((mh + 1) * 2 + 1) * 16 * 32);
;         }
;         __builtin_amdgcn_sched_barrier(0);
; #pragma unroll
;         for (int m = 0; m < 2; ++m)
; #pragma unroll
;           for (int n = 0; n < 4; ++n) acc[mh * 2 + m][n] = MFMA(bfr[n], afc[m], acc[mh * 2 + m][n]);
;         __builtin_amdgcn_sched_barrier(0);
;         afc[0] = afn[0]; afc[1] = afn[1];
;       }
;     ...
;       } else if (EPI == EPI_RESID) {
;         const float* rp = (row < MP) ? ep.res0 + (size_t)row * DM : ep.res1 + (size_t)(row - MP) * DM;
;         float ssq = 0.f;
; #pragma unroll
;         for (int n = 0; n < 4; ++n) {
;           const int col = cb + n * 16;
;           const float4 r = *(const float4*)(rp + col);
;           float4 v;
;           v.x = r.x + ep.scale * acc[m][n][0]; v.y = r.y + ep.scale * acc[m][n][1];
;           v.z = r.z + ep.scale * acc[m][n][2]; v.w = r.w + ep.scale * acc[m][n][3];
;           *(float4*)(ep.outf + (size_t)row * DM + col) = v;
;           if (ep.xcopy) {
;             bf16x4 o;
;             o[0] = (short)f2bf(v.x); o[1] = (short)f2bf(v.y); o[2] = (short)f2bf(v.z); o[3] = (short)f2bf(v.w);
;             *(bf16x4*)(ep.xcopy + (size_t)row * DM + col) = o;
	ds_read_b128 v[136:139], v166 offset:16384
	ds_read_b128 v[146:149], v166 offset:17408
	ds_read_b128 v[150:153], v166 offset:18432
	ds_read_b128 v[166:169], v166 offset:19456
	ds_read_b128 v[170:173], v162
	ds_read_b128 v[174:177], v162 offset:1024
	ds_read_b128 v[178:181], v162 offset:3072
	ds_read_b128 v[182:185], v162 offset:2048
	s_waitcnt lgkmcnt(0)
	v_mfma_f32_16x16x32_bf16 v[126:129], v[136:139], v[170:173], v[126:129]
	v_mfma_f32_16x16x32_bf16 v[122:125], v[146:149], v[170:173], v[122:125]
	v_mfma_f32_16x16x32_bf16 v[118:121], v[150:153], v[170:173], v[118:121]
	v_mfma_f32_16x16x32_bf16 v[114:117], v[166:169], v[170:173], v[114:117]
	v_mfma_f32_16x16x32_bf16 v[110:113], v[136:139], v[174:177], v[110:113]
	v_mfma_f32_16x16x32_bf16 v[106:109], v[146:149], v[174:177], v[106:109]
	v_mfma_f32_16x16x32_bf16 v[102:105], v[150:153], v[174:177], v[102:105]
	v_mfma_f32_16x16x32_bf16 v[98:101], v[166:169], v[174:177], v[98:101]
	ds_read_b128 v[170:173], v162 offset:5120
	ds_read_b128 v[174:177], v162 offset:4096
	v_mfma_f32_16x16x32_bf16 v[94:97], v[136:139], v[182:185], v[94:97]
	v_mfma_f32_16x16x32_bf16 v[90:93], v[146:149], v[182:185], v[90:93]
	v_mfma_f32_16x16x32_bf16 v[86:89], v[150:153], v[182:185], v[86:89]
	v_mfma_f32_16x16x32_bf16 v[82:85], v[166:169], v[182:185], v[82:85]
	v_mfma_f32_16x16x32_bf16 v[78:81], v[136:139], v[178:181], v[78:81]
	v_mfma_f32_16x16x32_bf16 v[74:77], v[146:149], v[178:181], v[74:77]
	v_mfma_f32_16x16x32_bf16 v[70:73], v[150:153], v[178:181], v[70:73]
	v_mfma_f32_16x16x32_bf16 v[66:69], v[166:169], v[178:181], v[66:69]
	ds_read_b128 v[178:181], v162 offset:7168
	ds_read_b128 v[182:185], v162 offset:6144
	s_waitcnt lgkmcnt(0)
	v_mfma_f32_16x16x32_bf16 v[62:65], v[136:139], v[174:177], v[62:65]
	v_mfma_f32_16x16x32_bf16 v[58:61], v[146:149], v[174:177], v[58:61]
	v_mfma_f32_16x16x32_bf16 v[54:57], v[150:153], v[174:177], v[54:57]
	v_mfma_f32_16x16x32_bf16 v[50:53], v[166:169], v[174:177], v[50:53]
	v_mfma_f32_16x16x32_bf16 v[46:49], v[136:139], v[170:173], v[46:49]
	v_mfma_f32_16x16x32_bf16 v[42:45], v[146:149], v[170:173], v[42:45]
	v_mfma_f32_16x16x32_bf16 v[38:41], v[150:153], v[170:173], v[38:41]
	v_mfma_f32_16x16x32_bf16 v[34:37], v[166:169], v[170:173], v[34:37]
	v_mfma_f32_16x16x32_bf16 v[30:33], v[136:139], v[182:185], v[30:33]
	v_mfma_f32_16x16x32_bf16 v[26:29], v[146:149], v[182:185], v[26:29]
	v_mfma_f32_16x16x32_bf16 v[22:25], v[150:153], v[182:185], v[22:25]
	v_mfma_f32_16x16x32_bf16 v[18:21], v[166:169], v[182:185], v[18:21]
	v_mfma_f32_16x16x32_bf16 v[14:17], v[136:139], v[178:181], v[14:17]
	v_mfma_f32_16x16x32_bf16 v[10:13], v[146:149], v[178:181], v[10:13]
	v_mfma_f32_16x16x32_bf16 v[6:9], v[150:153], v[178:181], v[6:9]
	v_mfma_f32_16x16x32_bf16 v[2:5], v[166:169], v[178:181], v[2:5]
	v_add_u32_e32 v138, s2, v156
	s_waitcnt vmcnt(0)
	s_barrier
	s_mov_b32 s2, 0xffff
	v_cmp_lt_i32_e32 vcc, s2, v138
	s_and_saveexec_b64 s[2:3], vcc
	s_xor_b64 s[2:3], exec, s[2:3]
	v_add_u32_e32 v136, 0xffff0000, v138
	v_mov_b32_e32 v137, v0
	v_lshlrev_b64 v[136:137], 12, v[136:137]
	v_lshl_add_u64 v[136:137], s[18:19], 0, v[136:137]
	v_mov_b32_e32 v139, v0
	s_andn2_saveexec_b64 s[2:3], s[2:3]
	v_ashrrev_i32_e32 v139, 31, v138
	v_lshlrev_b64 v[136:137], 12, v[138:139]
	v_lshl_add_u64 v[136:137], s[8:9], 0, v[136:137]
	s_or_b64 exec, exec, s[2:3]
	v_lshlrev_b64 v[146:147], 12, v[138:139]
	v_or_b32_e32 v170, s11, v157
	v_lshl_add_u64 v[150:151], s[26:27], 0, v[146:147]
	v_lshlrev_b64 v[146:147], 11, v[138:139]
	v_lshl_add_u64 v[148:149], s[44:45], 0, v[146:147]
	v_lshlrev_b32_e32 v146, 2, v170
	v_mov_b32_e32 v147, v0
	v_lshl_add_u64 v[152:153], v[136:137], 0, v[146:147]
	global_load_dwordx4 v[166:169], v[152:153], off
	global_load_dwordx4 v[172:175], v[152:153], off offset:64
	global_load_dwordx4 v[176:179], v[152:153], off offset:128
	global_load_dwordx4 v[180:183], v[152:153], off offset:192
	v_readlane_b32 s2, v253, 24
	v_readlane_b32 s3, v253, 25
	v_lshl_add_u64 v[150:151], v[150:151], 0, v[146:147]
	s_andn2_b64 vcc, exec, s[2:3]
	v_cndmask_b32_e64 v136, 0, 1, s[2:3]
	v_cmp_ne_u32_e64 s[14:15], 1, v136
	v_lshlrev_b32_e32 v136, 1, v170
	s_waitcnt vmcnt(0)
	v_pk_fma_f32 v[126:127], v[126:127], 0.5, v[166:167] op_sel_hi:[1,0,1]
	v_pk_fma_f32 v[128:129], v[128:129], 0.5, v[168:169] op_sel_hi:[1,0,1]
	global_store_dwordx4 v[150:151], v[126:129], off
	s_cbranch_vccnz .LBB0_212
	v_mov_b32_e32 v137, v0
	v_cvt_pk_bf16_f32 v166, v126, v127
	v_cvt_pk_bf16_f32 v167, v128, v129
	v_lshl_add_u64 v[168:169], v[148:149], 0, v[136:137]
	v_lshlrev_b32_e32 v184, 1, v168
	v_bfi_b32 v184, s100, v184, v168
	v_lshrrev_b32_e32 v185, 5, v168
	v_bfi_b32 v184, 64, v185, v184
	v_mov_b32_e32 v185, v169
	global_store_dwordx2 v[184:185], v[166:167], off

; #define MFMA(a, b, c) __builtin_amdgcn_mfma_f32_16x16x32_bf16((a), (b), (c), 0, 0, 0)
; template <int EPI, int MF>
; __device__ __forceinline__ void gemm_part(const u16* __restrict__ A, int lda, const u16* __restrict__ Bt, int K, int ntn, GemmEpi ep, char* smem,
;                                           int mbase, int mrows) {
;     ...
;     GEMM_ISSUE(0);
;     GEMM_ISSUE(1);
;     for (int kt = 0; kt < nk; ++kt) {
;       if (kt + 1 < nk) {
;         if (MF == 8) asm volatile("s_waitcnt vmcnt(6)" ::: "memory");
;         else asm volatile("s_waitcnt vmcnt(3)" ::: "memory");
;       } else asm volatile("s_waitcnt vmcnt(0)" ::: "memory");
;       asm volatile("s_waitcnt lgkmcnt(0)" ::: "memory");
;       __builtin_amdgcn_s_barrier();
;       const u16* a_ = sbase + (kt % 3) * STG;
;       const u16* b_ = a_ + BM * 32;
;       bf16x8 bfr[4], afc[2], afn[2];
;       const u16* ap_ = a_ + (wr * (16 * MF) + fr) * 32 + fq * 8;
; #pragma unroll
;       for (int n = 0; n < 4; ++n) bfr[n] = rd_std(b_ + (wc * 64 + n * 16 + fr) * 32 + fq * 8);
;       afc[0] = rd_std(ap_); afc[1] = rd_std(ap_ + 16 * 32);
;       __builtin_amdgcn_sched_barrier(0);
;       if (kt + 2 < nk) GEMM_ISSUE(kt + 2);
;       __builtin_amdgcn_sched_barrier(0);
; #pragma unroll
;       for (int mh = 0; mh < MF / 2; ++mh) {
;         if (mh + 1 < MF / 2) {
;           afn[0] = rd_std(ap_ + ((mh + 1) * 2) * 16 * 32);
;           afn[1] = rd_std(ap_ + ((mh + 1) * 2 + 1) * 16 * 32);
;         }
;         __builtin_amdgcn_sched_barrier(0);
; #pragma unroll
;         for (int m = 0; m < 2; ++m)
; #pragma unroll
;           for (int n = 0; n < 4; ++n) acc[mh * 2 + m][n] = MFMA(bfr[n], afc[m], acc[mh * 2 + m][n]);
;         __builtin_amdgcn_sched_barrier(0);
;         afc[0] = afn[0]; afc[1] = afn[1];
;       }
.LBB0_414:
	s_mul_i32 s10, s9, 0xab
	s_add_i32 s11, s10, 0xfeaa
	s_bfe_u32 s11, s11, 0x70009
	s_mul_i32 s11, s11, 3
	s_sub_i32 s11, s9, s11
	s_add_i32 s11, s11, 0xfffe
	s_and_b32 s11, s11, 0xff
	s_mulk_i32 s11, 0x6000
	v_add_u32_e32 v147, s11, v159
	v_add_u32_e32 v148, s11, v158
	s_bfe_u32 s10, s10, 0x70009
	s_mul_i32 s10, s10, 3
	s_sub_i32 s10, s9, s10
	s_and_b32 s10, s10, 0xff
	s_mulk_i32 s10, 0x6000
	v_add_u32_e32 v176, s10, v149
	v_lshl_add_u64 v[160:161], s[2:3], 1, v[138:139]
	v_readfirstlane_b32 s101, v176
	v_lshl_add_u64 v[162:163], v[160:161], 0, s[74:75]
	v_lshl_add_u64 v[164:165], v[160:161], 0, s[92:93]
	v_lshl_add_u64 v[166:167], v[160:161], 0, s[88:89]
	v_lshl_add_u64 v[160:161], v[160:161], 0, s[6:7]
	v_lshl_add_u64 v[168:169], s[2:3], 1, v[136:137]
	v_lshl_add_u64 v[170:171], v[168:169], 0, s[74:75]
	v_lshl_add_u64 v[168:169], v[168:169], 0, s[92:93]
	s_waitcnt vmcnt(6)
	s_waitcnt lgkmcnt(0)
	s_barrier
	s_mov_b32 m0, s101
	s_nop 0
	global_load_lds_dwordx4 v[162:163], off
	s_add_u32 m0, m0, 0x1000
	s_nop 0
	global_load_lds_dwordx4 v[164:165], off
	s_add_u32 m0, m0, 0x1000
	s_nop 0
	global_load_lds_dwordx4 v[166:167], off
	s_add_u32 m0, m0, 0x1000
	s_nop 0
	global_load_lds_dwordx4 v[160:161], off
	s_add_u32 m0, m0, 0x1000
	s_nop 0
	global_load_lds_dwordx4 v[170:171], off
	s_add_u32 m0, m0, 0x1000
	s_nop 0
	global_load_lds_dwordx4 v[168:169], off
	ds_read_b128 v[160:163], v147 offset:16384
	ds_read_b128 v[164:167], v147 offset:17408
	ds_read_b128 v[168:171], v147 offset:18432
	ds_read_b128 v[172:175], v147 offset:19456
	ds_read_b128 v[176:179], v148
	ds_read_b128 v[180:183], v148 offset:1024
	ds_read_b128 v[184:187], v148 offset:3072
	ds_read_b128 v[188:191], v148 offset:2048
	s_waitcnt lgkmcnt(2)
	v_mfma_f32_16x16x32_bf16 v[126:129], v[160:163], v[176:179], v[126:129]
	v_mfma_f32_16x16x32_bf16 v[122:125], v[164:167], v[176:179], v[122:125]
	v_mfma_f32_16x16x32_bf16 v[118:121], v[168:171], v[176:179], v[118:121]
	v_mfma_f32_16x16x32_bf16 v[114:117], v[172:175], v[176:179], v[114:117]
	v_mfma_f32_16x16x32_bf16 v[110:113], v[160:163], v[180:183], v[110:113]
	v_mfma_f32_16x16x32_bf16 v[106:109], v[164:167], v[180:183], v[106:109]
	v_mfma_f32_16x16x32_bf16 v[102:105], v[168:171], v[180:183], v[102:105]
	v_mfma_f32_16x16x32_bf16 v[98:101], v[172:175], v[180:183], v[98:101]
	ds_read_b128 v[176:179], v148 offset:5120
	ds_read_b128 v[180:183], v148 offset:4096
	s_waitcnt lgkmcnt(2)
	v_mfma_f32_16x16x32_bf16 v[94:97], v[160:163], v[188:191], v[94:97]
	v_mfma_f32_16x16x32_bf16 v[90:93], v[164:167], v[188:191], v[90:93]
	v_mfma_f32_16x16x32_bf16 v[86:89], v[168:171], v[188:191], v[86:89]
	v_mfma_f32_16x16x32_bf16 v[82:85], v[172:175], v[188:191], v[82:85]
	v_mfma_f32_16x16x32_bf16 v[78:81], v[160:163], v[184:187], v[78:81]
	v_mfma_f32_16x16x32_bf16 v[74:77], v[164:167], v[184:187], v[74:77]
	v_mfma_f32_16x16x32_bf16 v[70:73], v[168:171], v[184:187], v[70:73]
	v_mfma_f32_16x16x32_bf16 v[66:69], v[172:175], v[184:187], v[66:69]
	ds_read_b128 v[184:187], v148 offset:7168
	ds_read_b128 v[188:191], v148 offset:6144
	s_waitcnt lgkmcnt(2)
	v_mfma_f32_16x16x32_bf16 v[62:65], v[160:163], v[180:183], v[62:65]
	v_mfma_f32_16x16x32_bf16 v[58:61], v[164:167], v[180:183], v[58:61]
	v_mfma_f32_16x16x32_bf16 v[54:57], v[168:171], v[180:183], v[54:57]
	v_mfma_f32_16x16x32_bf16 v[50:53], v[172:175], v[180:183], v[50:53]
	v_mfma_f32_16x16x32_bf16 v[46:49], v[160:163], v[176:179], v[46:49]
	v_mfma_f32_16x16x32_bf16 v[42:45], v[164:167], v[176:179], v[42:45]
	v_mfma_f32_16x16x32_bf16 v[38:41], v[168:171], v[176:179], v[38:41]
	v_mfma_f32_16x16x32_bf16 v[34:37], v[172:175], v[176:179], v[34:37]
	s_waitcnt lgkmcnt(0)
	v_mfma_f32_16x16x32_bf16 v[30:33], v[160:163], v[188:191], v[30:33]
	v_mfma_f32_16x16x32_bf16 v[26:29], v[164:167], v[188:191], v[26:29]
	v_mfma_f32_16x16x32_bf16 v[22:25], v[168:171], v[188:191], v[22:25]
	v_mfma_f32_16x16x32_bf16 v[18:21], v[172:175], v[188:191], v[18:21]
	v_mfma_f32_16x16x32_bf16 v[14:17], v[160:163], v[184:187], v[14:17]
	v_mfma_f32_16x16x32_bf16 v[10:13], v[164:167], v[184:187], v[10:13]
	v_mfma_f32_16x16x32_bf16 v[6:9], v[168:171], v[184:187], v[6:9]
	v_mfma_f32_16x16x32_bf16 v[2:5], v[172:175], v[184:187], v[2:5]
	s_add_u32 s2, s2, 64
	s_addc_u32 s3, s3, 0
	s_add_i32 s9, s9, 1
	s_cmpk_eq_i32 s2, 0x780
	s_cbranch_scc0 .LBB0_414
	s_waitcnt vmcnt(6)
	s_waitcnt lgkmcnt(0)
	s_barrier
; #define MFMA(a, b, c) __builtin_amdgcn_mfma_f32_16x16x32_bf16((a), (b), (c), 0, 0, 0)
; template <int EPI, int MF>
; __device__ __forceinline__ void gemm_part(const u16* __restrict__ A, int lda, const u16* __restrict__ Bt, int K, int ntn, GemmEpi ep, char* smem,
;                                           int mbase, int mrows) {
;     ...
; #pragma unroll
;       for (int n = 0; n < 4; ++n) bfr[n] = rd_std(b_ + (wc * 64 + n * 16 + fr) * 32 + fq * 8);
;       afc[0] = rd_std(ap_); afc[1] = rd_std(ap_ + 16 * 32);
;       __builtin_amdgcn_sched_barrier(0);
;       if (kt + 2 < nk) GEMM_ISSUE(kt + 2);
;       __builtin_amdgcn_sched_barrier(0);
; #pragma unroll
;       for (int mh = 0; mh < MF / 2; ++mh) {
;         if (mh + 1 < MF / 2) {
;           afn[0] = rd_std(ap_ + ((mh + 1) * 2) * 16 * 32);
;           afn[1] = rd_std(ap_ + ((mh + 1) * 2 + 1) * 16 * 32);
;         }
;         __builtin_amdgcn_sched_barrier(0);
; #pragma unroll
;         for (int m = 0; m < 2; ++m)
; #pragma unroll
;           for (int n = 0; n < 4; ++n) acc[mh * 2 + m][n] = MFMA(bfr[n], afc[m], acc[mh * 2 + m][n]);
;         __builtin_amdgcn_sched_barrier(0);
;         afc[0] = afn[0]; afc[1] = afn[1];
;       }
;     }
;     ...
;     __syncthreads();
; #pragma unroll
;     for (int m = 0; m < MF; ++m) {
;       if (EPI == EPI_SWIGLU || (m & 1) == 0) __builtin_amdgcn_sched_barrier(0);
;       const int row = row0 + wr * (16 * MF) + m * 16 + fr;
;       const int cb = col0 + wc * 64 + 4 * fq;
;       float rstd = 1.f;
;       if (EPI != EPI_RESID) { if (ep.rss_in) rstd = rsqrtf(ep.rss_in[row] * (1.f / DM) + 1e-6f); }
	ds_read_b128 v[136:139], v159 offset:16384
	ds_read_b128 v[160:163], v159 offset:17408
	ds_read_b128 v[164:167], v159 offset:18432
	ds_read_b128 v[168:171], v159 offset:19456
	ds_read_b128 v[172:175], v158
	ds_read_b128 v[176:179], v158 offset:1024
	ds_read_b128 v[180:183], v158 offset:3072
	ds_read_b128 v[184:187], v158 offset:2048
	s_waitcnt lgkmcnt(0)
	v_mfma_f32_16x16x32_bf16 v[126:129], v[136:139], v[172:175], v[126:129]
	v_mfma_f32_16x16x32_bf16 v[122:125], v[160:163], v[172:175], v[122:125]
	v_mfma_f32_16x16x32_bf16 v[118:121], v[164:167], v[172:175], v[118:121]
	v_mfma_f32_16x16x32_bf16 v[114:117], v[168:171], v[172:175], v[114:117]
	v_mfma_f32_16x16x32_bf16 v[110:113], v[136:139], v[176:179], v[110:113]
	v_mfma_f32_16x16x32_bf16 v[106:109], v[160:163], v[176:179], v[106:109]
	v_mfma_f32_16x16x32_bf16 v[102:105], v[164:167], v[176:179], v[102:105]
	v_mfma_f32_16x16x32_bf16 v[98:101], v[168:171], v[176:179], v[98:101]
	ds_read_b128 v[172:175], v158 offset:5120
	ds_read_b128 v[176:179], v158 offset:4096
	v_mfma_f32_16x16x32_bf16 v[94:97], v[136:139], v[184:187], v[94:97]
	v_mfma_f32_16x16x32_bf16 v[90:93], v[160:163], v[184:187], v[90:93]
	v_mfma_f32_16x16x32_bf16 v[86:89], v[164:167], v[184:187], v[86:89]
	v_mfma_f32_16x16x32_bf16 v[82:85], v[168:171], v[184:187], v[82:85]
	v_mfma_f32_16x16x32_bf16 v[78:81], v[136:139], v[180:183], v[78:81]
	v_mfma_f32_16x16x32_bf16 v[74:77], v[160:163], v[180:183], v[74:77]
	v_mfma_f32_16x16x32_bf16 v[70:73], v[164:167], v[180:183], v[70:73]
	v_mfma_f32_16x16x32_bf16 v[66:69], v[168:171], v[180:183], v[66:69]
	ds_read_b128 v[180:183], v158 offset:7168
	ds_read_b128 v[184:187], v158 offset:6144
	s_waitcnt lgkmcnt(0)
	v_mfma_f32_16x16x32_bf16 v[62:65], v[136:139], v[176:179], v[62:65]
	v_mfma_f32_16x16x32_bf16 v[58:61], v[160:163], v[176:179], v[58:61]
	v_mfma_f32_16x16x32_bf16 v[54:57], v[164:167], v[176:179], v[54:57]
	v_mfma_f32_16x16x32_bf16 v[50:53], v[168:171], v[176:179], v[50:53]
	v_mfma_f32_16x16x32_bf16 v[46:49], v[136:139], v[172:175], v[46:49]
	v_mfma_f32_16x16x32_bf16 v[42:45], v[160:163], v[172:175], v[42:45]
	v_mfma_f32_16x16x32_bf16 v[38:41], v[164:167], v[172:175], v[38:41]
	v_mfma_f32_16x16x32_bf16 v[34:37], v[168:171], v[172:175], v[34:37]
	v_mfma_f32_16x16x32_bf16 v[30:33], v[136:139], v[184:187], v[30:33]
	v_mfma_f32_16x16x32_bf16 v[26:29], v[160:163], v[184:187], v[26:29]
	v_mfma_f32_16x16x32_bf16 v[22:25], v[164:167], v[184:187], v[22:25]
	v_mfma_f32_16x16x32_bf16 v[18:21], v[168:171], v[184:187], v[18:21]
	v_mfma_f32_16x16x32_bf16 v[14:17], v[136:139], v[180:183], v[14:17]
	v_mfma_f32_16x16x32_bf16 v[10:13], v[160:163], v[180:183], v[10:13]
	v_mfma_f32_16x16x32_bf16 v[6:9], v[164:167], v[180:183], v[6:9]
	v_mfma_f32_16x16x32_bf16 v[2:5], v[168:171], v[180:183], v[2:5]
	s_waitcnt vmcnt(0)
	s_waitcnt lgkmcnt(0)
	s_barrier
	ds_read_b128 v[136:139], v159 offset:40960
	ds_read_b128 v[160:163], v159 offset:41984
	ds_read_b128 v[164:167], v159 offset:43008
	ds_read_b128 v[168:171], v159 offset:44032
	ds_read_b128 v[172:175], v158 offset:24576
	ds_read_b128 v[176:179], v158 offset:25600
	ds_read_b128 v[180:183], v158 offset:27648
	ds_read_b128 v[184:187], v158 offset:26624
	s_waitcnt lgkmcnt(0)
	v_mfma_f32_16x16x32_bf16 v[126:129], v[136:139], v[172:175], v[126:129]
	v_mfma_f32_16x16x32_bf16 v[122:125], v[160:163], v[172:175], v[122:125]
	v_mfma_f32_16x16x32_bf16 v[118:121], v[164:167], v[172:175], v[118:121]
	v_mfma_f32_16x16x32_bf16 v[114:117], v[168:171], v[172:175], v[114:117]
	v_mfma_f32_16x16x32_bf16 v[110:113], v[136:139], v[176:179], v[110:113]
	v_mfma_f32_16x16x32_bf16 v[106:109], v[160:163], v[176:179], v[106:109]
	v_mfma_f32_16x16x32_bf16 v[102:105], v[164:167], v[176:179], v[102:105]
	v_mfma_f32_16x16x32_bf16 v[98:101], v[168:171], v[176:179], v[98:101]
	ds_read_b128 v[172:175], v158 offset:29696
	ds_read_b128 v[176:179], v158 offset:28672
	v_mfma_f32_16x16x32_bf16 v[94:97], v[136:139], v[184:187], v[94:97]
	v_mfma_f32_16x16x32_bf16 v[90:93], v[160:163], v[184:187], v[90:93]
	v_mfma_f32_16x16x32_bf16 v[86:89], v[164:167], v[184:187], v[86:89]
	v_mfma_f32_16x16x32_bf16 v[82:85], v[168:171], v[184:187], v[82:85]
	v_mfma_f32_16x16x32_bf16 v[78:81], v[136:139], v[180:183], v[78:81]
	v_mfma_f32_16x16x32_bf16 v[74:77], v[160:163], v[180:183], v[74:77]
	v_mfma_f32_16x16x32_bf16 v[70:73], v[164:167], v[180:183], v[70:73]
	v_mfma_f32_16x16x32_bf16 v[66:69], v[168:171], v[180:183], v[66:69]
	ds_read_b128 v[180:183], v158 offset:31744
	ds_read_b128 v[184:187], v158 offset:30720
	s_waitcnt lgkmcnt(0)
	v_mfma_f32_16x16x32_bf16 v[62:65], v[136:139], v[176:179], v[62:65]
	v_mfma_f32_16x16x32_bf16 v[58:61], v[160:163], v[176:179], v[58:61]
	v_mfma_f32_16x16x32_bf16 v[54:57], v[164:167], v[176:179], v[54:57]
	v_mfma_f32_16x16x32_bf16 v[50:53], v[168:171], v[176:179], v[50:53]
	v_mfma_f32_16x16x32_bf16 v[46:49], v[136:139], v[172:175], v[46:49]
	v_mfma_f32_16x16x32_bf16 v[42:45], v[160:163], v[172:175], v[42:45]
	v_mfma_f32_16x16x32_bf16 v[38:41], v[164:167], v[172:175], v[38:41]
	v_mfma_f32_16x16x32_bf16 v[34:37], v[168:171], v[172:175], v[34:37]
	v_mfma_f32_16x16x32_bf16 v[30:33], v[136:139], v[184:187], v[30:33]
	v_mfma_f32_16x16x32_bf16 v[26:29], v[160:163], v[184:187], v[26:29]
	v_mfma_f32_16x16x32_bf16 v[22:25], v[164:167], v[184:187], v[22:25]
	v_mfma_f32_16x16x32_bf16 v[18:21], v[168:171], v[184:187], v[18:21]
	v_mfma_f32_16x16x32_bf16 v[14:17], v[136:139], v[180:183], v[14:17]
	v_mfma_f32_16x16x32_bf16 v[10:13], v[160:163], v[180:183], v[10:13]
	v_mfma_f32_16x16x32_bf16 v[6:9], v[164:167], v[180:183], v[6:9]
	v_mfma_f32_16x16x32_bf16 v[2:5], v[168:171], v[180:183], v[2:5]
	v_add_u32_e32 v138, s8, v154
	s_waitcnt vmcnt(0)
	s_barrier
	v_readlane_b32 s2, v253, 30
	v_ashrrev_i32_e32 v139, 31, v138
	v_readlane_b32 s3, v253, 31
	s_and_b64 vcc, exec, s[2:3]
	v_lshl_add_u64 v[146:147], v[138:139], 2, s[66:67]
	s_cbranch_vccz .LBB0_417
	global_load_dword v136, v[146:147], off
	s_waitcnt vmcnt(0)
	v_fmamk_f32 v136, v136, 0x3a800000, v142
	v_mul_f32_e32 v137, 0x4b800000, v136
	v_cmp_gt_f32_e32 vcc, s69, v136
	s_nop 1
	v_cndmask_b32_e32 v136, v136, v137, vcc
	v_rsq_f32_e32 v136, v136
	s_nop 0
	v_mul_f32_e32 v137, 0x45800000, v136
	v_cndmask_b32_e32 v148, v136, v137, vcc
	s_branch .LBB0_418

; #define MFMA(a, b, c) __builtin_amdgcn_mfma_f32_16x16x32_bf16((a), (b), (c), 0, 0, 0)
; template <int EPI, int MF>
; __device__ __forceinline__ void gemm_part(const u16* __restrict__ A, int lda, const u16* __restrict__ Bt, int K, int ntn, GemmEpi ep, char* smem,
;                                           int mbase, int mrows) {
;     ...
;     GEMM_ISSUE(0);
;     GEMM_ISSUE(1);
;     for (int kt = 0; kt < nk; ++kt) {
;       if (kt + 1 < nk) {
;         if (MF == 8) asm volatile("s_waitcnt vmcnt(6)" ::: "memory");
;         else asm volatile("s_waitcnt vmcnt(3)" ::: "memory");
;       } else asm volatile("s_waitcnt vmcnt(0)" ::: "memory");
;       asm volatile("s_waitcnt lgkmcnt(0)" ::: "memory");
;       __builtin_amdgcn_s_barrier();
;       const u16* a_ = sbase + (kt % 3) * STG;
;       const u16* b_ = a_ + BM * 32;
;       bf16x8 bfr[4], afc[2], afn[2];
;       const u16* ap_ = a_ + (wr * (16 * MF) + fr) * 32 + fq * 8;
; #pragma unroll
;       for (int n = 0; n < 4; ++n) bfr[n] = rd_std(b_ + (wc * 64 + n * 16 + fr) * 32 + fq * 8);
;       afc[0] = rd_std(ap_); afc[1] = rd_std(ap_ + 16 * 32);
;       __builtin_amdgcn_sched_barrier(0);
;       if (kt + 2 < nk) GEMM_ISSUE(kt + 2);
;       __builtin_amdgcn_sched_barrier(0);
; #pragma unroll
;       for (int mh = 0; mh < MF / 2; ++mh) {
;         if (mh + 1 < MF / 2) {
;           afn[0] = rd_std(ap_ + ((mh + 1) * 2) * 16 * 32);
;           afn[1] = rd_std(ap_ + ((mh + 1) * 2 + 1) * 16 * 32);
;         }
;         __builtin_amdgcn_sched_barrier(0);
; #pragma unroll
;         for (int m = 0; m < 2; ++m)
; #pragma unroll
;           for (int n = 0; n < 4; ++n) acc[mh * 2 + m][n] = MFMA(bfr[n], afc[m], acc[mh * 2 + m][n]);
;         __builtin_amdgcn_sched_barrier(0);
;         afc[0] = afn[0]; afc[1] = afn[1];
;       }
.LBB0_1128:
	s_mul_hi_u32 s13, s12, 0xaaaaaaab
	s_lshr_b32 s13, s13, 1
	s_mul_i32 s13, s13, 0x12000
	v_add_u32_e32 v146, s3, v156
	v_subrev_u32_e32 v147, s13, v159
	v_subrev_u32_e32 v161, s13, v155
	v_add_u32_e32 v147, v146, v147
	v_add_u32_e32 v161, v146, v161
	s_mul_hi_u32 s13, s11, 0xaaaaaaab
	s_add_i32 s12, s12, 1
	s_lshr_b32 s13, s13, 1
	s_mul_i32 s13, s13, 0x12000
	s_sub_i32 s13, s3, s13
	s_add_i32 s14, s13, 0xc000
	v_add_u32_e32 v178, s14, v148
	v_lshl_add_u64 v[162:163], v[136:137], 0, v[134:135]
	v_readfirstlane_b32 s101, v178
	v_lshl_add_u64 v[164:165], v[162:163], 0, s[74:75]
	v_lshl_add_u64 v[166:167], v[162:163], 0, s[92:93]
	v_lshl_add_u64 v[168:169], v[162:163], 0, s[88:89]
	v_lshl_add_u64 v[162:163], v[162:163], 0, s[6:7]
	v_lshl_add_u64 v[170:171], v[138:139], 0, v[134:135]
	v_lshl_add_u64 v[172:173], v[170:171], 0, s[74:75]
	v_lshl_add_u64 v[170:171], v[170:171], 0, s[92:93]
	s_waitcnt vmcnt(6)
	s_waitcnt lgkmcnt(0)
	s_barrier
	s_mov_b32 m0, s101
	s_nop 0
	global_load_lds_dwordx4 v[164:165], off
	s_add_u32 m0, m0, 0x1000
	s_nop 0
	global_load_lds_dwordx4 v[166:167], off
	s_add_u32 m0, m0, 0x1000
	s_nop 0
	global_load_lds_dwordx4 v[168:169], off
	s_add_u32 m0, m0, 0x1000
	s_nop 0
	global_load_lds_dwordx4 v[162:163], off
	s_add_u32 m0, m0, 0x1000
	s_nop 0
	global_load_lds_dwordx4 v[172:173], off
	s_add_u32 m0, m0, 0x1000
	s_nop 0
	global_load_lds_dwordx4 v[170:171], off
	ds_read_b128 v[162:165], v147 offset:16384
	ds_read_b128 v[166:169], v147 offset:17408
	ds_read_b128 v[170:173], v147 offset:18432
	ds_read_b128 v[174:177], v147 offset:19456
	ds_read_b128 v[178:181], v161
	ds_read_b128 v[182:185], v161 offset:1024
	ds_read_b128 v[186:189], v161 offset:3072
	ds_read_b128 v[190:193], v161 offset:2048
	s_waitcnt lgkmcnt(2)
	v_mfma_f32_16x16x32_bf16 v[126:129], v[162:165], v[178:181], v[126:129]
	v_mfma_f32_16x16x32_bf16 v[122:125], v[166:169], v[178:181], v[122:125]
	v_mfma_f32_16x16x32_bf16 v[118:121], v[170:173], v[178:181], v[118:121]
	v_mfma_f32_16x16x32_bf16 v[114:117], v[174:177], v[178:181], v[114:117]
	v_mfma_f32_16x16x32_bf16 v[110:113], v[162:165], v[182:185], v[110:113]
	v_mfma_f32_16x16x32_bf16 v[106:109], v[166:169], v[182:185], v[106:109]
	v_mfma_f32_16x16x32_bf16 v[102:105], v[170:173], v[182:185], v[102:105]
	v_mfma_f32_16x16x32_bf16 v[98:101], v[174:177], v[182:185], v[98:101]
	ds_read_b128 v[178:181], v161 offset:5120
	ds_read_b128 v[182:185], v161 offset:4096
	s_waitcnt lgkmcnt(2)
	v_mfma_f32_16x16x32_bf16 v[94:97], v[162:165], v[190:193], v[94:97]
	v_mfma_f32_16x16x32_bf16 v[90:93], v[166:169], v[190:193], v[90:93]
	v_mfma_f32_16x16x32_bf16 v[86:89], v[170:173], v[190:193], v[86:89]
	v_mfma_f32_16x16x32_bf16 v[82:85], v[174:177], v[190:193], v[82:85]
	v_mfma_f32_16x16x32_bf16 v[78:81], v[162:165], v[186:189], v[78:81]
	v_mfma_f32_16x16x32_bf16 v[74:77], v[166:169], v[186:189], v[74:77]
	v_mfma_f32_16x16x32_bf16 v[70:73], v[170:173], v[186:189], v[70:73]
	v_mfma_f32_16x16x32_bf16 v[66:69], v[174:177], v[186:189], v[66:69]
	ds_read_b128 v[186:189], v161 offset:7168
	ds_read_b128 v[190:193], v161 offset:6144
	s_waitcnt lgkmcnt(2)
	v_mfma_f32_16x16x32_bf16 v[62:65], v[162:165], v[182:185], v[62:65]
	v_mfma_f32_16x16x32_bf16 v[58:61], v[166:169], v[182:185], v[58:61]
	v_mfma_f32_16x16x32_bf16 v[54:57], v[170:173], v[182:185], v[54:57]
	v_mfma_f32_16x16x32_bf16 v[50:53], v[174:177], v[182:185], v[50:53]
	v_mfma_f32_16x16x32_bf16 v[46:49], v[162:165], v[178:181], v[46:49]
	v_mfma_f32_16x16x32_bf16 v[42:45], v[166:169], v[178:181], v[42:45]
	v_mfma_f32_16x16x32_bf16 v[38:41], v[170:173], v[178:181], v[38:41]
	v_mfma_f32_16x16x32_bf16 v[34:37], v[174:177], v[178:181], v[34:37]
	s_waitcnt lgkmcnt(0)
	v_mfma_f32_16x16x32_bf16 v[30:33], v[162:165], v[190:193], v[30:33]
	v_mfma_f32_16x16x32_bf16 v[26:29], v[166:169], v[190:193], v[26:29]
	v_mfma_f32_16x16x32_bf16 v[22:25], v[170:173], v[190:193], v[22:25]
	v_mfma_f32_16x16x32_bf16 v[18:21], v[174:177], v[190:193], v[18:21]
	v_mfma_f32_16x16x32_bf16 v[14:17], v[162:165], v[186:189], v[14:17]
	v_mfma_f32_16x16x32_bf16 v[10:13], v[166:169], v[186:189], v[10:13]
	v_mfma_f32_16x16x32_bf16 v[6:9], v[170:173], v[186:189], v[6:9]
	v_mfma_f32_16x16x32_bf16 v[2:5], v[174:177], v[186:189], v[2:5]
	s_addk_i32 s3, 0x6000
	s_add_i32 s10, s10, 1
	s_add_i32 s11, s11, 1
	v_lshl_add_u64 v[136:137], v[136:137], 0, 64
	s_cmp_eq_u32 s3, 0xb4000
	v_lshl_add_u64 v[138:139], v[138:139], 0, 64
	v_lshl_add_u64 v[138:139], v[138:139], 0, 64
	s_cbranch_scc0 .LBB0_1128
	s_waitcnt vmcnt(6)
	s_waitcnt lgkmcnt(0)
	s_barrier
; #define MFMA(a, b, c) __builtin_amdgcn_mfma_f32_16x16x32_bf16((a), (b), (c), 0, 0, 0)
; template <int EPI, int MF>
; __device__ __forceinline__ void gemm_part(const u16* __restrict__ A, int lda, const u16* __restrict__ Bt, int K, int ntn, GemmEpi ep, char* smem,
;                                           int mbase, int mrows) {
;     ...
; #pragma unroll
;       for (int n = 0; n < 4; ++n) bfr[n] = rd_std(b_ + (wc * 64 + n * 16 + fr) * 32 + fq * 8);
;       afc[0] = rd_std(ap_); afc[1] = rd_std(ap_ + 16 * 32);
;       __builtin_amdgcn_sched_barrier(0);
;       if (kt + 2 < nk) GEMM_ISSUE(kt + 2);
;       __builtin_amdgcn_sched_barrier(0);
; #pragma unroll
;       for (int mh = 0; mh < MF / 2; ++mh) {
;         if (mh + 1 < MF / 2) {
;           afn[0] = rd_std(ap_ + ((mh + 1) * 2) * 16 * 32);
;           afn[1] = rd_std(ap_ + ((mh + 1) * 2 + 1) * 16 * 32);
;         }
;         __builtin_amdgcn_sched_barrier(0);
; #pragma unroll
;         for (int m = 0; m < 2; ++m)
; #pragma unroll
;           for (int n = 0; n < 4; ++n) acc[mh * 2 + m][n] = MFMA(bfr[n], afc[m], acc[mh * 2 + m][n]);
;         __builtin_amdgcn_sched_barrier(0);
;         afc[0] = afn[0]; afc[1] = afn[1];
;       }
	ds_read_b128 v[136:139], v160 offset:16384
	ds_read_b128 v[162:165], v160 offset:17408
	ds_read_b128 v[166:169], v160 offset:18432
	ds_read_b128 v[170:173], v160 offset:19456
	ds_read_b128 v[174:177], v157
	ds_read_b128 v[178:181], v157 offset:1024
	s_mul_hi_u32 s10, s10, 0xaaaaaaab
	s_lshr_b32 s10, s10, 1
	s_mul_i32 s10, s10, 0x12000
	s_sub_i32 s3, s3, s10
	s_add_i32 s3, s3, 0
	s_addk_i32 s3, 0x6000
	ds_read_b128 v[182:185], v157 offset:3072
	ds_read_b128 v[186:189], v157 offset:2048
	s_waitcnt lgkmcnt(0)
	v_mfma_f32_16x16x32_bf16 v[126:129], v[136:139], v[174:177], v[126:129]
	v_mfma_f32_16x16x32_bf16 v[122:125], v[162:165], v[174:177], v[122:125]
	v_mfma_f32_16x16x32_bf16 v[118:121], v[166:169], v[174:177], v[118:121]
	v_mfma_f32_16x16x32_bf16 v[114:117], v[170:173], v[174:177], v[114:117]
	v_mfma_f32_16x16x32_bf16 v[110:113], v[136:139], v[178:181], v[110:113]
	v_mfma_f32_16x16x32_bf16 v[106:109], v[162:165], v[178:181], v[106:109]
	v_mfma_f32_16x16x32_bf16 v[102:105], v[166:169], v[178:181], v[102:105]
	v_mfma_f32_16x16x32_bf16 v[98:101], v[170:173], v[178:181], v[98:101]
	ds_read_b128 v[174:177], v157 offset:5120
	ds_read_b128 v[178:181], v157 offset:4096
	v_mfma_f32_16x16x32_bf16 v[94:97], v[136:139], v[186:189], v[94:97]
	v_mfma_f32_16x16x32_bf16 v[90:93], v[162:165], v[186:189], v[90:93]
	v_mfma_f32_16x16x32_bf16 v[86:89], v[166:169], v[186:189], v[86:89]
	v_mfma_f32_16x16x32_bf16 v[82:85], v[170:173], v[186:189], v[82:85]
	v_mfma_f32_16x16x32_bf16 v[78:81], v[136:139], v[182:185], v[78:81]
	v_mfma_f32_16x16x32_bf16 v[74:77], v[162:165], v[182:185], v[74:77]
	v_mfma_f32_16x16x32_bf16 v[70:73], v[166:169], v[182:185], v[70:73]
	v_mfma_f32_16x16x32_bf16 v[66:69], v[170:173], v[182:185], v[66:69]
	ds_read_b128 v[182:185], v157 offset:7168
	ds_read_b128 v[186:189], v157 offset:6144
	s_waitcnt lgkmcnt(0)
	v_mfma_f32_16x16x32_bf16 v[62:65], v[136:139], v[178:181], v[62:65]
	v_mfma_f32_16x16x32_bf16 v[58:61], v[162:165], v[178:181], v[58:61]
	v_mfma_f32_16x16x32_bf16 v[54:57], v[166:169], v[178:181], v[54:57]
	v_mfma_f32_16x16x32_bf16 v[50:53], v[170:173], v[178:181], v[50:53]
	v_mfma_f32_16x16x32_bf16 v[46:49], v[136:139], v[174:177], v[46:49]
	v_mfma_f32_16x16x32_bf16 v[42:45], v[162:165], v[174:177], v[42:45]
	v_mfma_f32_16x16x32_bf16 v[38:41], v[166:169], v[174:177], v[38:41]
	v_mfma_f32_16x16x32_bf16 v[34:37], v[170:173], v[174:177], v[34:37]
	v_mfma_f32_16x16x32_bf16 v[30:33], v[136:139], v[186:189], v[30:33]
	v_mfma_f32_16x16x32_bf16 v[26:29], v[162:165], v[186:189], v[26:29]
	v_mfma_f32_16x16x32_bf16 v[22:25], v[166:169], v[186:189], v[22:25]
	v_mfma_f32_16x16x32_bf16 v[18:21], v[170:173], v[186:189], v[18:21]
	v_mfma_f32_16x16x32_bf16 v[14:17], v[136:139], v[182:185], v[14:17]
	v_mfma_f32_16x16x32_bf16 v[10:13], v[162:165], v[182:185], v[10:13]
	v_mfma_f32_16x16x32_bf16 v[6:9], v[166:169], v[182:185], v[6:9]
	v_mfma_f32_16x16x32_bf16 v[2:5], v[170:173], v[182:185], v[2:5]
	v_add_u32_e32 v146, s3, v156
	s_waitcnt vmcnt(0)
	v_add3_u32 v147, v146, v153, v154
	s_waitcnt lgkmcnt(0)
	s_barrier
	ds_read_b128 v[136:139], v147 offset:16384
	ds_read_b128 v[162:165], v147 offset:17408
	ds_read_b128 v[166:169], v147 offset:18432
	ds_read_b128 v[170:173], v147 offset:19456
	v_lshl_add_u32 v146, v149, 1, v146
	ds_read_b128 v[174:177], v146
	ds_read_b128 v[178:181], v146 offset:1024
	ds_read_b128 v[182:185], v146 offset:3072
	ds_read_b128 v[186:189], v146 offset:2048
	s_waitcnt lgkmcnt(0)
	v_mfma_f32_16x16x32_bf16 v[126:129], v[136:139], v[174:177], v[126:129]
	v_mfma_f32_16x16x32_bf16 v[122:125], v[162:165], v[174:177], v[122:125]
	v_mfma_f32_16x16x32_bf16 v[118:121], v[166:169], v[174:177], v[118:121]
	v_mfma_f32_16x16x32_bf16 v[114:117], v[170:173], v[174:177], v[114:117]
	v_mfma_f32_16x16x32_bf16 v[110:113], v[136:139], v[178:181], v[110:113]
	v_mfma_f32_16x16x32_bf16 v[106:109], v[162:165], v[178:181], v[106:109]
	v_mfma_f32_16x16x32_bf16 v[102:105], v[166:169], v[178:181], v[102:105]
	v_mfma_f32_16x16x32_bf16 v[98:101], v[170:173], v[178:181], v[98:101]
	ds_read_b128 v[174:177], v146 offset:5120
	ds_read_b128 v[178:181], v146 offset:4096
	v_mfma_f32_16x16x32_bf16 v[94:97], v[136:139], v[186:189], v[94:97]
	v_mfma_f32_16x16x32_bf16 v[90:93], v[162:165], v[186:189], v[90:93]
	v_mfma_f32_16x16x32_bf16 v[86:89], v[166:169], v[186:189], v[86:89]
	v_mfma_f32_16x16x32_bf16 v[82:85], v[170:173], v[186:189], v[82:85]
	v_mfma_f32_16x16x32_bf16 v[78:81], v[136:139], v[182:185], v[78:81]
	v_mfma_f32_16x16x32_bf16 v[74:77], v[162:165], v[182:185], v[74:77]
	v_mfma_f32_16x16x32_bf16 v[70:73], v[166:169], v[182:185], v[70:73]
	v_mfma_f32_16x16x32_bf16 v[66:69], v[170:173], v[182:185], v[66:69]
	ds_read_b128 v[182:185], v146 offset:7168
	ds_read_b128 v[186:189], v146 offset:6144
	s_waitcnt lgkmcnt(0)
	v_mfma_f32_16x16x32_bf16 v[62:65], v[136:139], v[178:181], v[62:65]
	v_mfma_f32_16x16x32_bf16 v[58:61], v[162:165], v[178:181], v[58:61]
	v_mfma_f32_16x16x32_bf16 v[54:57], v[166:169], v[178:181], v[54:57]
	v_mfma_f32_16x16x32_bf16 v[50:53], v[170:173], v[178:181], v[50:53]
	v_mfma_f32_16x16x32_bf16 v[46:49], v[136:139], v[174:177], v[46:49]
	v_mfma_f32_16x16x32_bf16 v[42:45], v[162:165], v[174:177], v[42:45]
	v_mfma_f32_16x16x32_bf16 v[38:41], v[166:169], v[174:177], v[38:41]
	v_mfma_f32_16x16x32_bf16 v[34:37], v[170:173], v[174:177], v[34:37]
	v_mfma_f32_16x16x32_bf16 v[30:33], v[136:139], v[186:189], v[30:33]
	v_mfma_f32_16x16x32_bf16 v[26:29], v[162:165], v[186:189], v[26:29]
	v_mfma_f32_16x16x32_bf16 v[22:25], v[166:169], v[186:189], v[22:25]
	v_mfma_f32_16x16x32_bf16 v[18:21], v[170:173], v[186:189], v[18:21]
	v_mfma_f32_16x16x32_bf16 v[14:17], v[136:139], v[182:185], v[14:17]
	v_mfma_f32_16x16x32_bf16 v[10:13], v[162:165], v[182:185], v[10:13]
	v_mfma_f32_16x16x32_bf16 v[6:9], v[166:169], v[182:185], v[6:9]
	v_mfma_f32_16x16x32_bf16 v[2:5], v[170:173], v[182:185], v[2:5]
	v_add_u32_e32 v136, s2, v151
	s_waitcnt vmcnt(0)
	s_barrier
; template <int EPI, int MF>
; __device__ __forceinline__ void gemm_part(const u16* __restrict__ A, int lda, const u16* __restrict__ Bt, int K, int ntn, GemmEpi ep, char* smem,
;                                           int mbase, int mrows) {
;     ...
;       } else if (EPI == EPI_RESID) {
;         const float* rp = (row < MP) ? ep.res0 + (size_t)row * DM : ep.res1 + (size_t)(row - MP) * DM;
;         float ssq = 0.f;
; #pragma unroll
;         for (int n = 0; n < 4; ++n) {
;           const int col = cb + n * 16;
;           const float4 r = *(const float4*)(rp + col);
;           float4 v;
;           v.x = r.x + ep.scale * acc[m][n][0]; v.y = r.y + ep.scale * acc[m][n][1];
;           v.z = r.z + ep.scale * acc[m][n][2]; v.w = r.w + ep.scale * acc[m][n][3];
;           *(float4*)(ep.outf + (size_t)row * DM + col) = v;
;           if (ep.xcopy) {
;             bf16x4 o;
;             o[0] = (short)f2bf(v.x); o[1] = (short)f2bf(v.y); o[2] = (short)f2bf(v.z); o[3] = (short)f2bf(v.w);
;             *(bf16x4*)(ep.xcopy + (size_t)row * DM + col) = o;
;           }
;           ssq += v.x * v.x + v.y * v.y + v.z * v.z + v.w * v.w;
;         }
;         if (ep.rss_out) {
;           ssq += __shfl_xor(ssq, 16);
;           ssq += __shfl_xor(ssq, 32);
;           if (fq == 0) atomicAdd(ep.rss_out + row, ssq);
;         }
	s_mov_b32 s2, 0xffff
	v_cmp_lt_i32_e64 s[12:13], s2, v136
	s_and_saveexec_b64 s[2:3], s[12:13]
	s_xor_b64 s[2:3], exec, s[2:3]
	v_add_u32_e32 v138, 0xffff0000, v136
	v_mov_b32_e32 v139, v0
	v_lshlrev_b64 v[138:139], 12, v[138:139]
	v_lshl_add_u64 v[146:147], s[72:73], 0, v[138:139]
	v_mov_b32_e32 v137, v0
	s_andn2_saveexec_b64 s[2:3], s[2:3]
	v_ashrrev_i32_e32 v137, 31, v136
	v_lshlrev_b64 v[138:139], 12, v[136:137]
	v_lshl_add_u64 v[146:147], s[26:27], 0, v[138:139]
	s_or_b64 exec, exec, s[2:3]
	v_lshlrev_b64 v[138:139], 12, v[136:137]
	v_or_b32_e32 v161, s9, v152
	v_lshl_add_u64 v[162:163], s[26:27], 0, v[138:139]
	v_lshlrev_b64 v[138:139], 11, v[136:137]
	v_lshl_add_u64 v[166:167], s[28:29], 0, v[138:139]
	v_lshlrev_b32_e32 v138, 2, v161
	v_mov_b32_e32 v139, v0
	v_lshl_add_u64 v[146:147], v[146:147], 0, v[138:139]
	v_lshl_add_u64 v[168:169], v[162:163], 0, v[138:139]
	global_load_dwordx4 v[162:165], v[146:147], off
	global_load_dwordx4 v[172:175], v[146:147], off offset:64
	global_load_dwordx4 v[176:179], v[146:147], off offset:128
	global_load_dwordx4 v[180:183], v[146:147], off offset:192
	s_waitcnt vmcnt(0)
	v_pk_add_f32 v[162:163], v[126:127], v[162:163]
	v_pk_add_f32 v[164:165], v[128:129], v[164:165]
	v_lshlrev_b32_e32 v126, 1, v161
	v_mov_b32_e32 v127, v0
	v_cvt_pk_bf16_f32 v129, v164, v165
	v_cvt_pk_bf16_f32 v128, v162, v163
	v_lshl_add_u64 v[166:167], v[166:167], 0, v[126:127]
	global_store_dwordx4 v[168:169], v[162:165], off
	v_lshlrev_b32_e32 v184, 1, v166
	v_bfi_b32 v184, s100, v184, v166
	v_lshrrev_b32_e32 v185, 5, v166
	v_bfi_b32 v184, 64, v185, v184
	v_mov_b32_e32 v185, v167
	global_store_dwordx2 v[184:185], v[128:129], off
	v_pk_mul_f32 v[128:129], v[162:163], v[162:163]
	v_pk_mul_f32 v[170:171], v[164:165], v[164:165]
	s_nop 0
	s_nop 0
	v_pk_add_f32 v[122:123], v[122:123], v[172:173]
	v_pk_add_f32 v[124:125], v[124:125], v[174:175]
	v_cvt_pk_bf16_f32 v162, v122, v123
	v_cvt_pk_bf16_f32 v163, v124, v125
	global_store_dwordx4 v[168:169], v[122:125], off offset:64
	v_lshlrev_b32_e32 v184, 1, v166
	v_bfi_b32 v184, s100, v184, v166
	v_lshrrev_b32_e32 v185, 5, v166
	v_bfi_b32 v184, 64, v185, v184
	v_mov_b32_e32 v185, v167
	global_store_dwordx2 v[184:185], v[162:163], off offset:32
	v_pk_mul_f32 v[162:163], v[122:123], v[122:123]
	v_pk_mul_f32 v[164:165], v[124:125], v[124:125]
	s_nop 0
	s_nop 0
	v_pk_add_f32 v[118:119], v[118:119], v[176:177]
	v_pk_add_f32 v[120:121], v[120:121], v[178:179]
	v_cvt_pk_bf16_f32 v122, v118, v119
	v_cvt_pk_bf16_f32 v123, v120, v121
	global_store_dwordx4 v[168:169], v[118:121], off offset:128
	v_lshlrev_b32_e32 v184, 1, v166
	v_bfi_b32 v184, s100, v184, v166
	v_lshrrev_b32_e32 v185, 5, v166
	v_bfi_b32 v184, 64, v185, v184
	v_mov_b32_e32 v185, v167
	global_store_dwordx2 v[184:185], v[122:123], off offset:128
	v_pk_mul_f32 v[122:123], v[118:119], v[118:119]
	v_pk_mul_f32 v[124:125], v[120:121], v[120:121]
	s_nop 0
	s_nop 0
	v_pk_add_f32 v[114:115], v[114:115], v[180:181]
	v_pk_add_f32 v[116:117], v[116:117], v[182:183]
	v_cvt_pk_bf16_f32 v118, v114, v115
	v_cvt_pk_bf16_f32 v119, v116, v117
	global_store_dwordx4 v[168:169], v[114:117], off offset:192
	v_lshlrev_b32_e32 v184, 1, v166
	v_bfi_b32 v184, s100, v184, v166
	v_lshrrev_b32_e32 v185, 5, v166
	v_bfi_b32 v184, 64, v185, v184
	v_mov_b32_e32 v185, v167
	global_store_dwordx2 v[184:185], v[118:119], off offset:160
	v_add_f32_e32 v118, v128, v129
	v_add_f32_e32 v119, v162, v163
	v_pk_mul_f32 v[114:115], v[114:115], v[114:115]
	v_add_f32_e32 v118, v170, v118
	v_add_f32_e32 v119, v164, v119
	v_pk_mul_f32 v[116:117], v[116:117], v[116:117]
	v_add_f32_e32 v118, v171, v118
	v_add_f32_e32 v119, v165, v119
	v_add_f32_e32 v114, v114, v115
	v_add_f32_e32 v118, v118, v119
	v_add_f32_e32 v119, v122, v123
	v_add_f32_e32 v114, v116, v114
	v_and_b32_e32 v116, 64, v141
	v_add_f32_e32 v119, v124, v119
	v_xor_b32_e32 v115, 16, v141
	v_add_u32_e32 v116, 64, v116
	v_add_f32_e32 v119, v125, v119
	v_cmp_lt_i32_e64 s[12:13], v115, v116
	v_add_f32_e32 v118, v118, v119
	v_add_f32_e32 v114, v117, v114
	v_cndmask_b32_e64 v115, v141, v115, s[12:13]
	v_add_f32_e32 v114, v118, v114
	v_lshlrev_b32_e32 v118, 2, v115
	ds_bpermute_b32 v115, v118, v114
	s_waitcnt lgkmcnt(0)
	v_add_f32_e32 v114, v114, v115
	v_xor_b32_e32 v115, 32, v141
	v_cmp_lt_i32_e64 s[12:13], v115, v116
	s_nop 1
	v_cndmask_b32_e64 v115, v141, v115, s[12:13]
	v_lshlrev_b32_e32 v119, 2, v115
	ds_bpermute_b32 v115, v119, v114
	s_and_saveexec_b64 s[2:3], vcc
	s_cbranch_execz .LBB0_1135
	v_readlane_b32 s10, v252, 9
	v_readlane_b32 s11, v252, 10
	s_waitcnt lgkmcnt(0)
	v_add_f32_e32 v114, v114, v115
	v_lshl_add_u64 v[116:117], v[136:137], 2, s[10:11]
	global_atomic_add_f32 v[116:117], v114, off

; #define MFMA(a, b, c) __builtin_amdgcn_mfma_f32_16x16x32_bf16((a), (b), (c), 0, 0, 0)
; template <int EPI, int MF>
; __device__ __forceinline__ void gemm_part(const u16* __restrict__ A, int lda, const u16* __restrict__ Bt, int K, int ntn, GemmEpi ep, char* smem,
;                                           int mbase, int mrows) {
;     ...
;     GEMM_ISSUE(0);
;     GEMM_ISSUE(1);
;     for (int kt = 0; kt < nk; ++kt) {
;       if (kt + 1 < nk) {
;         if (MF == 8) asm volatile("s_waitcnt vmcnt(6)" ::: "memory");
;         else asm volatile("s_waitcnt vmcnt(3)" ::: "memory");
;       } else asm volatile("s_waitcnt vmcnt(0)" ::: "memory");
;       asm volatile("s_waitcnt lgkmcnt(0)" ::: "memory");
;       __builtin_amdgcn_s_barrier();
;       const u16* a_ = sbase + (kt % 3) * STG;
;       const u16* b_ = a_ + BM * 32;
;       bf16x8 bfr[4], afc[2], afn[2];
;       const u16* ap_ = a_ + (wr * (16 * MF) + fr) * 32 + fq * 8;
; #pragma unroll
;       for (int n = 0; n < 4; ++n) bfr[n] = rd_std(b_ + (wc * 64 + n * 16 + fr) * 32 + fq * 8);
;       afc[0] = rd_std(ap_); afc[1] = rd_std(ap_ + 16 * 32);
;       __builtin_amdgcn_sched_barrier(0);
;       if (kt + 2 < nk) GEMM_ISSUE(kt + 2);
;       __builtin_amdgcn_sched_barrier(0);
; #pragma unroll
;       for (int mh = 0; mh < MF / 2; ++mh) {
;         if (mh + 1 < MF / 2) {
;           afn[0] = rd_std(ap_ + ((mh + 1) * 2) * 16 * 32);
;           afn[1] = rd_std(ap_ + ((mh + 1) * 2 + 1) * 16 * 32);
;         }
;         __builtin_amdgcn_sched_barrier(0);
; #pragma unroll
;         for (int m = 0; m < 2; ++m)
; #pragma unroll
;           for (int n = 0; n < 4; ++n) acc[mh * 2 + m][n] = MFMA(bfr[n], afc[m], acc[mh * 2 + m][n]);
;         __builtin_amdgcn_sched_barrier(0);
;         afc[0] = afn[0]; afc[1] = afn[1];
;       }
.LBB0_1202:
	s_mul_i32 s12, s5, 0xab
	s_add_i32 s13, s12, 0xfeaa
	s_bfe_u32 s13, s13, 0x70009
	s_mul_i32 s13, s13, 3
	s_sub_i32 s13, s5, s13
	s_add_i32 s13, s13, 0xfffe
	s_and_b32 s13, s13, 0xff
	s_mulk_i32 s13, 0x6000
	v_add_u32_e32 v192, s13, v212
	v_add_u32_e32 v175, s13, v210
	s_bfe_u32 s12, s12, 0x70009
	s_mul_i32 s12, s12, 3
	s_sub_i32 s12, s5, s12
	s_and_b32 s12, s12, 0xff
	s_mulk_i32 s12, 0x6000
	v_add_u32_e32 v234, s12, v194
	v_lshl_add_u64 v[180:181], s[2:3], 1, v[178:179]
	v_readfirstlane_b32 s101, v234
	v_lshl_add_u64 v[182:183], v[180:181], 0, s[74:75]
	v_lshl_add_u64 v[184:185], v[180:181], 0, s[92:93]
	v_lshl_add_u64 v[186:187], v[180:181], 0, s[88:89]
	v_lshl_add_u64 v[180:181], v[180:181], 0, s[6:7]
	v_lshl_add_u64 v[188:189], s[2:3], 1, v[176:177]
	v_lshl_add_u64 v[190:191], v[188:189], 0, s[74:75]
	v_lshl_add_u64 v[188:189], v[188:189], 0, s[92:93]
	s_waitcnt vmcnt(6)
	s_waitcnt lgkmcnt(0)
	s_barrier
	s_mov_b32 m0, s101
	s_nop 0
	global_load_lds_dwordx4 v[182:183], off
	s_add_u32 m0, m0, 0x1000
	s_nop 0
	global_load_lds_dwordx4 v[184:185], off
	s_add_u32 m0, m0, 0x1000
	s_nop 0
	global_load_lds_dwordx4 v[186:187], off
	s_add_u32 m0, m0, 0x1000
	s_nop 0
	global_load_lds_dwordx4 v[180:181], off
	s_add_u32 m0, m0, 0x1000
	s_nop 0
	global_load_lds_dwordx4 v[190:191], off
	s_add_u32 m0, m0, 0x1000
	s_nop 0
	global_load_lds_dwordx4 v[188:189], off
	ds_read_b128 v[180:183], v192 offset:16384
	ds_read_b128 v[184:187], v192 offset:17408
	ds_read_b128 v[188:191], v192 offset:18432
	ds_read_b128 v[230:233], v192 offset:19456
	ds_read_b128 v[234:237], v175
	ds_read_b128 v[238:241], v175 offset:1024
	ds_read_b128 v[242:245], v175 offset:3072
	ds_read_b128 v[246:249], v175 offset:2048
	s_waitcnt lgkmcnt(2)
	v_mfma_f32_16x16x32_bf16 v[126:129], v[180:183], v[234:237], v[126:129]
	v_mfma_f32_16x16x32_bf16 v[122:125], v[184:187], v[234:237], v[122:125]
	v_mfma_f32_16x16x32_bf16 v[118:121], v[188:191], v[234:237], v[118:121]
	v_mfma_f32_16x16x32_bf16 v[114:117], v[230:233], v[234:237], v[114:117]
	v_mfma_f32_16x16x32_bf16 v[110:113], v[180:183], v[238:241], v[110:113]
	v_mfma_f32_16x16x32_bf16 v[106:109], v[184:187], v[238:241], v[106:109]
	v_mfma_f32_16x16x32_bf16 v[102:105], v[188:191], v[238:241], v[102:105]
	v_mfma_f32_16x16x32_bf16 v[98:101], v[230:233], v[238:241], v[98:101]
	ds_read_b128 v[234:237], v175 offset:5120
	ds_read_b128 v[238:241], v175 offset:4096
	s_waitcnt lgkmcnt(2)
	v_mfma_f32_16x16x32_bf16 v[94:97], v[180:183], v[246:249], v[94:97]
	v_mfma_f32_16x16x32_bf16 v[90:93], v[184:187], v[246:249], v[90:93]
	v_mfma_f32_16x16x32_bf16 v[86:89], v[188:191], v[246:249], v[86:89]
	v_mfma_f32_16x16x32_bf16 v[82:85], v[230:233], v[246:249], v[82:85]
	v_mfma_f32_16x16x32_bf16 v[78:81], v[180:183], v[242:245], v[78:81]
	v_mfma_f32_16x16x32_bf16 v[74:77], v[184:187], v[242:245], v[74:77]
	v_mfma_f32_16x16x32_bf16 v[70:73], v[188:191], v[242:245], v[70:73]
	v_mfma_f32_16x16x32_bf16 v[66:69], v[230:233], v[242:245], v[66:69]
	ds_read_b128 v[242:245], v175 offset:7168
	ds_read_b128 v[246:249], v175 offset:6144
	s_waitcnt lgkmcnt(2)
	v_mfma_f32_16x16x32_bf16 v[62:65], v[180:183], v[238:241], v[62:65]
	v_mfma_f32_16x16x32_bf16 v[58:61], v[184:187], v[238:241], v[58:61]
	v_mfma_f32_16x16x32_bf16 v[54:57], v[188:191], v[238:241], v[54:57]
	v_mfma_f32_16x16x32_bf16 v[50:53], v[230:233], v[238:241], v[50:53]
	v_mfma_f32_16x16x32_bf16 v[46:49], v[180:183], v[234:237], v[46:49]
	v_mfma_f32_16x16x32_bf16 v[42:45], v[184:187], v[234:237], v[42:45]
	v_mfma_f32_16x16x32_bf16 v[38:41], v[188:191], v[234:237], v[38:41]
	v_mfma_f32_16x16x32_bf16 v[34:37], v[230:233], v[234:237], v[34:37]
	s_waitcnt lgkmcnt(0)
	v_mfma_f32_16x16x32_bf16 v[30:33], v[180:183], v[246:249], v[30:33]
	v_mfma_f32_16x16x32_bf16 v[26:29], v[184:187], v[246:249], v[26:29]
	v_mfma_f32_16x16x32_bf16 v[22:25], v[188:191], v[246:249], v[22:25]
	v_mfma_f32_16x16x32_bf16 v[18:21], v[230:233], v[246:249], v[18:21]
	v_mfma_f32_16x16x32_bf16 v[14:17], v[180:183], v[242:245], v[14:17]
	v_mfma_f32_16x16x32_bf16 v[10:13], v[184:187], v[242:245], v[10:13]
	v_mfma_f32_16x16x32_bf16 v[6:9], v[188:191], v[242:245], v[6:9]
	v_mfma_f32_16x16x32_bf16 v[2:5], v[230:233], v[242:245], v[2:5]
	s_add_u32 s2, s2, 64
	s_addc_u32 s3, s3, 0
	s_add_i32 s5, s5, 1
	s_cmpk_eq_i32 s2, 0x780
	s_cbranch_scc0 .LBB0_1202
	s_waitcnt vmcnt(6)
	s_waitcnt lgkmcnt(0)
	s_barrier
; #define MFMA(a, b, c) __builtin_amdgcn_mfma_f32_16x16x32_bf16((a), (b), (c), 0, 0, 0)
; template <int EPI, int MF>
; __device__ __forceinline__ void gemm_part(const u16* __restrict__ A, int lda, const u16* __restrict__ Bt, int K, int ntn, GemmEpi ep, char* smem,
;                                           int mbase, int mrows) {
;     ...
; #pragma unroll
;       for (int n = 0; n < 4; ++n) bfr[n] = rd_std(b_ + (wc * 64 + n * 16 + fr) * 32 + fq * 8);
;       afc[0] = rd_std(ap_); afc[1] = rd_std(ap_ + 16 * 32);
;       __builtin_amdgcn_sched_barrier(0);
;       if (kt + 2 < nk) GEMM_ISSUE(kt + 2);
;       __builtin_amdgcn_sched_barrier(0);
; #pragma unroll
;       for (int mh = 0; mh < MF / 2; ++mh) {
;         if (mh + 1 < MF / 2) {
;           afn[0] = rd_std(ap_ + ((mh + 1) * 2) * 16 * 32);
;           afn[1] = rd_std(ap_ + ((mh + 1) * 2 + 1) * 16 * 32);
;         }
;         __builtin_amdgcn_sched_barrier(0);
; #pragma unroll
;         for (int m = 0; m < 2; ++m)
; #pragma unroll
;           for (int n = 0; n < 4; ++n) acc[mh * 2 + m][n] = MFMA(bfr[n], afc[m], acc[mh * 2 + m][n]);
;         __builtin_amdgcn_sched_barrier(0);
;         afc[0] = afn[0]; afc[1] = afn[1];
;       }
;     }
;     ...
;     __syncthreads();
; #pragma unroll
;     for (int m = 0; m < MF; ++m) {
;       if (EPI == EPI_SWIGLU || (m & 1) == 0) __builtin_amdgcn_sched_barrier(0);
;       const int row = row0 + wr * (16 * MF) + m * 16 + fr;
;       const int cb = col0 + wc * 64 + 4 * fq;
;       float rstd = 1.f;
;       if (EPI != EPI_RESID) { if (ep.rss_in) rstd = rsqrtf(ep.rss_in[row] * (1.f / DM) + 1e-6f); }
	ds_read_b128 v[176:179], v212 offset:16384
	ds_read_b128 v[180:183], v212 offset:17408
	ds_read_b128 v[184:187], v212 offset:18432
	ds_read_b128 v[188:191], v212 offset:19456
	ds_read_b128 v[230:233], v210
	ds_read_b128 v[234:237], v210 offset:1024
	ds_read_b128 v[238:241], v210 offset:3072
	ds_read_b128 v[242:245], v210 offset:2048
	s_waitcnt lgkmcnt(0)
	v_mfma_f32_16x16x32_bf16 v[126:129], v[176:179], v[230:233], v[126:129]
	v_mfma_f32_16x16x32_bf16 v[122:125], v[180:183], v[230:233], v[122:125]
	v_mfma_f32_16x16x32_bf16 v[118:121], v[184:187], v[230:233], v[118:121]
	v_mfma_f32_16x16x32_bf16 v[114:117], v[188:191], v[230:233], v[114:117]
	v_mfma_f32_16x16x32_bf16 v[110:113], v[176:179], v[234:237], v[110:113]
	v_mfma_f32_16x16x32_bf16 v[106:109], v[180:183], v[234:237], v[106:109]
	v_mfma_f32_16x16x32_bf16 v[102:105], v[184:187], v[234:237], v[102:105]
	v_mfma_f32_16x16x32_bf16 v[98:101], v[188:191], v[234:237], v[98:101]
	ds_read_b128 v[230:233], v210 offset:5120
	ds_read_b128 v[234:237], v210 offset:4096
	v_mfma_f32_16x16x32_bf16 v[94:97], v[176:179], v[242:245], v[94:97]
	v_mfma_f32_16x16x32_bf16 v[90:93], v[180:183], v[242:245], v[90:93]
	v_mfma_f32_16x16x32_bf16 v[86:89], v[184:187], v[242:245], v[86:89]
	v_mfma_f32_16x16x32_bf16 v[82:85], v[188:191], v[242:245], v[82:85]
	v_mfma_f32_16x16x32_bf16 v[78:81], v[176:179], v[238:241], v[78:81]
	v_mfma_f32_16x16x32_bf16 v[74:77], v[180:183], v[238:241], v[74:77]
	v_mfma_f32_16x16x32_bf16 v[70:73], v[184:187], v[238:241], v[70:73]
	v_mfma_f32_16x16x32_bf16 v[66:69], v[188:191], v[238:241], v[66:69]
	ds_read_b128 v[238:241], v210 offset:7168
	ds_read_b128 v[242:245], v210 offset:6144
	s_waitcnt lgkmcnt(0)
	v_mfma_f32_16x16x32_bf16 v[62:65], v[176:179], v[234:237], v[62:65]
	v_mfma_f32_16x16x32_bf16 v[58:61], v[180:183], v[234:237], v[58:61]
	v_mfma_f32_16x16x32_bf16 v[54:57], v[184:187], v[234:237], v[54:57]
	v_mfma_f32_16x16x32_bf16 v[50:53], v[188:191], v[234:237], v[50:53]
	v_mfma_f32_16x16x32_bf16 v[46:49], v[176:179], v[230:233], v[46:49]
	v_mfma_f32_16x16x32_bf16 v[42:45], v[180:183], v[230:233], v[42:45]
	v_mfma_f32_16x16x32_bf16 v[38:41], v[184:187], v[230:233], v[38:41]
	v_mfma_f32_16x16x32_bf16 v[34:37], v[188:191], v[230:233], v[34:37]
	v_mfma_f32_16x16x32_bf16 v[30:33], v[176:179], v[242:245], v[30:33]
	v_mfma_f32_16x16x32_bf16 v[26:29], v[180:183], v[242:245], v[26:29]
	v_mfma_f32_16x16x32_bf16 v[22:25], v[184:187], v[242:245], v[22:25]
	v_mfma_f32_16x16x32_bf16 v[18:21], v[188:191], v[242:245], v[18:21]
	v_mfma_f32_16x16x32_bf16 v[14:17], v[176:179], v[238:241], v[14:17]
	v_mfma_f32_16x16x32_bf16 v[10:13], v[180:183], v[238:241], v[10:13]
	v_mfma_f32_16x16x32_bf16 v[6:9], v[184:187], v[238:241], v[6:9]
	v_mfma_f32_16x16x32_bf16 v[2:5], v[188:191], v[238:241], v[2:5]
	s_waitcnt vmcnt(0)
	s_waitcnt lgkmcnt(0)
	s_barrier
	ds_read_b128 v[176:179], v212 offset:40960
	ds_read_b128 v[180:183], v212 offset:41984
	ds_read_b128 v[184:187], v212 offset:43008
	ds_read_b128 v[188:191], v212 offset:44032
	ds_read_b128 v[230:233], v210 offset:24576
	ds_read_b128 v[234:237], v210 offset:25600
	ds_read_b128 v[238:241], v210 offset:27648
	ds_read_b128 v[242:245], v210 offset:26624
	s_waitcnt lgkmcnt(0)
	v_mfma_f32_16x16x32_bf16 v[126:129], v[176:179], v[230:233], v[126:129]
	v_mfma_f32_16x16x32_bf16 v[122:125], v[180:183], v[230:233], v[122:125]
	v_mfma_f32_16x16x32_bf16 v[118:121], v[184:187], v[230:233], v[118:121]
	v_mfma_f32_16x16x32_bf16 v[114:117], v[188:191], v[230:233], v[114:117]
	v_mfma_f32_16x16x32_bf16 v[110:113], v[176:179], v[234:237], v[110:113]
	v_mfma_f32_16x16x32_bf16 v[106:109], v[180:183], v[234:237], v[106:109]
	v_mfma_f32_16x16x32_bf16 v[102:105], v[184:187], v[234:237], v[102:105]
	v_mfma_f32_16x16x32_bf16 v[98:101], v[188:191], v[234:237], v[98:101]
	ds_read_b128 v[230:233], v210 offset:29696
	ds_read_b128 v[234:237], v210 offset:28672
	v_mfma_f32_16x16x32_bf16 v[94:97], v[176:179], v[242:245], v[94:97]
	v_mfma_f32_16x16x32_bf16 v[90:93], v[180:183], v[242:245], v[90:93]
	v_mfma_f32_16x16x32_bf16 v[86:89], v[184:187], v[242:245], v[86:89]
	v_mfma_f32_16x16x32_bf16 v[82:85], v[188:191], v[242:245], v[82:85]
	v_mfma_f32_16x16x32_bf16 v[78:81], v[176:179], v[238:241], v[78:81]
	v_mfma_f32_16x16x32_bf16 v[74:77], v[180:183], v[238:241], v[74:77]
	v_mfma_f32_16x16x32_bf16 v[70:73], v[184:187], v[238:241], v[70:73]
	v_mfma_f32_16x16x32_bf16 v[66:69], v[188:191], v[238:241], v[66:69]
	ds_read_b128 v[238:241], v210 offset:31744
	ds_read_b128 v[242:245], v210 offset:30720
	s_waitcnt lgkmcnt(0)
	v_mfma_f32_16x16x32_bf16 v[62:65], v[176:179], v[234:237], v[62:65]
	v_mfma_f32_16x16x32_bf16 v[58:61], v[180:183], v[234:237], v[58:61]
	v_mfma_f32_16x16x32_bf16 v[54:57], v[184:187], v[234:237], v[54:57]
	v_mfma_f32_16x16x32_bf16 v[50:53], v[188:191], v[234:237], v[50:53]
	v_mfma_f32_16x16x32_bf16 v[46:49], v[176:179], v[230:233], v[46:49]
	v_mfma_f32_16x16x32_bf16 v[42:45], v[180:183], v[230:233], v[42:45]
	v_mfma_f32_16x16x32_bf16 v[38:41], v[184:187], v[230:233], v[38:41]
	v_mfma_f32_16x16x32_bf16 v[34:37], v[188:191], v[230:233], v[34:37]
	v_mfma_f32_16x16x32_bf16 v[30:33], v[176:179], v[242:245], v[30:33]
	v_mfma_f32_16x16x32_bf16 v[26:29], v[180:183], v[242:245], v[26:29]
	v_mfma_f32_16x16x32_bf16 v[22:25], v[184:187], v[242:245], v[22:25]
	v_mfma_f32_16x16x32_bf16 v[18:21], v[188:191], v[242:245], v[18:21]
	v_mfma_f32_16x16x32_bf16 v[14:17], v[176:179], v[238:241], v[14:17]
	v_mfma_f32_16x16x32_bf16 v[10:13], v[180:183], v[238:241], v[10:13]
	v_mfma_f32_16x16x32_bf16 v[6:9], v[184:187], v[238:241], v[6:9]
	v_mfma_f32_16x16x32_bf16 v[2:5], v[188:191], v[238:241], v[2:5]
	v_add_u32_e32 v178, s9, v197
	s_waitcnt vmcnt(0)
	s_barrier
	v_readlane_b32 s2, v253, 30
	v_ashrrev_i32_e32 v179, 31, v178
	v_readlane_b32 s3, v253, 31
	s_and_b64 vcc, exec, s[2:3]
	v_lshl_add_u64 v[180:181], v[178:179], 2, s[66:67]
	s_cbranch_vccz .LBB0_1205
	global_load_dword v175, v[180:181], off
	s_waitcnt vmcnt(0)
	v_fmamk_f32 v175, v175, 0x3a800000, v142
	v_mul_f32_e32 v176, 0x4b800000, v175
	v_cmp_gt_f32_e32 vcc, s69, v175
	s_nop 1
	v_cndmask_b32_e32 v175, v175, v176, vcc
	v_rsq_f32_e32 v175, v175
	s_nop 0
	v_mul_f32_e32 v176, 0x45800000, v175
	v_cndmask_b32_e32 v182, v175, v176, vcc
	s_branch .LBB0_1206

; #define MFMA(a, b, c) __builtin_amdgcn_mfma_f32_16x16x32_bf16((a), (b), (c), 0, 0, 0)
; template <int EPI, int MF>
; __device__ __forceinline__ void gemm_part(const u16* __restrict__ A, int lda, const u16* __restrict__ Bt, int K, int ntn, GemmEpi ep, char* smem,
;                                           int mbase, int mrows) {
;     ...
;     GEMM_ISSUE(0);
;     GEMM_ISSUE(1);
;     for (int kt = 0; kt < nk; ++kt) {
;       if (kt + 1 < nk) {
;         if (MF == 8) asm volatile("s_waitcnt vmcnt(6)" ::: "memory");
;         else asm volatile("s_waitcnt vmcnt(3)" ::: "memory");
;       } else asm volatile("s_waitcnt vmcnt(0)" ::: "memory");
;       asm volatile("s_waitcnt lgkmcnt(0)" ::: "memory");
;       __builtin_amdgcn_s_barrier();
;       const u16* a_ = sbase + (kt % 3) * STG;
;       const u16* b_ = a_ + BM * 32;
;       bf16x8 bfr[4], afc[2], afn[2];
;       const u16* ap_ = a_ + (wr * (16 * MF) + fr) * 32 + fq * 8;
; #pragma unroll
;       for (int n = 0; n < 4; ++n) bfr[n] = rd_std(b_ + (wc * 64 + n * 16 + fr) * 32 + fq * 8);
;       afc[0] = rd_std(ap_); afc[1] = rd_std(ap_ + 16 * 32);
;       __builtin_amdgcn_sched_barrier(0);
;       if (kt + 2 < nk) GEMM_ISSUE(kt + 2);
;       __builtin_amdgcn_sched_barrier(0);
; #pragma unroll
;       for (int mh = 0; mh < MF / 2; ++mh) {
;         if (mh + 1 < MF / 2) {
;           afn[0] = rd_std(ap_ + ((mh + 1) * 2) * 16 * 32);
;           afn[1] = rd_std(ap_ + ((mh + 1) * 2 + 1) * 16 * 32);
;         }
;         __builtin_amdgcn_sched_barrier(0);
; #pragma unroll
;         for (int m = 0; m < 2; ++m)
; #pragma unroll
;           for (int n = 0; n < 4; ++n) acc[mh * 2 + m][n] = MFMA(bfr[n], afc[m], acc[mh * 2 + m][n]);
;         __builtin_amdgcn_sched_barrier(0);
;         afc[0] = afn[0]; afc[1] = afn[1];
;       }
.LBB0_1947:
	s_mul_i32 s12, s9, 0xab
	s_add_i32 s13, s12, 0xfeaa
	s_bfe_u32 s13, s13, 0x70009
	s_mul_i32 s13, s13, 3
	s_sub_i32 s13, s9, s13
	s_add_i32 s13, s13, 0xfffe
	s_and_b32 s13, s13, 0xff
	s_mulk_i32 s13, 0x6000
	v_add_u32_e32 v168, s13, v155
	v_add_u32_e32 v188, s13, v154
	s_bfe_u32 s12, s12, 0x70009
	s_mul_i32 s12, s12, 3
	s_sub_i32 s12, s9, s12
	s_and_b32 s12, s12, 0xff
	s_mulk_i32 s12, 0x6000
	v_add_u32_e32 v172, s12, v150
	v_lshl_add_u64 v[156:157], s[2:3], 1, v[148:149]
	v_readfirstlane_b32 s101, v172
	v_lshl_add_u64 v[158:159], v[156:157], 0, s[30:31]
	s_mov_b64 s[12:13], 0x162e0080
	v_lshl_add_u64 v[160:161], v[156:157], 0, s[12:13]
	s_mov_b64 s[12:13], 0x16300080
	v_lshl_add_u64 v[162:163], v[156:157], 0, s[12:13]
	s_mov_b64 s[12:13], 0x16320080
	v_lshl_add_u64 v[156:157], v[156:157], 0, s[12:13]
	v_lshl_add_u64 v[164:165], s[2:3], 1, v[146:147]
	v_lshl_add_u64 v[166:167], v[164:165], 0, s[74:75]
	v_lshl_add_u64 v[164:165], v[164:165], 0, s[92:93]
	s_waitcnt vmcnt(6)
	s_waitcnt lgkmcnt(0)
	s_barrier
	s_mov_b32 m0, s101
	s_nop 0
	global_load_lds_dwordx4 v[158:159], off
	s_add_u32 m0, m0, 0x1000
	s_nop 0
	global_load_lds_dwordx4 v[160:161], off
	s_add_u32 m0, m0, 0x1000
	s_nop 0
	global_load_lds_dwordx4 v[162:163], off
	s_add_u32 m0, m0, 0x1000
	s_nop 0
	global_load_lds_dwordx4 v[156:157], off
	s_add_u32 m0, m0, 0x1000
	s_nop 0
	global_load_lds_dwordx4 v[166:167], off
	s_add_u32 m0, m0, 0x1000
	s_nop 0
	global_load_lds_dwordx4 v[164:165], off
	ds_read_b128 v[156:159], v168 offset:16384
	ds_read_b128 v[160:163], v168 offset:17408
	ds_read_b128 v[164:167], v168 offset:18432
	ds_read_b128 v[168:171], v168 offset:19456
	ds_read_b128 v[172:175], v188
	ds_read_b128 v[176:179], v188 offset:1024
	ds_read_b128 v[180:183], v188 offset:2048
	ds_read_b128 v[184:187], v188 offset:3072
	s_waitcnt lgkmcnt(2)
	v_mfma_f32_16x16x32_bf16 v[126:129], v[156:159], v[172:175], v[126:129]
	v_mfma_f32_16x16x32_bf16 v[122:125], v[160:163], v[172:175], v[122:125]
	v_mfma_f32_16x16x32_bf16 v[118:121], v[164:167], v[172:175], v[118:121]
	v_mfma_f32_16x16x32_bf16 v[114:117], v[168:171], v[172:175], v[114:117]
	v_mfma_f32_16x16x32_bf16 v[110:113], v[156:159], v[176:179], v[110:113]
	v_mfma_f32_16x16x32_bf16 v[106:109], v[160:163], v[176:179], v[106:109]
	v_mfma_f32_16x16x32_bf16 v[102:105], v[164:167], v[176:179], v[102:105]
	v_mfma_f32_16x16x32_bf16 v[98:101], v[168:171], v[176:179], v[98:101]
	ds_read_b128 v[172:175], v188 offset:4096
	ds_read_b128 v[176:179], v188 offset:5120
	s_waitcnt lgkmcnt(2)
	v_mfma_f32_16x16x32_bf16 v[94:97], v[156:159], v[180:183], v[94:97]
	v_mfma_f32_16x16x32_bf16 v[90:93], v[160:163], v[180:183], v[90:93]
	v_mfma_f32_16x16x32_bf16 v[86:89], v[164:167], v[180:183], v[86:89]
	v_mfma_f32_16x16x32_bf16 v[82:85], v[168:171], v[180:183], v[82:85]
	v_mfma_f32_16x16x32_bf16 v[78:81], v[156:159], v[184:187], v[78:81]
	v_mfma_f32_16x16x32_bf16 v[74:77], v[160:163], v[184:187], v[74:77]
	v_mfma_f32_16x16x32_bf16 v[70:73], v[164:167], v[184:187], v[70:73]
	v_mfma_f32_16x16x32_bf16 v[66:69], v[168:171], v[184:187], v[66:69]
	ds_read_b128 v[180:183], v188 offset:6144
	ds_read_b128 v[184:187], v188 offset:7168
	s_waitcnt lgkmcnt(2)
	v_mfma_f32_16x16x32_bf16 v[62:65], v[156:159], v[172:175], v[62:65]
	v_mfma_f32_16x16x32_bf16 v[58:61], v[160:163], v[172:175], v[58:61]
	v_mfma_f32_16x16x32_bf16 v[54:57], v[164:167], v[172:175], v[54:57]
	v_mfma_f32_16x16x32_bf16 v[50:53], v[168:171], v[172:175], v[50:53]
	v_mfma_f32_16x16x32_bf16 v[46:49], v[156:159], v[176:179], v[46:49]
	v_mfma_f32_16x16x32_bf16 v[42:45], v[160:163], v[176:179], v[42:45]
	v_mfma_f32_16x16x32_bf16 v[38:41], v[164:167], v[176:179], v[38:41]
	v_mfma_f32_16x16x32_bf16 v[34:37], v[168:171], v[176:179], v[34:37]
	s_waitcnt lgkmcnt(0)
	v_mfma_f32_16x16x32_bf16 v[30:33], v[156:159], v[180:183], v[30:33]
	v_mfma_f32_16x16x32_bf16 v[26:29], v[160:163], v[180:183], v[26:29]
	v_mfma_f32_16x16x32_bf16 v[22:25], v[164:167], v[180:183], v[22:25]
	v_mfma_f32_16x16x32_bf16 v[18:21], v[168:171], v[180:183], v[18:21]
	v_mfma_f32_16x16x32_bf16 v[14:17], v[156:159], v[184:187], v[14:17]
	v_mfma_f32_16x16x32_bf16 v[10:13], v[160:163], v[184:187], v[10:13]
	v_mfma_f32_16x16x32_bf16 v[6:9], v[164:167], v[184:187], v[6:9]
	v_mfma_f32_16x16x32_bf16 v[2:5], v[168:171], v[184:187], v[2:5]
	s_add_u32 s2, s2, 64
	s_addc_u32 s3, s3, 0
	s_add_i32 s9, s9, 1
	s_cmpk_eq_i32 s2, 0x780
	s_cbranch_scc0 .LBB0_1947
	s_waitcnt vmcnt(6)
	s_waitcnt lgkmcnt(0)
	s_barrier
; #define MFMA(a, b, c) __builtin_amdgcn_mfma_f32_16x16x32_bf16((a), (b), (c), 0, 0, 0)
; template <int EPI, int MF>
; __device__ __forceinline__ void gemm_part(const u16* __restrict__ A, int lda, const u16* __restrict__ Bt, int K, int ntn, GemmEpi ep, char* smem,
;                                           int mbase, int mrows) {
;     ...
; #pragma unroll
;       for (int n = 0; n < 4; ++n) bfr[n] = rd_std(b_ + (wc * 64 + n * 16 + fr) * 32 + fq * 8);
;       afc[0] = rd_std(ap_); afc[1] = rd_std(ap_ + 16 * 32);
;       __builtin_amdgcn_sched_barrier(0);
;       if (kt + 2 < nk) GEMM_ISSUE(kt + 2);
;       __builtin_amdgcn_sched_barrier(0);
; #pragma unroll
;       for (int mh = 0; mh < MF / 2; ++mh) {
;         if (mh + 1 < MF / 2) {
;           afn[0] = rd_std(ap_ + ((mh + 1) * 2) * 16 * 32);
;           afn[1] = rd_std(ap_ + ((mh + 1) * 2 + 1) * 16 * 32);
;         }
;         __builtin_amdgcn_sched_barrier(0);
; #pragma unroll
;         for (int m = 0; m < 2; ++m)
; #pragma unroll
;           for (int n = 0; n < 4; ++n) acc[mh * 2 + m][n] = MFMA(bfr[n], afc[m], acc[mh * 2 + m][n]);
;         __builtin_amdgcn_sched_barrier(0);
;         afc[0] = afn[0]; afc[1] = afn[1];
;       }
	ds_read_b128 v[146:149], v155 offset:16384
	ds_read_b128 v[156:159], v155 offset:17408
	ds_read_b128 v[160:163], v155 offset:18432
	ds_read_b128 v[164:167], v155 offset:19456
	ds_read_b128 v[168:171], v154
	ds_read_b128 v[172:175], v154 offset:1024
	ds_read_b128 v[176:179], v154 offset:2048
	ds_read_b128 v[180:183], v154 offset:3072
	s_waitcnt lgkmcnt(0)
	v_mfma_f32_16x16x32_bf16 v[126:129], v[146:149], v[168:171], v[126:129]
	v_mfma_f32_16x16x32_bf16 v[122:125], v[156:159], v[168:171], v[122:125]
	v_mfma_f32_16x16x32_bf16 v[184:187], v[160:163], v[168:171], v[118:121]
	v_mfma_f32_16x16x32_bf16 v[114:117], v[164:167], v[168:171], v[114:117]
	v_mfma_f32_16x16x32_bf16 v[110:113], v[146:149], v[172:175], v[110:113]
	v_mfma_f32_16x16x32_bf16 v[106:109], v[156:159], v[172:175], v[106:109]
	v_mfma_f32_16x16x32_bf16 v[168:171], v[160:163], v[172:175], v[102:105]
	v_mfma_f32_16x16x32_bf16 v[98:101], v[164:167], v[172:175], v[98:101]
	s_nop 1
	ds_read_b128 v[102:105], v154 offset:4096
	ds_read_b128 v[118:121], v154 offset:5120
	v_mfma_f32_16x16x32_bf16 v[94:97], v[146:149], v[176:179], v[94:97]
	v_mfma_f32_16x16x32_bf16 v[90:93], v[156:159], v[176:179], v[90:93]
	v_mfma_f32_16x16x32_bf16 v[172:175], v[160:163], v[176:179], v[86:89]
	v_mfma_f32_16x16x32_bf16 v[82:85], v[164:167], v[176:179], v[82:85]
	v_mfma_f32_16x16x32_bf16 v[78:81], v[146:149], v[180:183], v[78:81]
	v_mfma_f32_16x16x32_bf16 v[74:77], v[156:159], v[180:183], v[74:77]
	v_mfma_f32_16x16x32_bf16 v[176:179], v[160:163], v[180:183], v[70:73]
	v_mfma_f32_16x16x32_bf16 v[66:69], v[164:167], v[180:183], v[66:69]
	s_nop 1
	ds_read_b128 v[70:73], v154 offset:6144
	ds_read_b128 v[86:89], v154 offset:7168
	s_waitcnt lgkmcnt(0)
	v_mfma_f32_16x16x32_bf16 v[62:65], v[146:149], v[102:105], v[62:65]
	v_mfma_f32_16x16x32_bf16 v[58:61], v[156:159], v[102:105], v[58:61]
	v_mfma_f32_16x16x32_bf16 v[180:183], v[160:163], v[102:105], v[54:57]
	v_mfma_f32_16x16x32_bf16 v[50:53], v[164:167], v[102:105], v[50:53]
	v_mfma_f32_16x16x32_bf16 v[46:49], v[146:149], v[118:121], v[46:49]
	v_mfma_f32_16x16x32_bf16 v[42:45], v[156:159], v[118:121], v[42:45]
	v_mfma_f32_16x16x32_bf16 v[188:191], v[160:163], v[118:121], v[38:41]
	v_mfma_f32_16x16x32_bf16 v[34:37], v[164:167], v[118:121], v[34:37]
	v_mfma_f32_16x16x32_bf16 v[30:33], v[146:149], v[70:73], v[30:33]
	v_mfma_f32_16x16x32_bf16 v[26:29], v[156:159], v[70:73], v[26:29]
	v_mfma_f32_16x16x32_bf16 v[192:195], v[160:163], v[70:73], v[22:25]
	v_mfma_f32_16x16x32_bf16 v[18:21], v[164:167], v[70:73], v[18:21]
	v_mfma_f32_16x16x32_bf16 v[14:17], v[146:149], v[86:89], v[14:17]
	v_mfma_f32_16x16x32_bf16 v[10:13], v[156:159], v[86:89], v[10:13]
	v_mfma_f32_16x16x32_bf16 v[146:149], v[160:163], v[86:89], v[6:9]
	v_mfma_f32_16x16x32_bf16 v[2:5], v[164:167], v[86:89], v[2:5]
	s_waitcnt vmcnt(0)
	s_waitcnt lgkmcnt(0)
	s_barrier
	s_nop 0
	ds_read_b128 v[6:9], v155 offset:40960
	ds_read_b128 v[156:159], v155 offset:41984
	ds_read_b128 v[160:163], v155 offset:43008
	ds_read_b128 v[164:167], v155 offset:44032
	ds_read_b128 v[22:25], v154 offset:24576
	ds_read_b128 v[38:41], v154 offset:25600
	ds_read_b128 v[54:57], v154 offset:26624
	ds_read_b128 v[196:199], v154 offset:27648
	s_waitcnt lgkmcnt(0)
	v_mfma_f32_16x16x32_bf16 v[210:213], v[6:9], v[22:25], v[126:129]
	v_mfma_f32_16x16x32_bf16 v[118:121], v[156:159], v[22:25], v[122:125]
	v_mfma_f32_16x16x32_bf16 v[184:187], v[160:163], v[22:25], v[184:187]
	v_mfma_f32_16x16x32_bf16 v[114:117], v[164:167], v[22:25], v[114:117]
	v_mfma_f32_16x16x32_bf16 v[110:113], v[6:9], v[38:41], v[110:113]
	v_mfma_f32_16x16x32_bf16 v[102:105], v[156:159], v[38:41], v[106:109]
	v_mfma_f32_16x16x32_bf16 v[106:109], v[160:163], v[38:41], v[168:171]
	v_mfma_f32_16x16x32_bf16 v[98:101], v[164:167], v[38:41], v[98:101]
	ds_read_b128 v[22:25], v154 offset:28672
	ds_read_b128 v[122:125], v154 offset:29696
	v_mfma_f32_16x16x32_bf16 v[94:97], v[6:9], v[54:57], v[94:97]
	v_mfma_f32_16x16x32_bf16 v[86:89], v[156:159], v[54:57], v[90:93]
	v_mfma_f32_16x16x32_bf16 v[90:93], v[160:163], v[54:57], v[172:175]
	v_mfma_f32_16x16x32_bf16 v[82:85], v[164:167], v[54:57], v[82:85]
	v_mfma_f32_16x16x32_bf16 v[78:81], v[6:9], v[196:199], v[78:81]
	v_mfma_f32_16x16x32_bf16 v[70:73], v[156:159], v[196:199], v[74:77]
	v_mfma_f32_16x16x32_bf16 v[74:77], v[160:163], v[196:199], v[176:179]
	v_mfma_f32_16x16x32_bf16 v[66:69], v[164:167], v[196:199], v[66:69]
	ds_read_b128 v[126:129], v154 offset:30720
	ds_read_b128 v[168:171], v154 offset:31744
	s_waitcnt lgkmcnt(0)
	v_mfma_f32_16x16x32_bf16 v[62:65], v[6:9], v[22:25], v[62:65]
	v_mfma_f32_16x16x32_bf16 v[54:57], v[156:159], v[22:25], v[58:61]
	v_mfma_f32_16x16x32_bf16 v[58:61], v[160:163], v[22:25], v[180:183]
	v_mfma_f32_16x16x32_bf16 v[50:53], v[164:167], v[22:25], v[50:53]
	v_mfma_f32_16x16x32_bf16 v[46:49], v[6:9], v[122:125], v[46:49]
	v_mfma_f32_16x16x32_bf16 v[38:41], v[156:159], v[122:125], v[42:45]
	v_mfma_f32_16x16x32_bf16 v[42:45], v[160:163], v[122:125], v[188:191]
	v_mfma_f32_16x16x32_bf16 v[34:37], v[164:167], v[122:125], v[34:37]
	v_mfma_f32_16x16x32_bf16 v[30:33], v[6:9], v[126:129], v[30:33]
	v_mfma_f32_16x16x32_bf16 v[22:25], v[156:159], v[126:129], v[26:29]
	v_mfma_f32_16x16x32_bf16 v[26:29], v[160:163], v[126:129], v[192:195]
	v_mfma_f32_16x16x32_bf16 v[18:21], v[164:167], v[126:129], v[18:21]
	v_mfma_f32_16x16x32_bf16 v[14:17], v[6:9], v[168:171], v[14:17]
	v_mfma_f32_16x16x32_bf16 v[6:9], v[156:159], v[168:171], v[10:13]
	v_mfma_f32_16x16x32_bf16 v[10:13], v[160:163], v[168:171], v[146:149]
	v_mfma_f32_16x16x32_bf16 v[2:5], v[164:167], v[168:171], v[2:5]
	s_lshl_b32 s90, s5, 8
	s_waitcnt vmcnt(0)
	s_barrier
; __device__ __forceinline__ float siluf_(float x) { return x * __builtin_amdgcn_rcpf(1.f + __expf(-x)); }
; template <int EPI, int MF>
; __device__ __forceinline__ void gemm_part(const u16* __restrict__ A, int lda, const u16* __restrict__ Bt, int K, int ntn, GemmEpi ep, char* smem,
;                                           int mbase, int mrows) {
;     ...
;       if (EPI == EPI_SWIGLU || (m & 1) == 0) __builtin_amdgcn_sched_barrier(0);
;       const int row = row0 + wr * (16 * MF) + m * 16 + fr;
;       const int cb = col0 + wc * 64 + 4 * fq;
;       float rstd = 1.f;
;       if (EPI != EPI_RESID) { if (ep.rss_in) rstd = rsqrtf(ep.rss_in[row] * (1.f / DM) + 1e-6f); }
;       if (EPI == EPI_SWIGLU) {
; #pragma unroll
;         for (int n = 0; n < 2; ++n) {
;           bf16x4 o;
; #pragma unroll
;           for (int jj = 0; jj < 4; ++jj) o[jj] = (short)f2bf(siluf_(acc[m][n][jj] * rstd) * (acc[m][n + 2][jj] * rstd));
;           *(bf16x4*)(ep.outb + (size_t)row * FF + (col0 >> 1) + wc * 32 + n * 16 + 4 * fq) = o;
;         }
	v_add_u32_e32 v124, s8, v152
	v_lshl_add_u64 v[122:123], v[136:137], 0, s[90:91]
	v_readlane_b32 s2, v252, 9
	v_ashrrev_i32_e32 v125, 31, v124
	v_readlane_b32 s3, v252, 10
	s_nop 1
	v_lshl_add_u64 v[126:127], v[124:125], 2, s[2:3]
	global_load_dword v125, v[126:127], off
	s_waitcnt vmcnt(0)
	v_fmamk_f32 v125, v125, 0x3a800000, v142
	v_cmp_gt_f32_e32 vcc, s69, v125
	v_mul_f32_e32 v128, 0x4b800000, v125
	s_nop 0
	v_cndmask_b32_e32 v125, v125, v128, vcc
	v_rsq_f32_e32 v125, v125
	s_nop 0
	v_mul_f32_e32 v128, 0x45800000, v125
	v_cndmask_b32_e32 v146, v125, v128, vcc
	v_pk_mul_f32 v[148:149], v[210:211], v[146:147] op_sel_hi:[1,0]
	v_pk_mul_f32 v[118:119], v[118:119], v[146:147] op_sel_hi:[1,0]
	v_mul_f32_e32 v125, 0xbfb8aa3b, v148
	v_exp_f32_e32 v125, v125
	v_mad_i64_i32 v[128:129], s[2:3], v124, s33, v[122:123]
	v_pk_mul_f32 v[114:115], v[114:115], v[146:147] op_sel_hi:[1,0]
	v_add_f32_e32 v125, 1.0, v125
	v_rcp_f32_e32 v156, v125
	v_mul_f32_e32 v125, 0xbfb8aa3b, v149
	v_exp_f32_e32 v125, v125
	v_pk_mul_f32 v[116:117], v[116:117], v[146:147] op_sel_hi:[1,0]
	v_add_f32_e32 v125, 1.0, v125
	v_rcp_f32_e32 v157, v125
	s_nop 0
	v_pk_mul_f32 v[148:149], v[148:149], v[156:157]
	v_pk_mul_f32 v[156:157], v[184:185], v[146:147] op_sel_hi:[1,0]
	s_nop 0
	v_pk_mul_f32 v[148:149], v[156:157], v[148:149]
	v_pk_mul_f32 v[156:157], v[212:213], v[146:147] op_sel_hi:[1,0]
	v_cvt_pk_bf16_f32 v148, v148, v149
	v_mul_f32_e32 v125, 0xbfb8aa3b, v156
	v_exp_f32_e32 v125, v125
	s_nop 0
	v_add_f32_e32 v125, 1.0, v125
	v_rcp_f32_e32 v158, v125
	v_mul_f32_e32 v125, 0xbfb8aa3b, v157
	v_exp_f32_e32 v125, v125
	s_nop 0
	v_add_f32_e32 v125, 1.0, v125
	v_rcp_f32_e32 v159, v125
	v_mul_f32_e32 v125, 0xbfb8aa3b, v118
	v_exp_f32_e32 v125, v125
	v_pk_mul_f32 v[156:157], v[156:157], v[158:159]
	v_pk_mul_f32 v[158:159], v[186:187], v[146:147] op_sel_hi:[1,0]
	v_add_f32_e32 v125, 1.0, v125
	v_pk_mul_f32 v[156:157], v[158:159], v[156:157]
	s_nop 0
	v_cvt_pk_bf16_f32 v149, v156, v157
	global_store_dwordx2 v[128:129], v[148:149], off
	v_rcp_f32_e32 v148, v125
	v_mul_f32_e32 v125, 0xbfb8aa3b, v119
	v_exp_f32_e32 v125, v125
	s_nop 0
	v_add_f32_e32 v125, 1.0, v125
	v_rcp_f32_e32 v149, v125
	s_nop 0
	v_pk_mul_f32 v[118:119], v[118:119], v[148:149]
	s_nop 0
	v_pk_mul_f32 v[114:115], v[114:115], v[118:119]
	v_pk_mul_f32 v[118:119], v[120:121], v[146:147] op_sel_hi:[1,0]
	v_cvt_pk_bf16_f32 v114, v114, v115
	v_mul_f32_e32 v115, 0xbfb8aa3b, v118
	v_exp_f32_e32 v115, v115
	s_nop 0
	v_add_f32_e32 v115, 1.0, v115
	v_rcp_f32_e32 v120, v115
	v_mul_f32_e32 v115, 0xbfb8aa3b, v119
	v_exp_f32_e32 v115, v115
	s_nop 0
	v_add_f32_e32 v115, 1.0, v115
	v_rcp_f32_e32 v121, v115
	s_nop 0
	v_pk_mul_f32 v[118:119], v[118:119], v[120:121]
	s_nop 0
	v_pk_mul_f32 v[116:117], v[116:117], v[118:119]
	s_nop 0
	v_cvt_pk_bf16_f32 v115, v116, v117
	global_store_dwordx2 v[128:129], v[114:115], off offset:32
	global_load_dword v115, v[126:127], off offset:64
	v_or_b32_e32 v114, 16, v124
	s_waitcnt vmcnt(0)
	v_fmamk_f32 v115, v115, 0x3a800000, v142
	v_cmp_gt_f32_e32 vcc, s69, v115
	v_mul_f32_e32 v116, 0x4b800000, v115
	s_nop 0
	v_cndmask_b32_e32 v115, v115, v116, vcc
	v_rsq_f32_e32 v115, v115
	s_nop 0
	v_mul_f32_e32 v116, 0x45800000, v115
	v_cndmask_b32_e32 v116, v115, v116, vcc
	v_pk_mul_f32 v[110:111], v[110:111], v[116:117] op_sel_hi:[1,0]
	v_mad_i64_i32 v[114:115], s[2:3], v114, s33, v[122:123]
	v_mul_f32_e32 v117, 0xbfb8aa3b, v110
	v_exp_f32_e32 v117, v117
	s_nop 0
	v_add_f32_e32 v117, 1.0, v117
	v_rcp_f32_e32 v118, v117
	v_mul_f32_e32 v117, 0xbfb8aa3b, v111
	v_exp_f32_e32 v117, v117
	s_nop 0
	v_add_f32_e32 v117, 1.0, v117
	v_rcp_f32_e32 v119, v117
	v_pk_mul_f32 v[106:107], v[106:107], v[116:117] op_sel_hi:[1,0]
	v_pk_mul_f32 v[108:109], v[108:109], v[116:117] op_sel_hi:[1,0]
	v_pk_mul_f32 v[102:103], v[102:103], v[116:117] op_sel_hi:[1,0]
	v_pk_mul_f32 v[110:111], v[110:111], v[118:119]
	v_pk_mul_f32 v[98:99], v[98:99], v[116:117] op_sel_hi:[1,0]
	v_pk_mul_f32 v[106:107], v[106:107], v[110:111]
	v_pk_mul_f32 v[110:111], v[112:113], v[116:117] op_sel_hi:[1,0]
	v_cvt_pk_bf16_f32 v106, v106, v107
	v_mul_f32_e32 v107, 0xbfb8aa3b, v110
	v_exp_f32_e32 v107, v107
	v_pk_mul_f32 v[100:101], v[100:101], v[116:117] op_sel_hi:[1,0]
	v_add_f32_e32 v107, 1.0, v107
	v_rcp_f32_e32 v112, v107
	v_mul_f32_e32 v107, 0xbfb8aa3b, v111
	v_exp_f32_e32 v107, v107
	s_nop 0
	v_add_f32_e32 v107, 1.0, v107
	v_rcp_f32_e32 v113, v107
	s_nop 0
	v_pk_mul_f32 v[110:111], v[110:111], v[112:113]
	s_nop 0
	v_pk_mul_f32 v[108:109], v[108:109], v[110:111]
	s_nop 0
	v_cvt_pk_bf16_f32 v107, v108, v109
	global_store_dwordx2 v[114:115], v[106:107], off
	v_mul_f32_e32 v106, 0xbfb8aa3b, v102
	v_mul_f32_e32 v107, 0xbfb8aa3b, v103
	v_exp_f32_e32 v106, v106
	v_exp_f32_e32 v107, v107
	v_add_f32_e32 v106, 1.0, v106
	v_add_f32_e32 v107, 1.0, v107
	v_rcp_f32_e32 v106, v106
	v_rcp_f32_e32 v107, v107
	s_nop 0
	v_pk_mul_f32 v[102:103], v[102:103], v[106:107]
	s_nop 0
	v_pk_mul_f32 v[98:99], v[98:99], v[102:103]
	v_pk_mul_f32 v[102:103], v[104:105], v[116:117] op_sel_hi:[1,0]
	v_cvt_pk_bf16_f32 v98, v98, v99
	v_mul_f32_e32 v99, 0xbfb8aa3b, v102
	v_exp_f32_e32 v99, v99
	s_nop 0
	v_add_f32_e32 v99, 1.0, v99
	v_rcp_f32_e32 v104, v99
	v_mul_f32_e32 v99, 0xbfb8aa3b, v103
	v_exp_f32_e32 v99, v99
	s_nop 0
	v_add_f32_e32 v99, 1.0, v99
	v_rcp_f32_e32 v105, v99
	s_nop 0
	v_pk_mul_f32 v[102:103], v[102:103], v[104:105]
	s_nop 0
	v_pk_mul_f32 v[100:101], v[100:101], v[102:103]
	s_nop 0
	v_cvt_pk_bf16_f32 v99, v100, v101
	global_store_dwordx2 v[114:115], v[98:99], off offset:32
	global_load_dword v99, v[126:127], off offset:128
	v_or_b32_e32 v98, 32, v124
	s_waitcnt vmcnt(0)
; __device__ __forceinline__ float siluf_(float x) { return x * __builtin_amdgcn_rcpf(1.f + __expf(-x)); }
; template <int EPI, int MF>
; __device__ __forceinline__ void gemm_part(const u16* __restrict__ A, int lda, const u16* __restrict__ Bt, int K, int ntn, GemmEpi ep, char* smem,
;                                           int mbase, int mrows) {
;     ...
;       if (EPI == EPI_SWIGLU || (m & 1) == 0) __builtin_amdgcn_sched_barrier(0);
;       const int row = row0 + wr * (16 * MF) + m * 16 + fr;
;       const int cb = col0 + wc * 64 + 4 * fq;
;       float rstd = 1.f;
;       if (EPI != EPI_RESID) { if (ep.rss_in) rstd = rsqrtf(ep.rss_in[row] * (1.f / DM) + 1e-6f); }
;       if (EPI == EPI_SWIGLU) {
; #pragma unroll
;         for (int n = 0; n < 2; ++n) {
;           bf16x4 o;
; #pragma unroll
;           for (int jj = 0; jj < 4; ++jj) o[jj] = (short)f2bf(siluf_(acc[m][n][jj] * rstd) * (acc[m][n + 2][jj] * rstd));
;           *(bf16x4*)(ep.outb + (size_t)row * FF + (col0 >> 1) + wc * 32 + n * 16 + 4 * fq) = o;
;         }
	v_fmamk_f32 v99, v99, 0x3a800000, v142
	v_cmp_gt_f32_e32 vcc, s69, v99
	v_mul_f32_e32 v100, 0x4b800000, v99
	s_nop 0
	v_cndmask_b32_e32 v99, v99, v100, vcc
	v_rsq_f32_e32 v99, v99
	s_nop 0
	v_mul_f32_e32 v100, 0x45800000, v99
	v_cndmask_b32_e32 v100, v99, v100, vcc
	v_pk_mul_f32 v[94:95], v[94:95], v[100:101] op_sel_hi:[1,0]
	v_mad_i64_i32 v[98:99], s[2:3], v98, s33, v[122:123]
	v_mul_f32_e32 v101, 0xbfb8aa3b, v94
	v_exp_f32_e32 v101, v101
	s_nop 0
	v_add_f32_e32 v101, 1.0, v101
	v_rcp_f32_e32 v102, v101
	v_mul_f32_e32 v101, 0xbfb8aa3b, v95
	v_exp_f32_e32 v101, v101
	s_nop 0
	v_add_f32_e32 v101, 1.0, v101
	v_rcp_f32_e32 v103, v101
	v_pk_mul_f32 v[90:91], v[90:91], v[100:101] op_sel_hi:[1,0]
	v_pk_mul_f32 v[92:93], v[92:93], v[100:101] op_sel_hi:[1,0]
	v_pk_mul_f32 v[86:87], v[86:87], v[100:101] op_sel_hi:[1,0]
	v_pk_mul_f32 v[94:95], v[94:95], v[102:103]
	v_pk_mul_f32 v[82:83], v[82:83], v[100:101] op_sel_hi:[1,0]
	v_pk_mul_f32 v[90:91], v[90:91], v[94:95]
	v_pk_mul_f32 v[94:95], v[96:97], v[100:101] op_sel_hi:[1,0]
	v_cvt_pk_bf16_f32 v90, v90, v91
	v_mul_f32_e32 v91, 0xbfb8aa3b, v94
	v_exp_f32_e32 v91, v91
	v_pk_mul_f32 v[84:85], v[84:85], v[100:101] op_sel_hi:[1,0]
	v_add_f32_e32 v91, 1.0, v91
	v_rcp_f32_e32 v96, v91
	v_mul_f32_e32 v91, 0xbfb8aa3b, v95
	v_exp_f32_e32 v91, v91
	s_nop 0
	v_add_f32_e32 v91, 1.0, v91
	v_rcp_f32_e32 v97, v91
	s_nop 0
	v_pk_mul_f32 v[94:95], v[94:95], v[96:97]
	s_nop 0
	v_pk_mul_f32 v[92:93], v[92:93], v[94:95]
	s_nop 0
	v_cvt_pk_bf16_f32 v91, v92, v93
	global_store_dwordx2 v[98:99], v[90:91], off
	v_mul_f32_e32 v90, 0xbfb8aa3b, v86
	v_mul_f32_e32 v91, 0xbfb8aa3b, v87
	v_exp_f32_e32 v90, v90
	v_exp_f32_e32 v91, v91
	v_add_f32_e32 v90, 1.0, v90
	v_add_f32_e32 v91, 1.0, v91
	v_rcp_f32_e32 v90, v90
	v_rcp_f32_e32 v91, v91
	s_nop 0
	v_pk_mul_f32 v[86:87], v[86:87], v[90:91]
	s_nop 0
	v_pk_mul_f32 v[82:83], v[82:83], v[86:87]
	v_pk_mul_f32 v[86:87], v[88:89], v[100:101] op_sel_hi:[1,0]
	v_cvt_pk_bf16_f32 v82, v82, v83
	v_mul_f32_e32 v83, 0xbfb8aa3b, v86
	v_exp_f32_e32 v83, v83
	s_nop 0
	v_add_f32_e32 v83, 1.0, v83
	v_rcp_f32_e32 v88, v83
	v_mul_f32_e32 v83, 0xbfb8aa3b, v87
	v_exp_f32_e32 v83, v83
	s_nop 0
	v_add_f32_e32 v83, 1.0, v83
	v_rcp_f32_e32 v89, v83
	s_nop 0
	v_pk_mul_f32 v[86:87], v[86:87], v[88:89]
	s_nop 0
	v_pk_mul_f32 v[84:85], v[84:85], v[86:87]
	s_nop 0
	v_cvt_pk_bf16_f32 v83, v84, v85
	global_store_dwordx2 v[98:99], v[82:83], off offset:32
	global_load_dword v83, v[126:127], off offset:192
	v_or_b32_e32 v82, 48, v124
	s_waitcnt vmcnt(0)
	v_fmamk_f32 v83, v83, 0x3a800000, v142
	v_cmp_gt_f32_e32 vcc, s69, v83
	v_mul_f32_e32 v84, 0x4b800000, v83
	s_nop 0
	v_cndmask_b32_e32 v83, v83, v84, vcc
	v_rsq_f32_e32 v83, v83
	s_nop 0
	v_mul_f32_e32 v84, 0x45800000, v83
	v_cndmask_b32_e32 v84, v83, v84, vcc
	v_pk_mul_f32 v[78:79], v[78:79], v[84:85] op_sel_hi:[1,0]
	v_mad_i64_i32 v[82:83], s[2:3], v82, s33, v[122:123]
	v_mul_f32_e32 v85, 0xbfb8aa3b, v78
	v_exp_f32_e32 v85, v85
	s_nop 0
	v_add_f32_e32 v85, 1.0, v85
	v_rcp_f32_e32 v86, v85
	v_mul_f32_e32 v85, 0xbfb8aa3b, v79
	v_exp_f32_e32 v85, v85
	s_nop 0
	v_add_f32_e32 v85, 1.0, v85
	v_rcp_f32_e32 v87, v85
	v_pk_mul_f32 v[74:75], v[74:75], v[84:85] op_sel_hi:[1,0]
	v_pk_mul_f32 v[76:77], v[76:77], v[84:85] op_sel_hi:[1,0]
	v_pk_mul_f32 v[70:71], v[70:71], v[84:85] op_sel_hi:[1,0]
	v_pk_mul_f32 v[78:79], v[78:79], v[86:87]
	v_pk_mul_f32 v[66:67], v[66:67], v[84:85] op_sel_hi:[1,0]
	v_pk_mul_f32 v[74:75], v[74:75], v[78:79]
	v_pk_mul_f32 v[78:79], v[80:81], v[84:85] op_sel_hi:[1,0]
	v_cvt_pk_bf16_f32 v74, v74, v75
	v_mul_f32_e32 v75, 0xbfb8aa3b, v78
	v_exp_f32_e32 v75, v75
	v_pk_mul_f32 v[68:69], v[68:69], v[84:85] op_sel_hi:[1,0]
	v_add_f32_e32 v75, 1.0, v75
	v_rcp_f32_e32 v80, v75
	v_mul_f32_e32 v75, 0xbfb8aa3b, v79
	v_exp_f32_e32 v75, v75
	s_nop 0
	v_add_f32_e32 v75, 1.0, v75
	v_rcp_f32_e32 v81, v75
	s_nop 0
	v_pk_mul_f32 v[78:79], v[78:79], v[80:81]
	s_nop 0
	v_pk_mul_f32 v[76:77], v[76:77], v[78:79]
	s_nop 0
	v_cvt_pk_bf16_f32 v75, v76, v77
	global_store_dwordx2 v[82:83], v[74:75], off
	v_mul_f32_e32 v74, 0xbfb8aa3b, v70
	v_mul_f32_e32 v75, 0xbfb8aa3b, v71
	v_exp_f32_e32 v74, v74
	v_exp_f32_e32 v75, v75
	v_add_f32_e32 v74, 1.0, v74
	v_add_f32_e32 v75, 1.0, v75
	v_rcp_f32_e32 v74, v74
	v_rcp_f32_e32 v75, v75
	s_nop 0
	v_pk_mul_f32 v[70:71], v[70:71], v[74:75]
	s_nop 0
	v_pk_mul_f32 v[66:67], v[66:67], v[70:71]
	v_pk_mul_f32 v[70:71], v[72:73], v[84:85] op_sel_hi:[1,0]
	v_cvt_pk_bf16_f32 v66, v66, v67
	v_mul_f32_e32 v67, 0xbfb8aa3b, v70
	v_exp_f32_e32 v67, v67
	s_nop 0
	v_add_f32_e32 v67, 1.0, v67
	v_rcp_f32_e32 v72, v67
	v_mul_f32_e32 v67, 0xbfb8aa3b, v71
	v_exp_f32_e32 v67, v67
	s_nop 0
	v_add_f32_e32 v67, 1.0, v67
	v_rcp_f32_e32 v73, v67
	s_nop 0
	v_pk_mul_f32 v[70:71], v[70:71], v[72:73]
	s_nop 0
	v_pk_mul_f32 v[68:69], v[68:69], v[70:71]
	s_nop 0
	v_cvt_pk_bf16_f32 v67, v68, v69
	global_store_dwordx2 v[82:83], v[66:67], off offset:32
	global_load_dword v67, v[126:127], off offset:256
	v_or_b32_e32 v66, 64, v124
	s_waitcnt vmcnt(0)
; __device__ __forceinline__ float siluf_(float x) { return x * __builtin_amdgcn_rcpf(1.f + __expf(-x)); }
; template <int EPI, int MF>
; __device__ __forceinline__ void gemm_part(const u16* __restrict__ A, int lda, const u16* __restrict__ Bt, int K, int ntn, GemmEpi ep, char* smem,
;                                           int mbase, int mrows) {
;     ...
;       if (EPI == EPI_SWIGLU || (m & 1) == 0) __builtin_amdgcn_sched_barrier(0);
;       const int row = row0 + wr * (16 * MF) + m * 16 + fr;
;       const int cb = col0 + wc * 64 + 4 * fq;
;       float rstd = 1.f;
;       if (EPI != EPI_RESID) { if (ep.rss_in) rstd = rsqrtf(ep.rss_in[row] * (1.f / DM) + 1e-6f); }
;       if (EPI == EPI_SWIGLU) {
; #pragma unroll
;         for (int n = 0; n < 2; ++n) {
;           bf16x4 o;
; #pragma unroll
;           for (int jj = 0; jj < 4; ++jj) o[jj] = (short)f2bf(siluf_(acc[m][n][jj] * rstd) * (acc[m][n + 2][jj] * rstd));
;           *(bf16x4*)(ep.outb + (size_t)row * FF + (col0 >> 1) + wc * 32 + n * 16 + 4 * fq) = o;
;         }
	v_fmamk_f32 v67, v67, 0x3a800000, v142
	v_cmp_gt_f32_e32 vcc, s69, v67
	v_mul_f32_e32 v68, 0x4b800000, v67
	s_nop 0
	v_cndmask_b32_e32 v67, v67, v68, vcc
	v_rsq_f32_e32 v67, v67
	s_nop 0
	v_mul_f32_e32 v68, 0x45800000, v67
	v_cndmask_b32_e32 v68, v67, v68, vcc
	v_pk_mul_f32 v[62:63], v[62:63], v[68:69] op_sel_hi:[1,0]
	v_mad_i64_i32 v[66:67], s[2:3], v66, s33, v[122:123]
	v_mul_f32_e32 v69, 0xbfb8aa3b, v62
	v_exp_f32_e32 v69, v69
	s_nop 0
	v_add_f32_e32 v69, 1.0, v69
	v_rcp_f32_e32 v70, v69
	v_mul_f32_e32 v69, 0xbfb8aa3b, v63
	v_exp_f32_e32 v69, v69
	s_nop 0
	v_add_f32_e32 v69, 1.0, v69
	v_rcp_f32_e32 v71, v69
	v_pk_mul_f32 v[58:59], v[58:59], v[68:69] op_sel_hi:[1,0]
	v_pk_mul_f32 v[60:61], v[60:61], v[68:69] op_sel_hi:[1,0]
	v_pk_mul_f32 v[54:55], v[54:55], v[68:69] op_sel_hi:[1,0]
	v_pk_mul_f32 v[62:63], v[62:63], v[70:71]
	v_pk_mul_f32 v[50:51], v[50:51], v[68:69] op_sel_hi:[1,0]
	v_pk_mul_f32 v[58:59], v[58:59], v[62:63]
	v_pk_mul_f32 v[62:63], v[64:65], v[68:69] op_sel_hi:[1,0]
	v_cvt_pk_bf16_f32 v58, v58, v59
	v_mul_f32_e32 v59, 0xbfb8aa3b, v62
	v_exp_f32_e32 v59, v59
	v_pk_mul_f32 v[52:53], v[52:53], v[68:69] op_sel_hi:[1,0]
	v_add_f32_e32 v59, 1.0, v59
	v_rcp_f32_e32 v64, v59
	v_mul_f32_e32 v59, 0xbfb8aa3b, v63
	v_exp_f32_e32 v59, v59
	s_nop 0
	v_add_f32_e32 v59, 1.0, v59
	v_rcp_f32_e32 v65, v59
	s_nop 0
	v_pk_mul_f32 v[62:63], v[62:63], v[64:65]
	s_nop 0
	v_pk_mul_f32 v[60:61], v[60:61], v[62:63]
	s_nop 0
	v_cvt_pk_bf16_f32 v59, v60, v61
	global_store_dwordx2 v[66:67], v[58:59], off
	v_mul_f32_e32 v58, 0xbfb8aa3b, v54
	v_mul_f32_e32 v59, 0xbfb8aa3b, v55
	v_exp_f32_e32 v58, v58
	v_exp_f32_e32 v59, v59
	v_add_f32_e32 v58, 1.0, v58
	v_add_f32_e32 v59, 1.0, v59
	v_rcp_f32_e32 v58, v58
	v_rcp_f32_e32 v59, v59
	s_nop 0
	v_pk_mul_f32 v[54:55], v[54:55], v[58:59]
	s_nop 0
	v_pk_mul_f32 v[50:51], v[50:51], v[54:55]
	v_pk_mul_f32 v[54:55], v[56:57], v[68:69] op_sel_hi:[1,0]
	v_cvt_pk_bf16_f32 v50, v50, v51
	v_mul_f32_e32 v51, 0xbfb8aa3b, v54
	v_exp_f32_e32 v51, v51
	s_nop 0
	v_add_f32_e32 v51, 1.0, v51
	v_rcp_f32_e32 v56, v51
	v_mul_f32_e32 v51, 0xbfb8aa3b, v55
	v_exp_f32_e32 v51, v51
	s_nop 0
	v_add_f32_e32 v51, 1.0, v51
	v_rcp_f32_e32 v57, v51
	s_nop 0
	v_pk_mul_f32 v[54:55], v[54:55], v[56:57]
	s_nop 0
	v_pk_mul_f32 v[52:53], v[52:53], v[54:55]
	s_nop 0
	v_cvt_pk_bf16_f32 v51, v52, v53
	global_store_dwordx2 v[66:67], v[50:51], off offset:32
	global_load_dword v51, v[126:127], off offset:320
	v_or_b32_e32 v50, 0x50, v124
	s_waitcnt vmcnt(0)
	v_fmamk_f32 v51, v51, 0x3a800000, v142
	v_cmp_gt_f32_e32 vcc, s69, v51
	v_mul_f32_e32 v52, 0x4b800000, v51
	s_nop 0
	v_cndmask_b32_e32 v51, v51, v52, vcc
	v_rsq_f32_e32 v51, v51
	s_nop 0
	v_mul_f32_e32 v52, 0x45800000, v51
	v_cndmask_b32_e32 v52, v51, v52, vcc
	v_pk_mul_f32 v[46:47], v[46:47], v[52:53] op_sel_hi:[1,0]
	v_mad_i64_i32 v[50:51], s[2:3], v50, s33, v[122:123]
	v_mul_f32_e32 v53, 0xbfb8aa3b, v46
	v_exp_f32_e32 v53, v53
	s_nop 0
	v_add_f32_e32 v53, 1.0, v53
	v_rcp_f32_e32 v54, v53
	v_mul_f32_e32 v53, 0xbfb8aa3b, v47
	v_exp_f32_e32 v53, v53
	s_nop 0
	v_add_f32_e32 v53, 1.0, v53
	v_rcp_f32_e32 v55, v53
	v_pk_mul_f32 v[42:43], v[42:43], v[52:53] op_sel_hi:[1,0]
	v_pk_mul_f32 v[44:45], v[44:45], v[52:53] op_sel_hi:[1,0]
	v_pk_mul_f32 v[38:39], v[38:39], v[52:53] op_sel_hi:[1,0]
	v_pk_mul_f32 v[46:47], v[46:47], v[54:55]
	v_pk_mul_f32 v[34:35], v[34:35], v[52:53] op_sel_hi:[1,0]
	v_pk_mul_f32 v[42:43], v[42:43], v[46:47]
	v_pk_mul_f32 v[46:47], v[48:49], v[52:53] op_sel_hi:[1,0]
	v_cvt_pk_bf16_f32 v42, v42, v43
	v_mul_f32_e32 v43, 0xbfb8aa3b, v46
	v_exp_f32_e32 v43, v43
	v_pk_mul_f32 v[36:37], v[36:37], v[52:53] op_sel_hi:[1,0]
	v_add_f32_e32 v43, 1.0, v43
	v_rcp_f32_e32 v48, v43
	v_mul_f32_e32 v43, 0xbfb8aa3b, v47
	v_exp_f32_e32 v43, v43
	s_nop 0
	v_add_f32_e32 v43, 1.0, v43
	v_rcp_f32_e32 v49, v43
	s_nop 0
	v_pk_mul_f32 v[46:47], v[46:47], v[48:49]
	s_nop 0
	v_pk_mul_f32 v[44:45], v[44:45], v[46:47]
	s_nop 0
	v_cvt_pk_bf16_f32 v43, v44, v45
	global_store_dwordx2 v[50:51], v[42:43], off
	v_mul_f32_e32 v42, 0xbfb8aa3b, v38
	v_mul_f32_e32 v43, 0xbfb8aa3b, v39
	v_exp_f32_e32 v42, v42
	v_exp_f32_e32 v43, v43
	v_add_f32_e32 v42, 1.0, v42
	v_add_f32_e32 v43, 1.0, v43
	v_rcp_f32_e32 v42, v42
	v_rcp_f32_e32 v43, v43
	s_nop 0
	v_pk_mul_f32 v[38:39], v[38:39], v[42:43]
	s_nop 0
	v_pk_mul_f32 v[34:35], v[34:35], v[38:39]
	v_pk_mul_f32 v[38:39], v[40:41], v[52:53] op_sel_hi:[1,0]
	v_cvt_pk_bf16_f32 v34, v34, v35
	v_mul_f32_e32 v35, 0xbfb8aa3b, v38
	v_exp_f32_e32 v35, v35
	s_nop 0
	v_add_f32_e32 v35, 1.0, v35
	v_rcp_f32_e32 v40, v35
	v_mul_f32_e32 v35, 0xbfb8aa3b, v39
	v_exp_f32_e32 v35, v35
	s_nop 0
	v_add_f32_e32 v35, 1.0, v35
	v_rcp_f32_e32 v41, v35
	s_nop 0
	v_pk_mul_f32 v[38:39], v[38:39], v[40:41]
	s_nop 0
	v_pk_mul_f32 v[36:37], v[36:37], v[38:39]
	s_nop 0
	v_cvt_pk_bf16_f32 v35, v36, v37
	global_store_dwordx2 v[50:51], v[34:35], off offset:32
	global_load_dword v35, v[126:127], off offset:384
	v_or_b32_e32 v34, 0x60, v124
	s_waitcnt vmcnt(0)
; __device__ __forceinline__ float siluf_(float x) { return x * __builtin_amdgcn_rcpf(1.f + __expf(-x)); }
; template <int EPI, int MF>
; __device__ __forceinline__ void gemm_part(const u16* __restrict__ A, int lda, const u16* __restrict__ Bt, int K, int ntn, GemmEpi ep, char* smem,
;                                           int mbase, int mrows) {
;     ...
;       if (EPI == EPI_SWIGLU || (m & 1) == 0) __builtin_amdgcn_sched_barrier(0);
;       const int row = row0 + wr * (16 * MF) + m * 16 + fr;
;       const int cb = col0 + wc * 64 + 4 * fq;
;       float rstd = 1.f;
;       if (EPI != EPI_RESID) { if (ep.rss_in) rstd = rsqrtf(ep.rss_in[row] * (1.f / DM) + 1e-6f); }
;       if (EPI == EPI_SWIGLU) {
; #pragma unroll
;         for (int n = 0; n < 2; ++n) {
;           bf16x4 o;
; #pragma unroll
;           for (int jj = 0; jj < 4; ++jj) o[jj] = (short)f2bf(siluf_(acc[m][n][jj] * rstd) * (acc[m][n + 2][jj] * rstd));
;           *(bf16x4*)(ep.outb + (size_t)row * FF + (col0 >> 1) + wc * 32 + n * 16 + 4 * fq) = o;
;         }
	v_fmamk_f32 v35, v35, 0x3a800000, v142
	v_cmp_gt_f32_e32 vcc, s69, v35
	v_mul_f32_e32 v36, 0x4b800000, v35
	s_nop 0
	v_cndmask_b32_e32 v35, v35, v36, vcc
	v_rsq_f32_e32 v35, v35
	s_nop 0
	v_mul_f32_e32 v36, 0x45800000, v35
	v_cndmask_b32_e32 v36, v35, v36, vcc
	v_pk_mul_f32 v[30:31], v[30:31], v[36:37] op_sel_hi:[1,0]
	v_mad_i64_i32 v[34:35], s[2:3], v34, s33, v[122:123]
	v_mul_f32_e32 v37, 0xbfb8aa3b, v30
	v_exp_f32_e32 v37, v37
	s_nop 0
	v_add_f32_e32 v37, 1.0, v37
	v_rcp_f32_e32 v38, v37
	v_mul_f32_e32 v37, 0xbfb8aa3b, v31
	v_exp_f32_e32 v37, v37
	s_nop 0
	v_add_f32_e32 v37, 1.0, v37
	v_rcp_f32_e32 v39, v37
	v_pk_mul_f32 v[26:27], v[26:27], v[36:37] op_sel_hi:[1,0]
	v_pk_mul_f32 v[28:29], v[28:29], v[36:37] op_sel_hi:[1,0]
	v_pk_mul_f32 v[22:23], v[22:23], v[36:37] op_sel_hi:[1,0]
	v_pk_mul_f32 v[30:31], v[30:31], v[38:39]
	v_pk_mul_f32 v[18:19], v[18:19], v[36:37] op_sel_hi:[1,0]
	v_pk_mul_f32 v[26:27], v[26:27], v[30:31]
	v_pk_mul_f32 v[30:31], v[32:33], v[36:37] op_sel_hi:[1,0]
	v_cvt_pk_bf16_f32 v26, v26, v27
	v_mul_f32_e32 v27, 0xbfb8aa3b, v30
	v_exp_f32_e32 v27, v27
	v_pk_mul_f32 v[20:21], v[20:21], v[36:37] op_sel_hi:[1,0]
	v_add_f32_e32 v27, 1.0, v27
	v_rcp_f32_e32 v32, v27
	v_mul_f32_e32 v27, 0xbfb8aa3b, v31
	v_exp_f32_e32 v27, v27
	s_nop 0
	v_add_f32_e32 v27, 1.0, v27
	v_rcp_f32_e32 v33, v27
	s_nop 0
	v_pk_mul_f32 v[30:31], v[30:31], v[32:33]
	s_nop 0
	v_pk_mul_f32 v[28:29], v[28:29], v[30:31]
	s_nop 0
	v_cvt_pk_bf16_f32 v27, v28, v29
	global_store_dwordx2 v[34:35], v[26:27], off
	v_mul_f32_e32 v26, 0xbfb8aa3b, v22
	v_mul_f32_e32 v27, 0xbfb8aa3b, v23
	v_exp_f32_e32 v26, v26
	v_exp_f32_e32 v27, v27
	v_add_f32_e32 v26, 1.0, v26
	v_add_f32_e32 v27, 1.0, v27
	v_rcp_f32_e32 v26, v26
	v_rcp_f32_e32 v27, v27
	s_nop 0
	v_pk_mul_f32 v[22:23], v[22:23], v[26:27]
	s_nop 0
	v_pk_mul_f32 v[18:19], v[18:19], v[22:23]
	v_pk_mul_f32 v[22:23], v[24:25], v[36:37] op_sel_hi:[1,0]
	v_cvt_pk_bf16_f32 v18, v18, v19
	v_mul_f32_e32 v19, 0xbfb8aa3b, v22
	v_exp_f32_e32 v19, v19
	s_nop 0
	v_add_f32_e32 v19, 1.0, v19
	v_rcp_f32_e32 v24, v19
	v_mul_f32_e32 v19, 0xbfb8aa3b, v23
	v_exp_f32_e32 v19, v19
	s_nop 0
	v_add_f32_e32 v19, 1.0, v19
	v_rcp_f32_e32 v25, v19
	s_nop 0
	v_pk_mul_f32 v[22:23], v[22:23], v[24:25]
	s_nop 0
	v_pk_mul_f32 v[20:21], v[20:21], v[22:23]
	s_nop 0
	v_cvt_pk_bf16_f32 v19, v20, v21
	global_store_dwordx2 v[34:35], v[18:19], off offset:32
	global_load_dword v19, v[126:127], off offset:448
	v_or_b32_e32 v18, 0x70, v124
	s_waitcnt vmcnt(0)
	v_fmamk_f32 v19, v19, 0x3a800000, v142
	v_cmp_gt_f32_e32 vcc, s69, v19
	v_mul_f32_e32 v20, 0x4b800000, v19
	s_nop 0
	v_cndmask_b32_e32 v19, v19, v20, vcc
	v_rsq_f32_e32 v19, v19
	s_nop 0
	v_mul_f32_e32 v20, 0x45800000, v19
	v_cndmask_b32_e32 v20, v19, v20, vcc
	v_pk_mul_f32 v[14:15], v[14:15], v[20:21] op_sel_hi:[1,0]
	v_mad_i64_i32 v[18:19], s[2:3], v18, s33, v[122:123]
	v_mul_f32_e32 v21, 0xbfb8aa3b, v14
	v_exp_f32_e32 v21, v21
	s_nop 0
	v_add_f32_e32 v21, 1.0, v21
	v_rcp_f32_e32 v22, v21
	v_mul_f32_e32 v21, 0xbfb8aa3b, v15
	v_exp_f32_e32 v21, v21
	s_nop 0
	v_add_f32_e32 v21, 1.0, v21
	v_rcp_f32_e32 v23, v21
	v_pk_mul_f32 v[10:11], v[10:11], v[20:21] op_sel_hi:[1,0]
	v_pk_mul_f32 v[12:13], v[12:13], v[20:21] op_sel_hi:[1,0]
	v_pk_mul_f32 v[6:7], v[6:7], v[20:21] op_sel_hi:[1,0]
	v_pk_mul_f32 v[14:15], v[14:15], v[22:23]
	v_pk_mul_f32 v[2:3], v[2:3], v[20:21] op_sel_hi:[1,0]
	v_pk_mul_f32 v[10:11], v[10:11], v[14:15]
	v_pk_mul_f32 v[14:15], v[16:17], v[20:21] op_sel_hi:[1,0]
	v_cvt_pk_bf16_f32 v10, v10, v11
	v_mul_f32_e32 v11, 0xbfb8aa3b, v14
	v_exp_f32_e32 v11, v11
	v_pk_mul_f32 v[4:5], v[4:5], v[20:21] op_sel_hi:[1,0]
	v_add_f32_e32 v11, 1.0, v11
	v_rcp_f32_e32 v16, v11
	v_mul_f32_e32 v11, 0xbfb8aa3b, v15
	v_exp_f32_e32 v11, v11
	s_nop 0
	v_add_f32_e32 v11, 1.0, v11
	v_rcp_f32_e32 v17, v11
	s_nop 0
	v_pk_mul_f32 v[14:15], v[14:15], v[16:17]
	s_nop 0
	v_pk_mul_f32 v[12:13], v[12:13], v[14:15]
	s_nop 0
	v_cvt_pk_bf16_f32 v11, v12, v13
	global_store_dwordx2 v[18:19], v[10:11], off
	v_mul_f32_e32 v10, 0xbfb8aa3b, v6
	v_mul_f32_e32 v11, 0xbfb8aa3b, v7
	v_exp_f32_e32 v10, v10
	v_exp_f32_e32 v11, v11
	v_add_f32_e32 v10, 1.0, v10
	v_add_f32_e32 v11, 1.0, v11
	v_rcp_f32_e32 v10, v10
	v_rcp_f32_e32 v11, v11
	s_nop 0
	v_pk_mul_f32 v[6:7], v[6:7], v[10:11]
	s_nop 0
	v_pk_mul_f32 v[2:3], v[2:3], v[6:7]
	v_pk_mul_f32 v[6:7], v[8:9], v[20:21] op_sel_hi:[1,0]
	v_cvt_pk_bf16_f32 v2, v2, v3
	v_mul_f32_e32 v3, 0xbfb8aa3b, v6
	v_exp_f32_e32 v3, v3
	s_nop 0
	v_add_f32_e32 v3, 1.0, v3
	v_rcp_f32_e32 v8, v3
	v_mul_f32_e32 v3, 0xbfb8aa3b, v7
	v_exp_f32_e32 v3, v3
	s_nop 0
	v_add_f32_e32 v3, 1.0, v3
	v_rcp_f32_e32 v9, v3
	s_nop 0
	v_pk_mul_f32 v[6:7], v[6:7], v[8:9]
	s_nop 0
	v_pk_mul_f32 v[4:5], v[4:5], v[6:7]
	s_nop 0
	v_cvt_pk_bf16_f32 v3, v4, v5
	global_store_dwordx2 v[18:19], v[2:3], off offset:32
	s_branch .LBB0_1944

; #define MFMA(a, b, c) __builtin_amdgcn_mfma_f32_16x16x32_bf16((a), (b), (c), 0, 0, 0)
; template <int EPI, int MF>
; __device__ __forceinline__ void gemm_part(const u16* __restrict__ A, int lda, const u16* __restrict__ Bt, int K, int ntn, GemmEpi ep, char* smem,
;                                           int mbase, int mrows) {
;     ...
;     GEMM_ISSUE(0);
;     GEMM_ISSUE(1);
;     for (int kt = 0; kt < nk; ++kt) {
;       if (kt + 1 < nk) {
;         if (MF == 8) asm volatile("s_waitcnt vmcnt(6)" ::: "memory");
;         else asm volatile("s_waitcnt vmcnt(3)" ::: "memory");
;       } else asm volatile("s_waitcnt vmcnt(0)" ::: "memory");
;       asm volatile("s_waitcnt lgkmcnt(0)" ::: "memory");
;       __builtin_amdgcn_s_barrier();
;       const u16* a_ = sbase + (kt % 3) * STG;
;       const u16* b_ = a_ + BM * 32;
;       bf16x8 bfr[4], afc[2], afn[2];
;       const u16* ap_ = a_ + (wr * (16 * MF) + fr) * 32 + fq * 8;
; #pragma unroll
;       for (int n = 0; n < 4; ++n) bfr[n] = rd_std(b_ + (wc * 64 + n * 16 + fr) * 32 + fq * 8);
;       afc[0] = rd_std(ap_); afc[1] = rd_std(ap_ + 16 * 32);
;       __builtin_amdgcn_sched_barrier(0);
;       if (kt + 2 < nk) GEMM_ISSUE(kt + 2);
;       __builtin_amdgcn_sched_barrier(0);
; #pragma unroll
;       for (int mh = 0; mh < MF / 2; ++mh) {
;         if (mh + 1 < MF / 2) {
;           afn[0] = rd_std(ap_ + ((mh + 1) * 2) * 16 * 32);
;           afn[1] = rd_std(ap_ + ((mh + 1) * 2 + 1) * 16 * 32);
;         }
;         __builtin_amdgcn_sched_barrier(0);
; #pragma unroll
;         for (int m = 0; m < 2; ++m)
; #pragma unroll
;           for (int n = 0; n < 4; ++n) acc[mh * 2 + m][n] = MFMA(bfr[n], afc[m], acc[mh * 2 + m][n]);
;         __builtin_amdgcn_sched_barrier(0);
;         afc[0] = afn[0]; afc[1] = afn[1];
;       }
.LBB0_1998:
	s_mul_hi_u32 s21, s13, 0xaaaaaaab
	s_lshr_b32 s21, s21, 1
	s_mul_i32 s21, s21, 0x12000
	v_add_u32_e32 v146, s5, v161
	v_subrev_u32_e32 v147, s21, v164
	v_subrev_u32_e32 v148, s21, v160
	v_add_u32_e32 v170, v146, v147
	v_add_u32_e32 v190, v146, v148
	s_mul_hi_u32 s21, s12, 0xaaaaaaab
	s_add_i32 s13, s13, 1
	s_lshr_b32 s21, s21, 1
	s_mul_i32 s21, s21, 0x12000
	s_sub_i32 s21, s5, s21
	s_add_i32 s22, s21, 0xc000
	v_add_u32_e32 v178, s22, v154
	v_lshl_add_u64 v[150:151], v[136:137], 0, v[134:135]
	v_readfirstlane_b32 s101, v178
	v_lshl_add_u64 v[152:153], v[150:151], 0, s[74:75]
	v_lshl_add_u64 v[166:167], v[150:151], 0, s[56:57]
	v_lshl_add_u64 v[168:169], v[150:151], 0, s[58:59]
	v_lshl_add_u64 v[150:151], v[150:151], 0, s[86:87]
	v_lshl_add_u64 v[174:175], v[138:139], 0, v[134:135]
	v_lshl_add_u64 v[176:177], v[174:175], 0, s[74:75]
	v_lshl_add_u64 v[174:175], v[174:175], 0, s[56:57]
	s_waitcnt vmcnt(6)
	s_waitcnt lgkmcnt(0)
	s_barrier
	s_mov_b32 m0, s101
	s_nop 0
	global_load_lds_dwordx4 v[152:153], off
	s_add_u32 m0, m0, 0x1000
	s_nop 0
	global_load_lds_dwordx4 v[166:167], off
	s_add_u32 m0, m0, 0x1000
	s_nop 0
	global_load_lds_dwordx4 v[168:169], off
	s_add_u32 m0, m0, 0x1000
	s_nop 0
	global_load_lds_dwordx4 v[150:151], off
	s_add_u32 m0, m0, 0x1000
	s_nop 0
	global_load_lds_dwordx4 v[176:177], off
	s_add_u32 m0, m0, 0x1000
	s_nop 0
	global_load_lds_dwordx4 v[174:175], off
	ds_read_b128 v[146:149], v170 offset:16384
	ds_read_b128 v[150:153], v170 offset:17408
	ds_read_b128 v[166:169], v170 offset:18432
	ds_read_b128 v[170:173], v170 offset:19456
	ds_read_b128 v[174:177], v190
	ds_read_b128 v[178:181], v190 offset:1024
	ds_read_b128 v[182:185], v190 offset:3072
	ds_read_b128 v[186:189], v190 offset:2048
	s_waitcnt lgkmcnt(2)
	v_mfma_f32_16x16x32_bf16 v[126:129], v[146:149], v[174:177], v[126:129]
	v_mfma_f32_16x16x32_bf16 v[122:125], v[150:153], v[174:177], v[122:125]
	v_mfma_f32_16x16x32_bf16 v[118:121], v[166:169], v[174:177], v[118:121]
	v_mfma_f32_16x16x32_bf16 v[114:117], v[170:173], v[174:177], v[114:117]
	v_mfma_f32_16x16x32_bf16 v[110:113], v[146:149], v[178:181], v[110:113]
	v_mfma_f32_16x16x32_bf16 v[106:109], v[150:153], v[178:181], v[106:109]
	v_mfma_f32_16x16x32_bf16 v[102:105], v[166:169], v[178:181], v[102:105]
	v_mfma_f32_16x16x32_bf16 v[98:101], v[170:173], v[178:181], v[98:101]
	ds_read_b128 v[174:177], v190 offset:5120
	ds_read_b128 v[178:181], v190 offset:4096
	s_waitcnt lgkmcnt(2)
	v_mfma_f32_16x16x32_bf16 v[94:97], v[146:149], v[186:189], v[94:97]
	v_mfma_f32_16x16x32_bf16 v[90:93], v[150:153], v[186:189], v[90:93]
	v_mfma_f32_16x16x32_bf16 v[86:89], v[166:169], v[186:189], v[86:89]
	v_mfma_f32_16x16x32_bf16 v[82:85], v[170:173], v[186:189], v[82:85]
	v_mfma_f32_16x16x32_bf16 v[78:81], v[146:149], v[182:185], v[78:81]
	v_mfma_f32_16x16x32_bf16 v[74:77], v[150:153], v[182:185], v[74:77]
	v_mfma_f32_16x16x32_bf16 v[70:73], v[166:169], v[182:185], v[70:73]
	v_mfma_f32_16x16x32_bf16 v[66:69], v[170:173], v[182:185], v[66:69]
	ds_read_b128 v[182:185], v190 offset:7168
	ds_read_b128 v[186:189], v190 offset:6144
	s_waitcnt lgkmcnt(2)
	v_mfma_f32_16x16x32_bf16 v[62:65], v[146:149], v[178:181], v[62:65]
	v_mfma_f32_16x16x32_bf16 v[58:61], v[150:153], v[178:181], v[58:61]
	v_mfma_f32_16x16x32_bf16 v[54:57], v[166:169], v[178:181], v[54:57]
	v_mfma_f32_16x16x32_bf16 v[50:53], v[170:173], v[178:181], v[50:53]
	v_mfma_f32_16x16x32_bf16 v[46:49], v[146:149], v[174:177], v[46:49]
	v_mfma_f32_16x16x32_bf16 v[42:45], v[150:153], v[174:177], v[42:45]
	v_mfma_f32_16x16x32_bf16 v[38:41], v[166:169], v[174:177], v[38:41]
	v_mfma_f32_16x16x32_bf16 v[34:37], v[170:173], v[174:177], v[34:37]
	s_waitcnt lgkmcnt(0)
	v_mfma_f32_16x16x32_bf16 v[30:33], v[146:149], v[186:189], v[30:33]
	v_mfma_f32_16x16x32_bf16 v[26:29], v[150:153], v[186:189], v[26:29]
	v_mfma_f32_16x16x32_bf16 v[22:25], v[166:169], v[186:189], v[22:25]
	v_mfma_f32_16x16x32_bf16 v[18:21], v[170:173], v[186:189], v[18:21]
	v_mfma_f32_16x16x32_bf16 v[14:17], v[146:149], v[182:185], v[14:17]
	v_mfma_f32_16x16x32_bf16 v[10:13], v[150:153], v[182:185], v[10:13]
	v_mfma_f32_16x16x32_bf16 v[6:9], v[166:169], v[182:185], v[6:9]
	v_mfma_f32_16x16x32_bf16 v[2:5], v[170:173], v[182:185], v[2:5]
	s_addk_i32 s5, 0x6000
	s_add_i32 s11, s11, 1
	s_add_i32 s12, s12, 1
	v_lshl_add_u64 v[136:137], v[136:137], 0, 64
	v_lshl_add_u64 v[136:137], v[136:137], 0, 64
	s_cmp_eq_u32 s5, 0x204000
	v_lshl_add_u64 v[138:139], v[138:139], 0, 64
	v_lshl_add_u64 v[138:139], v[138:139], 0, 64
	s_cbranch_scc0 .LBB0_1998
	s_waitcnt vmcnt(6)
	s_waitcnt lgkmcnt(0)
	s_barrier
; #define MFMA(a, b, c) __builtin_amdgcn_mfma_f32_16x16x32_bf16((a), (b), (c), 0, 0, 0)
; template <int EPI, int MF>
; __device__ __forceinline__ void gemm_part(const u16* __restrict__ A, int lda, const u16* __restrict__ Bt, int K, int ntn, GemmEpi ep, char* smem,
;                                           int mbase, int mrows) {
;     ...
;     for (int kt = 0; kt < nk; ++kt) {
;       if (kt + 1 < nk) {
;         if (MF == 8) asm volatile("s_waitcnt vmcnt(6)" ::: "memory");
;         else asm volatile("s_waitcnt vmcnt(3)" ::: "memory");
;       } else asm volatile("s_waitcnt vmcnt(0)" ::: "memory");
;       asm volatile("s_waitcnt lgkmcnt(0)" ::: "memory");
;       __builtin_amdgcn_s_barrier();
;       const u16* a_ = sbase + (kt % 3) * STG;
;       const u16* b_ = a_ + BM * 32;
;       bf16x8 bfr[4], afc[2], afn[2];
;       const u16* ap_ = a_ + (wr * (16 * MF) + fr) * 32 + fq * 8;
; #pragma unroll
;       for (int n = 0; n < 4; ++n) bfr[n] = rd_std(b_ + (wc * 64 + n * 16 + fr) * 32 + fq * 8);
;       afc[0] = rd_std(ap_); afc[1] = rd_std(ap_ + 16 * 32);
;       __builtin_amdgcn_sched_barrier(0);
;       if (kt + 2 < nk) GEMM_ISSUE(kt + 2);
;       __builtin_amdgcn_sched_barrier(0);
; #pragma unroll
;       for (int mh = 0; mh < MF / 2; ++mh) {
;         if (mh + 1 < MF / 2) {
;           afn[0] = rd_std(ap_ + ((mh + 1) * 2) * 16 * 32);
;           afn[1] = rd_std(ap_ + ((mh + 1) * 2 + 1) * 16 * 32);
;         }
;         __builtin_amdgcn_sched_barrier(0);
; #pragma unroll
;         for (int m = 0; m < 2; ++m)
; #pragma unroll
;           for (int n = 0; n < 4; ++n) acc[mh * 2 + m][n] = MFMA(bfr[n], afc[m], acc[mh * 2 + m][n]);
;         __builtin_amdgcn_sched_barrier(0);
;         afc[0] = afn[0]; afc[1] = afn[1];
;       }
	ds_read_b128 v[136:139], v165
	ds_read_b128 v[146:149], v165 offset:1024
	ds_read_b128 v[150:153], v165 offset:2048
	ds_read_b128 v[166:169], v165 offset:3072
	ds_read_b128 v[170:173], v162 offset:49152
	ds_read_b128 v[174:177], v162 offset:50176
	s_mul_hi_u32 s11, s11, 0xaaaaaaab
	s_lshr_b32 s11, s11, 1
	s_mul_i32 s11, s11, 0x12000
	s_sub_i32 s5, s5, s11
	s_add_i32 s5, s5, 0
	s_addk_i32 s5, 0x6000
	ds_read_b128 v[178:181], v162 offset:52224
	ds_read_b128 v[182:185], v162 offset:51200
	s_waitcnt lgkmcnt(0)
	v_mfma_f32_16x16x32_bf16 v[126:129], v[136:139], v[170:173], v[126:129]
	v_mfma_f32_16x16x32_bf16 v[122:125], v[146:149], v[170:173], v[122:125]
	v_mfma_f32_16x16x32_bf16 v[118:121], v[150:153], v[170:173], v[118:121]
	v_mfma_f32_16x16x32_bf16 v[114:117], v[166:169], v[170:173], v[114:117]
	v_mfma_f32_16x16x32_bf16 v[110:113], v[136:139], v[174:177], v[110:113]
	v_mfma_f32_16x16x32_bf16 v[106:109], v[146:149], v[174:177], v[106:109]
	v_mfma_f32_16x16x32_bf16 v[102:105], v[150:153], v[174:177], v[102:105]
	v_mfma_f32_16x16x32_bf16 v[98:101], v[166:169], v[174:177], v[98:101]
	ds_read_b128 v[170:173], v162 offset:54272
	ds_read_b128 v[174:177], v162 offset:53248
	v_mfma_f32_16x16x32_bf16 v[94:97], v[136:139], v[182:185], v[94:97]
	v_mfma_f32_16x16x32_bf16 v[90:93], v[146:149], v[182:185], v[90:93]
	v_mfma_f32_16x16x32_bf16 v[86:89], v[150:153], v[182:185], v[86:89]
	v_mfma_f32_16x16x32_bf16 v[82:85], v[166:169], v[182:185], v[82:85]
	v_mfma_f32_16x16x32_bf16 v[78:81], v[136:139], v[178:181], v[78:81]
	v_mfma_f32_16x16x32_bf16 v[74:77], v[146:149], v[178:181], v[74:77]
	v_mfma_f32_16x16x32_bf16 v[70:73], v[150:153], v[178:181], v[70:73]
	v_mfma_f32_16x16x32_bf16 v[66:69], v[166:169], v[178:181], v[66:69]
	ds_read_b128 v[178:181], v162 offset:56320
	ds_read_b128 v[182:185], v162 offset:55296
	s_waitcnt lgkmcnt(0)
	v_mfma_f32_16x16x32_bf16 v[62:65], v[136:139], v[174:177], v[62:65]
	v_mfma_f32_16x16x32_bf16 v[58:61], v[146:149], v[174:177], v[58:61]
	v_mfma_f32_16x16x32_bf16 v[54:57], v[150:153], v[174:177], v[54:57]
	v_mfma_f32_16x16x32_bf16 v[50:53], v[166:169], v[174:177], v[50:53]
	v_mfma_f32_16x16x32_bf16 v[46:49], v[136:139], v[170:173], v[46:49]
	v_mfma_f32_16x16x32_bf16 v[42:45], v[146:149], v[170:173], v[42:45]
	v_mfma_f32_16x16x32_bf16 v[38:41], v[150:153], v[170:173], v[38:41]
	v_mfma_f32_16x16x32_bf16 v[34:37], v[166:169], v[170:173], v[34:37]
	v_mfma_f32_16x16x32_bf16 v[30:33], v[136:139], v[182:185], v[30:33]
	v_mfma_f32_16x16x32_bf16 v[26:29], v[146:149], v[182:185], v[26:29]
	v_mfma_f32_16x16x32_bf16 v[22:25], v[150:153], v[182:185], v[22:25]
	v_mfma_f32_16x16x32_bf16 v[18:21], v[166:169], v[182:185], v[18:21]
	v_mfma_f32_16x16x32_bf16 v[14:17], v[136:139], v[178:181], v[14:17]
	v_mfma_f32_16x16x32_bf16 v[10:13], v[146:149], v[178:181], v[10:13]
	v_mfma_f32_16x16x32_bf16 v[6:9], v[150:153], v[178:181], v[6:9]
	v_mfma_f32_16x16x32_bf16 v[2:5], v[166:169], v[178:181], v[2:5]
	v_add_u32_e32 v136, s5, v161
	s_waitcnt vmcnt(0)
	v_add3_u32 v166, v136, v158, v159
	s_waitcnt lgkmcnt(0)
	s_barrier
; #define MFMA(a, b, c) __builtin_amdgcn_mfma_f32_16x16x32_bf16((a), (b), (c), 0, 0, 0)
; template <int EPI, int MF>
; __device__ __forceinline__ void gemm_part(const u16* __restrict__ A, int lda, const u16* __restrict__ Bt, int K, int ntn, GemmEpi ep, char* smem,
;                                           int mbase, int mrows) {
;     ...
;     for (int kt = 0; kt < nk; ++kt) {
;       if (kt + 1 < nk) {
;         if (MF == 8) asm volatile("s_waitcnt vmcnt(6)" ::: "memory");
;         else asm volatile("s_waitcnt vmcnt(3)" ::: "memory");
;       } else asm volatile("s_waitcnt vmcnt(0)" ::: "memory");
;       asm volatile("s_waitcnt lgkmcnt(0)" ::: "memory");
;       __builtin_amdgcn_s_barrier();
;       const u16* a_ = sbase + (kt % 3) * STG;
;       const u16* b_ = a_ + BM * 32;
;       bf16x8 bfr[4], afc[2], afn[2];
;       const u16* ap_ = a_ + (wr * (16 * MF) + fr) * 32 + fq * 8;
; #pragma unroll
;       for (int n = 0; n < 4; ++n) bfr[n] = rd_std(b_ + (wc * 64 + n * 16 + fr) * 32 + fq * 8);
;       afc[0] = rd_std(ap_); afc[1] = rd_std(ap_ + 16 * 32);
;       __builtin_amdgcn_sched_barrier(0);
;       if (kt + 2 < nk) GEMM_ISSUE(kt + 2);
;       __builtin_amdgcn_sched_barrier(0);
; #pragma unroll
;       for (int mh = 0; mh < MF / 2; ++mh) {
;         if (mh + 1 < MF / 2) {
;           afn[0] = rd_std(ap_ + ((mh + 1) * 2) * 16 * 32);
;           afn[1] = rd_std(ap_ + ((mh + 1) * 2 + 1) * 16 * 32);
;         }
;         __builtin_amdgcn_sched_barrier(0);
; #pragma unroll
;         for (int m = 0; m < 2; ++m)
; #pragma unroll
;           for (int n = 0; n < 4; ++n) acc[mh * 2 + m][n] = MFMA(bfr[n], afc[m], acc[mh * 2 + m][n]);
;         __builtin_amdgcn_sched_barrier(0);
;         afc[0] = afn[0]; afc[1] = afn[1];
;       }
;     ...
;       } else if (EPI == EPI_RESID) {
;         const float* rp = (row < MP) ? ep.res0 + (size_t)row * DM : ep.res1 + (size_t)(row - MP) * DM;
;         float ssq = 0.f;
; #pragma unroll
;         for (int n = 0; n < 4; ++n) {
;           const int col = cb + n * 16;
;           const float4 r = *(const float4*)(rp + col);
;           float4 v;
;           v.x = r.x + ep.scale * acc[m][n][0]; v.y = r.y + ep.scale * acc[m][n][1];
;           v.z = r.z + ep.scale * acc[m][n][2]; v.w = r.w + ep.scale * acc[m][n][3];
;           *(float4*)(ep.outf + (size_t)row * DM + col) = v;
;           if (ep.xcopy) {
;             bf16x4 o;
	ds_read_b128 v[136:139], v166 offset:16384
	ds_read_b128 v[146:149], v166 offset:17408
	ds_read_b128 v[150:153], v166 offset:18432
	ds_read_b128 v[166:169], v166 offset:19456
	ds_read_b128 v[170:173], v162
	ds_read_b128 v[174:177], v162 offset:1024
	ds_read_b128 v[178:181], v162 offset:3072
	ds_read_b128 v[182:185], v162 offset:2048
	s_waitcnt lgkmcnt(0)
	v_mfma_f32_16x16x32_bf16 v[126:129], v[136:139], v[170:173], v[126:129]
	v_mfma_f32_16x16x32_bf16 v[122:125], v[146:149], v[170:173], v[122:125]
	v_mfma_f32_16x16x32_bf16 v[118:121], v[150:153], v[170:173], v[118:121]
	v_mfma_f32_16x16x32_bf16 v[114:117], v[166:169], v[170:173], v[114:117]
	v_mfma_f32_16x16x32_bf16 v[110:113], v[136:139], v[174:177], v[110:113]
	v_mfma_f32_16x16x32_bf16 v[106:109], v[146:149], v[174:177], v[106:109]
	v_mfma_f32_16x16x32_bf16 v[102:105], v[150:153], v[174:177], v[102:105]
	v_mfma_f32_16x16x32_bf16 v[98:101], v[166:169], v[174:177], v[98:101]
	ds_read_b128 v[170:173], v162 offset:5120
	ds_read_b128 v[174:177], v162 offset:4096
	v_mfma_f32_16x16x32_bf16 v[94:97], v[136:139], v[182:185], v[94:97]
	v_mfma_f32_16x16x32_bf16 v[90:93], v[146:149], v[182:185], v[90:93]
	v_mfma_f32_16x16x32_bf16 v[86:89], v[150:153], v[182:185], v[86:89]
	v_mfma_f32_16x16x32_bf16 v[82:85], v[166:169], v[182:185], v[82:85]
	v_mfma_f32_16x16x32_bf16 v[78:81], v[136:139], v[178:181], v[78:81]
	v_mfma_f32_16x16x32_bf16 v[74:77], v[146:149], v[178:181], v[74:77]
	v_mfma_f32_16x16x32_bf16 v[70:73], v[150:153], v[178:181], v[70:73]
	v_mfma_f32_16x16x32_bf16 v[66:69], v[166:169], v[178:181], v[66:69]
	ds_read_b128 v[178:181], v162 offset:7168
	ds_read_b128 v[182:185], v162 offset:6144
	s_waitcnt lgkmcnt(0)
	v_mfma_f32_16x16x32_bf16 v[62:65], v[136:139], v[174:177], v[62:65]
	v_mfma_f32_16x16x32_bf16 v[58:61], v[146:149], v[174:177], v[58:61]
	v_mfma_f32_16x16x32_bf16 v[54:57], v[150:153], v[174:177], v[54:57]
	v_mfma_f32_16x16x32_bf16 v[50:53], v[166:169], v[174:177], v[50:53]
	v_mfma_f32_16x16x32_bf16 v[46:49], v[136:139], v[170:173], v[46:49]
	v_mfma_f32_16x16x32_bf16 v[42:45], v[146:149], v[170:173], v[42:45]
	v_mfma_f32_16x16x32_bf16 v[38:41], v[150:153], v[170:173], v[38:41]
	v_mfma_f32_16x16x32_bf16 v[34:37], v[166:169], v[170:173], v[34:37]
	v_mfma_f32_16x16x32_bf16 v[30:33], v[136:139], v[182:185], v[30:33]
	v_mfma_f32_16x16x32_bf16 v[26:29], v[146:149], v[182:185], v[26:29]
	v_mfma_f32_16x16x32_bf16 v[22:25], v[150:153], v[182:185], v[22:25]
	v_mfma_f32_16x16x32_bf16 v[18:21], v[166:169], v[182:185], v[18:21]
	v_mfma_f32_16x16x32_bf16 v[14:17], v[136:139], v[178:181], v[14:17]
	v_mfma_f32_16x16x32_bf16 v[10:13], v[146:149], v[178:181], v[10:13]
	v_mfma_f32_16x16x32_bf16 v[6:9], v[150:153], v[178:181], v[6:9]
	v_mfma_f32_16x16x32_bf16 v[2:5], v[166:169], v[178:181], v[2:5]
	v_add_u32_e32 v138, s4, v156
	s_waitcnt vmcnt(0)
	s_barrier
	s_mov_b32 s4, 0xffff
	v_cmp_lt_i32_e32 vcc, s4, v138
	s_and_saveexec_b64 s[4:5], vcc
	s_xor_b64 s[4:5], exec, s[4:5]
	v_add_u32_e32 v136, 0xffff0000, v138
	v_mov_b32_e32 v137, v0
	v_lshlrev_b64 v[136:137], 12, v[136:137]
	v_lshl_add_u64 v[136:137], s[72:73], 0, v[136:137]
	v_mov_b32_e32 v139, v0
	s_andn2_saveexec_b64 s[4:5], s[4:5]
	v_ashrrev_i32_e32 v139, 31, v138
	v_lshlrev_b64 v[136:137], 12, v[138:139]
	v_lshl_add_u64 v[136:137], s[26:27], 0, v[136:137]
	s_or_b64 exec, exec, s[4:5]
	v_lshlrev_b64 v[146:147], 12, v[138:139]
	v_or_b32_e32 v170, s10, v157
	v_lshl_add_u64 v[150:151], s[26:27], 0, v[146:147]
	v_lshlrev_b64 v[146:147], 11, v[138:139]
	v_lshl_add_u64 v[148:149], s[14:15], 0, v[146:147]
	v_lshlrev_b32_e32 v146, 2, v170
	v_mov_b32_e32 v147, v0
	v_lshl_add_u64 v[152:153], v[136:137], 0, v[146:147]
	global_load_dwordx4 v[166:169], v[152:153], off
	global_load_dwordx4 v[172:175], v[152:153], off offset:64
	global_load_dwordx4 v[176:179], v[152:153], off offset:128
	global_load_dwordx4 v[180:183], v[152:153], off offset:192
	v_cndmask_b32_e64 v136, 0, 1, s[2:3]
	v_lshl_add_u64 v[150:151], v[150:151], 0, v[146:147]
	v_cmp_ne_u32_e64 s[10:11], 1, v136
	s_andn2_b64 vcc, exec, s[2:3]
	v_lshlrev_b32_e32 v136, 1, v170
	s_waitcnt vmcnt(0)
	v_pk_fma_f32 v[126:127], v[126:127], 0.5, v[166:167] op_sel_hi:[1,0,1]
	v_pk_fma_f32 v[128:129], v[128:129], 0.5, v[168:169] op_sel_hi:[1,0,1]
	global_store_dwordx4 v[150:151], v[126:129], off
	s_cbranch_vccnz .LBB0_2005
	v_mov_b32_e32 v137, v0
	v_cvt_pk_bf16_f32 v166, v126, v127
	v_cvt_pk_bf16_f32 v167, v128, v129
	v_lshl_add_u64 v[168:169], v[148:149], 0, v[136:137]
	v_lshlrev_b32_e32 v184, 1, v168
	v_bfi_b32 v184, s100, v184, v168
	v_lshrrev_b32_e32 v185, 5, v168
	v_bfi_b32 v184, 64, v185, v184
	v_mov_b32_e32 v185, v169
	global_store_dwordx2 v[184:185], v[166:167], off

; __global__ void __launch_bounds__(256, 2) fwd_megakernel(Params p) {
;   extern __shared__ __attribute__((aligned(16))) char smem[];
	.amdhsa_kernel _Z14fwd_megakernel6Params
		.amdhsa_group_segment_fixed_size 0
		.amdhsa_private_segment_fixed_size 0
		.amdhsa_kernarg_size 664
		.amdhsa_user_sgpr_count 2
		.amdhsa_user_sgpr_dispatch_ptr 0
		.amdhsa_user_sgpr_queue_ptr 0
		.amdhsa_user_sgpr_kernarg_segment_ptr 1
		.amdhsa_user_sgpr_dispatch_id 0
		.amdhsa_user_sgpr_kernarg_preload_length 0
		.amdhsa_user_sgpr_kernarg_preload_offset 0
		.amdhsa_user_sgpr_private_segment_size 0
		.amdhsa_uses_dynamic_stack 0
		.amdhsa_enable_private_segment 0
		.amdhsa_system_sgpr_workgroup_id_x 1
		.amdhsa_system_sgpr_workgroup_id_y 0
		.amdhsa_system_sgpr_workgroup_id_z 0
		.amdhsa_system_sgpr_workgroup_info 0
		.amdhsa_system_vgpr_workitem_id 2
		.amdhsa_next_free_vgpr 256
		.amdhsa_next_free_sgpr 102
		.amdhsa_accum_offset 256
		.amdhsa_reserve_vcc 1
		.amdhsa_float_round_mode_32 0
		.amdhsa_float_round_mode_16_64 0
		.amdhsa_float_denorm_mode_32 3
		.amdhsa_float_denorm_mode_16_64 3
		.amdhsa_dx10_clamp 1
		.amdhsa_ieee_mode 1
		.amdhsa_fp16_overflow 0
		.amdhsa_tg_split 0
		.amdhsa_exception_fp_ieee_invalid_op 0
		.amdhsa_exception_fp_denorm_src 0
		.amdhsa_exception_fp_ieee_div_zero 0
		.amdhsa_exception_fp_ieee_overflow 0
		.amdhsa_exception_fp_ieee_underflow 0
		.amdhsa_exception_fp_ieee_inexact 0
		.amdhsa_exception_int_div_zero 0
	.end_amdhsa_kernel

amdhsa.kernels:
  - .agpr_count:     0
    .args:
      - .offset:         0
        .size:           408
        .value_kind:     by_value
      - .offset:         408
        .size:           4
        .value_kind:     hidden_block_count_x
      - .offset:         412
        .size:           4
        .value_kind:     hidden_block_count_y
      - .offset:         416
        .size:           4
        .value_kind:     hidden_block_count_z
      - .offset:         420
        .size:           2
        .value_kind:     hidden_group_size_x
      - .offset:         422
        .size:           2
        .value_kind:     hidden_group_size_y
      - .offset:         424
        .size:           2
        .value_kind:     hidden_group_size_z
      - .offset:         426
        .size:           2
        .value_kind:     hidden_remainder_x
      - .offset:         428
        .size:           2
        .value_kind:     hidden_remainder_y
      - .offset:         430
        .size:           2
        .value_kind:     hidden_remainder_z
      - .offset:         448
        .size:           8
        .value_kind:     hidden_global_offset_x
      - .offset:         456
        .size:           8
        .value_kind:     hidden_global_offset_y
      - .offset:         464
        .size:           8
        .value_kind:     hidden_global_offset_z
      - .offset:         472
        .size:           2
        .value_kind:     hidden_grid_dims
      - .offset:         496
        .size:           8
        .value_kind:     hidden_multigrid_sync_arg
      - .offset:         528
        .size:           4
        .value_kind:     hidden_dynamic_lds_size
    .group_segment_fixed_size: 0
    .kernarg_segment_align: 8
    .kernarg_segment_size: 664
    .language:       OpenCL C
    .language_version:
      - 2
      - 0
    .max_flat_workgroup_size: 256
    .name:           _Z14fwd_megakernel6Params
    .private_segment_fixed_size: 0
    .sgpr_count:     108
    .sgpr_spill_count: 139
    .symbol:         _Z14fwd_megakernel6Params.kd
    .uniform_work_group_size: 1
    .uses_dynamic_stack: false
    .vgpr_count:     256
    .vgpr_spill_count: 0
    .wavefront_size: 64
